# H1 and rowB row phases rewritten for G==256: norm/adaLN parameter vectors staged once per workgroup in LDS (ds_read instead of per-batch global loads), six rows per wave unrolled with the next row's l
# speedup vs baseline: 1.0067x; 1.0009x over previous
.LBB0_100:
	s_cmp_lt_i32 s72, 3
	s_cselect_b64 s[0:1], -1, 0
	s_cmp_gt_i32 s73, 2
	s_cselect_b64 s[4:5], -1, 0
	s_and_b64 s[0:1], s[0:1], s[4:5]
	s_andn2_b64 vcc, exec, s[0:1]
	s_cbranch_vccnz .LBB0_104
	s_lshl_b32 s3, s2, 3
	s_add_i32 s4, s96, s3
	s_cmpk_gt_i32 s4, 0x2fff
	s_cbranch_scc1 .LBB0_104
	s_cmp_lg_u32 s33, 0x100
	s_cbranch_scc1 .Lh1_old
	v_readlane_b32 s12, v255, 6
	v_readlane_b32 s13, v255, 7
	v_lshl_add_u32 v162, s96, 6, v174
	v_lshlrev_b32_e32 v162, 4, v162
	v_add_u32_e32 v163, 0x2000, v162
	v_add_u32_e32 v164, 0x10000, v162
	v_add_u32_e32 v165, 0x12000, v162
	s_lshr_b32 s3, s2, 7
	s_add_i32 s5, s3, 1
	s_mul_i32 s5, s5, 0x18000
	s_add_u32 s18, s28, s5
	s_addc_u32 s19, s29, 0
	s_add_i32 s5, s3, 3
	s_mul_i32 s5, s5, 0x18000
	s_add_u32 s22, s28, s5
	s_addc_u32 s23, s29, 0
	s_nop 4
	s_add_u32 s6, s28, 0x4000
	s_addc_u32 s7, s29, 0
	s_add_u32 s8, s18, 0x4000
	s_addc_u32 s9, s19, 0
	s_add_u32 s36, s22, 0x4000
	s_addc_u32 s37, s23, 0
	global_load_dwordx4 v[2:5], v162, s[12:13]
	global_load_dwordx4 v[6:9], v163, s[12:13]
	global_load_dwordx4 v[10:13], v162, s[28:29]
	global_load_dwordx4 v[14:17], v163, s[28:29]
	global_load_dwordx4 v[18:21], v162, s[6:7]
	global_load_dwordx4 v[22:25], v163, s[6:7]
	global_load_dwordx4 v[26:29], v162, s[18:19]
	global_load_dwordx4 v[30:33], v163, s[18:19]
	global_load_dwordx4 v[34:37], v162, s[8:9]
	global_load_dwordx4 v[38:41], v163, s[8:9]
	global_load_dwordx4 v[42:45], v162, s[22:23]
	global_load_dwordx4 v[46:49], v163, s[22:23]
	global_load_dwordx4 v[50:53], v162, s[36:37]
	global_load_dwordx4 v[54:57], v163, s[36:37]
	s_waitcnt vmcnt(0)
	ds_write_b128 v162, v[2:5] offset:0
	ds_write_b128 v162, v[6:9] offset:8192
	ds_write_b128 v162, v[10:13] offset:16384
	ds_write_b128 v162, v[14:17] offset:24576
	ds_write_b128 v162, v[18:21] offset:32768
	ds_write_b128 v162, v[22:25] offset:40960
	ds_write_b128 v162, v[26:29] offset:49152
	ds_write_b128 v162, v[30:33] offset:57344
	ds_write_b128 v164, v[34:37] offset:0
	ds_write_b128 v164, v[38:41] offset:8192
	ds_write_b128 v164, v[42:45] offset:16384
	ds_write_b128 v164, v[46:49] offset:24576
	ds_write_b128 v164, v[50:53] offset:32768
	ds_write_b128 v164, v[54:57] offset:40960
	v_lshlrev_b32_e32 v238, 4, v174
	v_add_u32_e32 v239, 0x10000, v238
	v_add_u32_e32 v241, 0x1000, v238
	v_add_u32_e32 v242, 0x2000, v238
	v_add_u32_e32 v243, 0x3000, v238
	v_lshlrev_b32_e32 v244, 3, v174
	v_add_u32_e32 v245, 0x1000, v244
	v_xor_b32_e32 v246, 1, v174
	v_lshlrev_b32_e32 v246, 2, v246
	v_xor_b32_e32 v247, 2, v174
	v_lshlrev_b32_e32 v247, 2, v247
	v_xor_b32_e32 v248, 4, v174
	v_lshlrev_b32_e32 v248, 2, v248
	v_xor_b32_e32 v249, 8, v174
	v_lshlrev_b32_e32 v249, 2, v249
	v_xor_b32_e32 v250, 16, v174
	v_lshlrev_b32_e32 v250, 2, v250
	v_xor_b32_e32 v251, 32, v174
	v_lshlrev_b32_e32 v251, 2, v251
	s_mov_b32 s20, 0x800000
	s_lshl_b32 s5, s4, 14
	s_add_u32 s14, s52, s5
	s_addc_u32 s15, s53, 0
	s_add_u32 s42, s54, s5
	s_addc_u32 s43, s55, 0
	s_lshl_b32 s5, s4, 13
	s_add_u32 s16, s70, s5
	s_addc_u32 s17, s71, 0
	s_add_u32 s16, s16, 0x3f000000
	s_addc_u32 s17, s17, 0
	s_waitcnt lgkmcnt(0)
	s_barrier
	global_load_dwordx4 v[2:5], v238, s[14:15] offset:0 nt
	global_load_dwordx4 v[6:9], v238, s[14:15] offset:1024 nt
	global_load_dwordx4 v[10:13], v238, s[14:15] offset:2048 nt
	global_load_dwordx4 v[14:17], v238, s[14:15] offset:3072 nt
	global_load_dwordx4 v[18:21], v241, s[14:15] offset:0 nt
	global_load_dwordx4 v[22:25], v241, s[14:15] offset:1024 nt
	global_load_dwordx4 v[26:29], v241, s[14:15] offset:2048 nt
	global_load_dwordx4 v[30:33], v241, s[14:15] offset:3072 nt
	global_load_dwordx4 v[34:37], v242, s[14:15] offset:0 nt
	global_load_dwordx4 v[38:41], v242, s[14:15] offset:1024 nt
	global_load_dwordx4 v[42:45], v242, s[14:15] offset:2048 nt
	global_load_dwordx4 v[46:49], v242, s[14:15] offset:3072 nt
	global_load_dwordx4 v[50:53], v243, s[14:15] offset:0 nt
	global_load_dwordx4 v[54:57], v243, s[14:15] offset:1024 nt
	global_load_dwordx4 v[58:61], v243, s[14:15] offset:2048 nt
	global_load_dwordx4 v[62:65], v243, s[14:15] offset:3072 nt
	s_waitcnt vmcnt(0)
	s_add_u32 s14, s14, 0x2000000
	s_addc_u32 s15, s15, 0
	global_load_dwordx4 v[66:69], v238, s[14:15] offset:0 nt
	global_load_dwordx4 v[70:73], v238, s[14:15] offset:1024 nt
	global_load_dwordx4 v[74:77], v238, s[14:15] offset:2048 nt
	global_load_dwordx4 v[78:81], v238, s[14:15] offset:3072 nt
	global_load_dwordx4 v[82:85], v241, s[14:15] offset:0 nt
	global_load_dwordx4 v[86:89], v241, s[14:15] offset:1024 nt
	global_load_dwordx4 v[90:93], v241, s[14:15] offset:2048 nt
	global_load_dwordx4 v[94:97], v241, s[14:15] offset:3072 nt
	global_load_dwordx4 v[98:101], v242, s[14:15] offset:0 nt
	global_load_dwordx4 v[102:105], v242, s[14:15] offset:1024 nt
	global_load_dwordx4 v[106:109], v242, s[14:15] offset:2048 nt
	global_load_dwordx4 v[110:113], v242, s[14:15] offset:3072 nt
	global_load_dwordx4 v[114:117], v243, s[14:15] offset:0 nt
	global_load_dwordx4 v[118:121], v243, s[14:15] offset:1024 nt
	global_load_dwordx4 v[122:125], v243, s[14:15] offset:2048 nt
	global_load_dwordx4 v[126:129], v243, s[14:15] offset:3072 nt
	ds_read_b128 v[130:133], v238 offset:0
	ds_read_b128 v[134:137], v238 offset:16384
	ds_read_b128 v[138:141], v238 offset:32768
	ds_read_b128 v[142:145], v238 offset:1024
	ds_read_b128 v[146:149], v238 offset:17408
	ds_read_b128 v[150:153], v238 offset:33792
	v_pk_mul_f32 v[156:157], v[2:3], v[2:3]
	v_pk_mul_f32 v[158:159], v[4:5], v[4:5]
	v_pk_fma_f32 v[156:157], v[6:7], v[6:7], v[156:157]
	v_pk_fma_f32 v[158:159], v[8:9], v[8:9], v[158:159]
	v_pk_fma_f32 v[156:157], v[10:11], v[10:11], v[156:157]
	v_pk_fma_f32 v[158:159], v[12:13], v[12:13], v[158:159]
	v_pk_fma_f32 v[156:157], v[14:15], v[14:15], v[156:157]
	v_pk_fma_f32 v[158:159], v[16:17], v[16:17], v[158:159]
	v_pk_fma_f32 v[156:157], v[18:19], v[18:19], v[156:157]
	v_pk_fma_f32 v[158:159], v[20:21], v[20:21], v[158:159]
	v_pk_fma_f32 v[156:157], v[22:23], v[22:23], v[156:157]
	v_pk_fma_f32 v[158:159], v[24:25], v[24:25], v[158:159]
	v_pk_fma_f32 v[156:157], v[26:27], v[26:27], v[156:157]
	v_pk_fma_f32 v[158:159], v[28:29], v[28:29], v[158:159]
	v_pk_fma_f32 v[156:157], v[30:31], v[30:31], v[156:157]
	v_pk_fma_f32 v[158:159], v[32:33], v[32:33], v[158:159]
	v_pk_fma_f32 v[156:157], v[34:35], v[34:35], v[156:157]
	v_pk_fma_f32 v[158:159], v[36:37], v[36:37], v[158:159]
	v_pk_fma_f32 v[156:157], v[38:39], v[38:39], v[156:157]
	v_pk_fma_f32 v[158:159], v[40:41], v[40:41], v[158:159]
	v_pk_fma_f32 v[156:157], v[42:43], v[42:43], v[156:157]
	v_pk_fma_f32 v[158:159], v[44:45], v[44:45], v[158:159]
	v_pk_fma_f32 v[156:157], v[46:47], v[46:47], v[156:157]
	v_pk_fma_f32 v[158:159], v[48:49], v[48:49], v[158:159]
	v_pk_fma_f32 v[156:157], v[50:51], v[50:51], v[156:157]
	v_pk_fma_f32 v[158:159], v[52:53], v[52:53], v[158:159]
	v_pk_fma_f32 v[156:157], v[54:55], v[54:55], v[156:157]
	v_pk_fma_f32 v[158:159], v[56:57], v[56:57], v[158:159]
	v_pk_fma_f32 v[156:157], v[58:59], v[58:59], v[156:157]
	v_pk_fma_f32 v[158:159], v[60:61], v[60:61], v[158:159]
	v_pk_fma_f32 v[156:157], v[62:63], v[62:63], v[156:157]
	v_pk_fma_f32 v[158:159], v[64:65], v[64:65], v[158:159]
	v_pk_add_f32 v[156:157], v[156:157], v[158:159]
	s_nop 0
	v_add_f32_e32 v252, v156, v157
	s_waitcnt lgkmcnt(0)
	ds_bpermute_b32 v254, v246, v252
	s_waitcnt lgkmcnt(0)
	v_add_f32_e32 v252, v252, v254
	ds_bpermute_b32 v254, v247, v252
	s_waitcnt lgkmcnt(0)
	v_add_f32_e32 v252, v252, v254
	ds_bpermute_b32 v254, v248, v252
	s_waitcnt lgkmcnt(0)
	v_add_f32_e32 v252, v252, v254
	ds_bpermute_b32 v254, v249, v252
	s_waitcnt lgkmcnt(0)
	v_add_f32_e32 v252, v252, v254
	ds_bpermute_b32 v254, v250, v252
	s_waitcnt lgkmcnt(0)
	v_add_f32_e32 v252, v252, v254
	ds_bpermute_b32 v254, v251, v252
	s_waitcnt lgkmcnt(0)
	v_add_f32_e32 v252, v252, v254
	v_mov_b32_e32 v254, 0x358637bd
	v_fmac_f32_e32 v254, 0x39800000, v252
	v_mul_f32_e32 v252, 0x4b800000, v254
	v_cmp_gt_f32_e32 vcc, s20, v254
	s_nop 1
	v_cndmask_b32_e32 v254, v254, v252, vcc
	v_rsq_f32_e32 v254, v254
	s_nop 0
	v_mul_f32_e32 v252, 0x45800000, v254
	v_cndmask_b32_e32 v252, v254, v252, vcc
	ds_read_b128 v[214:217], v238 offset:2048
	ds_read_b128 v[218:221], v238 offset:18432
	ds_read_b128 v[222:225], v238 offset:34816
	ds_read_b128 v[226:229], v238 offset:3072
	ds_read_b128 v[230:233], v238 offset:19456
	ds_read_b128 v[234:237], v238 offset:35840
	s_waitcnt lgkmcnt(6)
	v_pk_mul_f32 v[2:3], v[2:3], v[252:253] op_sel_hi:[1,0]
	v_pk_mul_f32 v[4:5], v[4:5], v[252:253] op_sel_hi:[1,0]
	v_pk_mul_f32 v[2:3], v[130:131], v[2:3]
	v_pk_mul_f32 v[4:5], v[132:133], v[4:5]
	v_pk_add_f32 v[138:139], v[138:139], 1.0 op_sel_hi:[1,0]
	v_pk_add_f32 v[140:141], v[140:141], 1.0 op_sel_hi:[1,0]
	v_pk_fma_f32 v[2:3], v[138:139], v[2:3], v[134:135]
	v_pk_fma_f32 v[4:5], v[140:141], v[4:5], v[136:137]
	s_nop 0
	v_cvt_pk_bf16_f32 v2, v2, v3
	v_cvt_pk_bf16_f32 v3, v4, v5
	global_store_dwordx2 v244, v[2:3], s[16:17] offset:0
	v_pk_mul_f32 v[6:7], v[6:7], v[252:253] op_sel_hi:[1,0]
	v_pk_mul_f32 v[8:9], v[8:9], v[252:253] op_sel_hi:[1,0]
	v_pk_mul_f32 v[6:7], v[142:143], v[6:7]
	v_pk_mul_f32 v[8:9], v[144:145], v[8:9]
	v_pk_add_f32 v[150:151], v[150:151], 1.0 op_sel_hi:[1,0]
	v_pk_add_f32 v[152:153], v[152:153], 1.0 op_sel_hi:[1,0]
	v_pk_fma_f32 v[6:7], v[150:151], v[6:7], v[146:147]
	v_pk_fma_f32 v[8:9], v[152:153], v[8:9], v[148:149]
	s_nop 0
	v_cvt_pk_bf16_f32 v6, v6, v7
	v_cvt_pk_bf16_f32 v7, v8, v9
	global_store_dwordx2 v244, v[6:7], s[16:17] offset:512
	ds_read_b128 v[130:133], v238 offset:4096
	ds_read_b128 v[134:137], v238 offset:20480
	ds_read_b128 v[138:141], v238 offset:36864
	ds_read_b128 v[142:145], v238 offset:5120
	ds_read_b128 v[146:149], v238 offset:21504
	ds_read_b128 v[150:153], v238 offset:37888
	s_waitcnt lgkmcnt(6)
	v_pk_mul_f32 v[10:11], v[10:11], v[252:253] op_sel_hi:[1,0]
	v_pk_mul_f32 v[12:13], v[12:13], v[252:253] op_sel_hi:[1,0]
	v_pk_mul_f32 v[10:11], v[214:215], v[10:11]
	v_pk_mul_f32 v[12:13], v[216:217], v[12:13]
	v_pk_add_f32 v[222:223], v[222:223], 1.0 op_sel_hi:[1,0]
	v_pk_add_f32 v[224:225], v[224:225], 1.0 op_sel_hi:[1,0]
	v_pk_fma_f32 v[10:11], v[222:223], v[10:11], v[218:219]
	v_pk_fma_f32 v[12:13], v[224:225], v[12:13], v[220:221]
	s_nop 0
	v_cvt_pk_bf16_f32 v10, v10, v11
	v_cvt_pk_bf16_f32 v11, v12, v13
	global_store_dwordx2 v244, v[10:11], s[16:17] offset:1024
	v_pk_mul_f32 v[14:15], v[14:15], v[252:253] op_sel_hi:[1,0]
	v_pk_mul_f32 v[16:17], v[16:17], v[252:253] op_sel_hi:[1,0]
	v_pk_mul_f32 v[14:15], v[226:227], v[14:15]
	v_pk_mul_f32 v[16:17], v[228:229], v[16:17]
	v_pk_add_f32 v[234:235], v[234:235], 1.0 op_sel_hi:[1,0]
	v_pk_add_f32 v[236:237], v[236:237], 1.0 op_sel_hi:[1,0]
	v_pk_fma_f32 v[14:15], v[234:235], v[14:15], v[230:231]
	v_pk_fma_f32 v[16:17], v[236:237], v[16:17], v[232:233]
	s_nop 0
	v_cvt_pk_bf16_f32 v14, v14, v15
	v_cvt_pk_bf16_f32 v15, v16, v17
	global_store_dwordx2 v244, v[14:15], s[16:17] offset:1536
	ds_read_b128 v[214:217], v238 offset:6144
	ds_read_b128 v[218:221], v238 offset:22528
	ds_read_b128 v[222:225], v238 offset:38912
	ds_read_b128 v[226:229], v238 offset:7168
	ds_read_b128 v[230:233], v238 offset:23552
	ds_read_b128 v[234:237], v238 offset:39936
	s_waitcnt lgkmcnt(6)
	v_pk_mul_f32 v[18:19], v[18:19], v[252:253] op_sel_hi:[1,0]
	v_pk_mul_f32 v[20:21], v[20:21], v[252:253] op_sel_hi:[1,0]
	v_pk_mul_f32 v[18:19], v[130:131], v[18:19]
	v_pk_mul_f32 v[20:21], v[132:133], v[20:21]
	v_pk_add_f32 v[138:139], v[138:139], 1.0 op_sel_hi:[1,0]
	v_pk_add_f32 v[140:141], v[140:141], 1.0 op_sel_hi:[1,0]
	v_pk_fma_f32 v[18:19], v[138:139], v[18:19], v[134:135]
	v_pk_fma_f32 v[20:21], v[140:141], v[20:21], v[136:137]
	s_nop 0
	v_cvt_pk_bf16_f32 v18, v18, v19
	v_cvt_pk_bf16_f32 v19, v20, v21
	global_store_dwordx2 v244, v[18:19], s[16:17] offset:2048
	v_pk_mul_f32 v[22:23], v[22:23], v[252:253] op_sel_hi:[1,0]
	v_pk_mul_f32 v[24:25], v[24:25], v[252:253] op_sel_hi:[1,0]
	v_pk_mul_f32 v[22:23], v[142:143], v[22:23]
	v_pk_mul_f32 v[24:25], v[144:145], v[24:25]
	v_pk_add_f32 v[150:151], v[150:151], 1.0 op_sel_hi:[1,0]
	v_pk_add_f32 v[152:153], v[152:153], 1.0 op_sel_hi:[1,0]
	v_pk_fma_f32 v[22:23], v[150:151], v[22:23], v[146:147]
	v_pk_fma_f32 v[24:25], v[152:153], v[24:25], v[148:149]
	s_nop 0
	v_cvt_pk_bf16_f32 v22, v22, v23
	v_cvt_pk_bf16_f32 v23, v24, v25
	global_store_dwordx2 v244, v[22:23], s[16:17] offset:2560
	ds_read_b128 v[130:133], v238 offset:8192
	ds_read_b128 v[134:137], v238 offset:24576
	ds_read_b128 v[138:141], v238 offset:40960
	ds_read_b128 v[142:145], v238 offset:9216
	ds_read_b128 v[146:149], v238 offset:25600
	ds_read_b128 v[150:153], v238 offset:41984
	s_waitcnt lgkmcnt(6)
	v_pk_mul_f32 v[26:27], v[26:27], v[252:253] op_sel_hi:[1,0]
	v_pk_mul_f32 v[28:29], v[28:29], v[252:253] op_sel_hi:[1,0]
	v_pk_mul_f32 v[26:27], v[214:215], v[26:27]
	v_pk_mul_f32 v[28:29], v[216:217], v[28:29]
	v_pk_add_f32 v[222:223], v[222:223], 1.0 op_sel_hi:[1,0]
	v_pk_add_f32 v[224:225], v[224:225], 1.0 op_sel_hi:[1,0]
	v_pk_fma_f32 v[26:27], v[222:223], v[26:27], v[218:219]
	v_pk_fma_f32 v[28:29], v[224:225], v[28:29], v[220:221]
	s_nop 0
	v_cvt_pk_bf16_f32 v26, v26, v27
	v_cvt_pk_bf16_f32 v27, v28, v29
	global_store_dwordx2 v244, v[26:27], s[16:17] offset:3072
	v_pk_mul_f32 v[30:31], v[30:31], v[252:253] op_sel_hi:[1,0]
	v_pk_mul_f32 v[32:33], v[32:33], v[252:253] op_sel_hi:[1,0]
	v_pk_mul_f32 v[30:31], v[226:227], v[30:31]
	v_pk_mul_f32 v[32:33], v[228:229], v[32:33]
	v_pk_add_f32 v[234:235], v[234:235], 1.0 op_sel_hi:[1,0]
	v_pk_add_f32 v[236:237], v[236:237], 1.0 op_sel_hi:[1,0]
	v_pk_fma_f32 v[30:31], v[234:235], v[30:31], v[230:231]
	v_pk_fma_f32 v[32:33], v[236:237], v[32:33], v[232:233]
	s_nop 0
	v_cvt_pk_bf16_f32 v30, v30, v31
	v_cvt_pk_bf16_f32 v31, v32, v33
	global_store_dwordx2 v244, v[30:31], s[16:17] offset:3584
	ds_read_b128 v[214:217], v238 offset:10240
	ds_read_b128 v[218:221], v238 offset:26624
	ds_read_b128 v[222:225], v238 offset:43008
	ds_read_b128 v[226:229], v238 offset:11264
	ds_read_b128 v[230:233], v238 offset:27648
	ds_read_b128 v[234:237], v238 offset:44032
	s_waitcnt lgkmcnt(6)
	v_pk_mul_f32 v[34:35], v[34:35], v[252:253] op_sel_hi:[1,0]
	v_pk_mul_f32 v[36:37], v[36:37], v[252:253] op_sel_hi:[1,0]
	v_pk_mul_f32 v[34:35], v[130:131], v[34:35]
	v_pk_mul_f32 v[36:37], v[132:133], v[36:37]
	v_pk_add_f32 v[138:139], v[138:139], 1.0 op_sel_hi:[1,0]
	v_pk_add_f32 v[140:141], v[140:141], 1.0 op_sel_hi:[1,0]
	v_pk_fma_f32 v[34:35], v[138:139], v[34:35], v[134:135]
	v_pk_fma_f32 v[36:37], v[140:141], v[36:37], v[136:137]
	s_nop 0
	v_cvt_pk_bf16_f32 v34, v34, v35
	v_cvt_pk_bf16_f32 v35, v36, v37
	global_store_dwordx2 v245, v[34:35], s[16:17] offset:0
	v_pk_mul_f32 v[38:39], v[38:39], v[252:253] op_sel_hi:[1,0]
	v_pk_mul_f32 v[40:41], v[40:41], v[252:253] op_sel_hi:[1,0]
	v_pk_mul_f32 v[38:39], v[142:143], v[38:39]
	v_pk_mul_f32 v[40:41], v[144:145], v[40:41]
	v_pk_add_f32 v[150:151], v[150:151], 1.0 op_sel_hi:[1,0]
	v_pk_add_f32 v[152:153], v[152:153], 1.0 op_sel_hi:[1,0]
	v_pk_fma_f32 v[38:39], v[150:151], v[38:39], v[146:147]
	v_pk_fma_f32 v[40:41], v[152:153], v[40:41], v[148:149]
	s_nop 0
	v_cvt_pk_bf16_f32 v38, v38, v39
	v_cvt_pk_bf16_f32 v39, v40, v41
	global_store_dwordx2 v245, v[38:39], s[16:17] offset:512
	ds_read_b128 v[130:133], v238 offset:12288
	ds_read_b128 v[134:137], v238 offset:28672
	ds_read_b128 v[138:141], v238 offset:45056
	ds_read_b128 v[142:145], v238 offset:13312
	ds_read_b128 v[146:149], v238 offset:29696
	ds_read_b128 v[150:153], v238 offset:46080
	s_waitcnt lgkmcnt(6)
	v_pk_mul_f32 v[42:43], v[42:43], v[252:253] op_sel_hi:[1,0]
	v_pk_mul_f32 v[44:45], v[44:45], v[252:253] op_sel_hi:[1,0]
	v_pk_mul_f32 v[42:43], v[214:215], v[42:43]
	v_pk_mul_f32 v[44:45], v[216:217], v[44:45]
	v_pk_add_f32 v[222:223], v[222:223], 1.0 op_sel_hi:[1,0]
	v_pk_add_f32 v[224:225], v[224:225], 1.0 op_sel_hi:[1,0]
	v_pk_fma_f32 v[42:43], v[222:223], v[42:43], v[218:219]
	v_pk_fma_f32 v[44:45], v[224:225], v[44:45], v[220:221]
	s_nop 0
	v_cvt_pk_bf16_f32 v42, v42, v43
	v_cvt_pk_bf16_f32 v43, v44, v45
	global_store_dwordx2 v245, v[42:43], s[16:17] offset:1024
	v_pk_mul_f32 v[46:47], v[46:47], v[252:253] op_sel_hi:[1,0]
	v_pk_mul_f32 v[48:49], v[48:49], v[252:253] op_sel_hi:[1,0]
	v_pk_mul_f32 v[46:47], v[226:227], v[46:47]
	v_pk_mul_f32 v[48:49], v[228:229], v[48:49]
	v_pk_add_f32 v[234:235], v[234:235], 1.0 op_sel_hi:[1,0]
	v_pk_add_f32 v[236:237], v[236:237], 1.0 op_sel_hi:[1,0]
	v_pk_fma_f32 v[46:47], v[234:235], v[46:47], v[230:231]
	v_pk_fma_f32 v[48:49], v[236:237], v[48:49], v[232:233]
	s_nop 0
	v_cvt_pk_bf16_f32 v46, v46, v47
	v_cvt_pk_bf16_f32 v47, v48, v49
	global_store_dwordx2 v245, v[46:47], s[16:17] offset:1536
	ds_read_b128 v[214:217], v238 offset:14336
	ds_read_b128 v[218:221], v238 offset:30720
	ds_read_b128 v[222:225], v238 offset:47104
	ds_read_b128 v[226:229], v238 offset:15360
	ds_read_b128 v[230:233], v238 offset:31744
	ds_read_b128 v[234:237], v238 offset:48128
	s_waitcnt lgkmcnt(6)
	v_pk_mul_f32 v[50:51], v[50:51], v[252:253] op_sel_hi:[1,0]
	v_pk_mul_f32 v[52:53], v[52:53], v[252:253] op_sel_hi:[1,0]
	v_pk_mul_f32 v[50:51], v[130:131], v[50:51]
	v_pk_mul_f32 v[52:53], v[132:133], v[52:53]
	v_pk_add_f32 v[138:139], v[138:139], 1.0 op_sel_hi:[1,0]
	v_pk_add_f32 v[140:141], v[140:141], 1.0 op_sel_hi:[1,0]
	v_pk_fma_f32 v[50:51], v[138:139], v[50:51], v[134:135]
	v_pk_fma_f32 v[52:53], v[140:141], v[52:53], v[136:137]
	s_nop 0
	v_cvt_pk_bf16_f32 v50, v50, v51
	v_cvt_pk_bf16_f32 v51, v52, v53
	global_store_dwordx2 v245, v[50:51], s[16:17] offset:2048
	v_pk_mul_f32 v[54:55], v[54:55], v[252:253] op_sel_hi:[1,0]
	v_pk_mul_f32 v[56:57], v[56:57], v[252:253] op_sel_hi:[1,0]
	v_pk_mul_f32 v[54:55], v[142:143], v[54:55]
	v_pk_mul_f32 v[56:57], v[144:145], v[56:57]
	v_pk_add_f32 v[150:151], v[150:151], 1.0 op_sel_hi:[1,0]
	v_pk_add_f32 v[152:153], v[152:153], 1.0 op_sel_hi:[1,0]
	v_pk_fma_f32 v[54:55], v[150:151], v[54:55], v[146:147]
	v_pk_fma_f32 v[56:57], v[152:153], v[56:57], v[148:149]
	s_nop 0
	v_cvt_pk_bf16_f32 v54, v54, v55
	v_cvt_pk_bf16_f32 v55, v56, v57
	global_store_dwordx2 v245, v[54:55], s[16:17] offset:2560
	s_waitcnt lgkmcnt(0)
	v_pk_mul_f32 v[58:59], v[58:59], v[252:253] op_sel_hi:[1,0]
	v_pk_mul_f32 v[60:61], v[60:61], v[252:253] op_sel_hi:[1,0]
	v_pk_mul_f32 v[58:59], v[214:215], v[58:59]
	v_pk_mul_f32 v[60:61], v[216:217], v[60:61]
	v_pk_add_f32 v[222:223], v[222:223], 1.0 op_sel_hi:[1,0]
	v_pk_add_f32 v[224:225], v[224:225], 1.0 op_sel_hi:[1,0]
	v_pk_fma_f32 v[58:59], v[222:223], v[58:59], v[218:219]
	v_pk_fma_f32 v[60:61], v[224:225], v[60:61], v[220:221]
	s_nop 0
	v_cvt_pk_bf16_f32 v58, v58, v59
	v_cvt_pk_bf16_f32 v59, v60, v61
	global_store_dwordx2 v245, v[58:59], s[16:17] offset:3072
	v_pk_mul_f32 v[62:63], v[62:63], v[252:253] op_sel_hi:[1,0]
	v_pk_mul_f32 v[64:65], v[64:65], v[252:253] op_sel_hi:[1,0]
	v_pk_mul_f32 v[62:63], v[226:227], v[62:63]
	v_pk_mul_f32 v[64:65], v[228:229], v[64:65]
	v_pk_add_f32 v[234:235], v[234:235], 1.0 op_sel_hi:[1,0]
	v_pk_add_f32 v[236:237], v[236:237], 1.0 op_sel_hi:[1,0]
	v_pk_fma_f32 v[62:63], v[234:235], v[62:63], v[230:231]
	v_pk_fma_f32 v[64:65], v[236:237], v[64:65], v[232:233]
	s_nop 0
	v_cvt_pk_bf16_f32 v62, v62, v63
	v_cvt_pk_bf16_f32 v63, v64, v65
	global_store_dwordx2 v245, v[62:63], s[16:17] offset:3584
	s_add_u32 s16, s16, 0x1000000
	s_addc_u32 s17, s17, 0
	s_waitcnt vmcnt(16)
	s_add_u32 s14, s14, 0x2000000
	s_addc_u32 s15, s15, 0
	global_load_dwordx4 v[2:5], v238, s[14:15] offset:0 nt
	global_load_dwordx4 v[6:9], v238, s[14:15] offset:1024 nt
	global_load_dwordx4 v[10:13], v238, s[14:15] offset:2048 nt
	global_load_dwordx4 v[14:17], v238, s[14:15] offset:3072 nt
	global_load_dwordx4 v[18:21], v241, s[14:15] offset:0 nt
	global_load_dwordx4 v[22:25], v241, s[14:15] offset:1024 nt
	global_load_dwordx4 v[26:29], v241, s[14:15] offset:2048 nt
	global_load_dwordx4 v[30:33], v241, s[14:15] offset:3072 nt
	global_load_dwordx4 v[34:37], v242, s[14:15] offset:0 nt
	global_load_dwordx4 v[38:41], v242, s[14:15] offset:1024 nt
	global_load_dwordx4 v[42:45], v242, s[14:15] offset:2048 nt
	global_load_dwordx4 v[46:49], v242, s[14:15] offset:3072 nt
	global_load_dwordx4 v[50:53], v243, s[14:15] offset:0 nt
	global_load_dwordx4 v[54:57], v243, s[14:15] offset:1024 nt
	global_load_dwordx4 v[58:61], v243, s[14:15] offset:2048 nt
	global_load_dwordx4 v[62:65], v243, s[14:15] offset:3072 nt
	ds_read_b128 v[130:133], v238 offset:0
	ds_read_b128 v[134:137], v238 offset:16384
	ds_read_b128 v[138:141], v238 offset:32768
	ds_read_b128 v[142:145], v238 offset:1024
	ds_read_b128 v[146:149], v238 offset:17408
	ds_read_b128 v[150:153], v238 offset:33792
	v_pk_mul_f32 v[156:157], v[66:67], v[66:67]
	v_pk_mul_f32 v[158:159], v[68:69], v[68:69]
	v_pk_fma_f32 v[156:157], v[70:71], v[70:71], v[156:157]
	v_pk_fma_f32 v[158:159], v[72:73], v[72:73], v[158:159]
	v_pk_fma_f32 v[156:157], v[74:75], v[74:75], v[156:157]
	v_pk_fma_f32 v[158:159], v[76:77], v[76:77], v[158:159]
	v_pk_fma_f32 v[156:157], v[78:79], v[78:79], v[156:157]
	v_pk_fma_f32 v[158:159], v[80:81], v[80:81], v[158:159]
	v_pk_fma_f32 v[156:157], v[82:83], v[82:83], v[156:157]
	v_pk_fma_f32 v[158:159], v[84:85], v[84:85], v[158:159]
	v_pk_fma_f32 v[156:157], v[86:87], v[86:87], v[156:157]
	v_pk_fma_f32 v[158:159], v[88:89], v[88:89], v[158:159]
	v_pk_fma_f32 v[156:157], v[90:91], v[90:91], v[156:157]
	v_pk_fma_f32 v[158:159], v[92:93], v[92:93], v[158:159]
	v_pk_fma_f32 v[156:157], v[94:95], v[94:95], v[156:157]
	v_pk_fma_f32 v[158:159], v[96:97], v[96:97], v[158:159]
	v_pk_fma_f32 v[156:157], v[98:99], v[98:99], v[156:157]
	v_pk_fma_f32 v[158:159], v[100:101], v[100:101], v[158:159]
	v_pk_fma_f32 v[156:157], v[102:103], v[102:103], v[156:157]
	v_pk_fma_f32 v[158:159], v[104:105], v[104:105], v[158:159]
	v_pk_fma_f32 v[156:157], v[106:107], v[106:107], v[156:157]
	v_pk_fma_f32 v[158:159], v[108:109], v[108:109], v[158:159]
	v_pk_fma_f32 v[156:157], v[110:111], v[110:111], v[156:157]
	v_pk_fma_f32 v[158:159], v[112:113], v[112:113], v[158:159]
	v_pk_fma_f32 v[156:157], v[114:115], v[114:115], v[156:157]
	v_pk_fma_f32 v[158:159], v[116:117], v[116:117], v[158:159]
	v_pk_fma_f32 v[156:157], v[118:119], v[118:119], v[156:157]
	v_pk_fma_f32 v[158:159], v[120:121], v[120:121], v[158:159]
	v_pk_fma_f32 v[156:157], v[122:123], v[122:123], v[156:157]
	v_pk_fma_f32 v[158:159], v[124:125], v[124:125], v[158:159]
	v_pk_fma_f32 v[156:157], v[126:127], v[126:127], v[156:157]
	v_pk_fma_f32 v[158:159], v[128:129], v[128:129], v[158:159]
	v_pk_add_f32 v[156:157], v[156:157], v[158:159]
	s_nop 0
	v_add_f32_e32 v252, v156, v157
	s_waitcnt lgkmcnt(0)
	ds_bpermute_b32 v254, v246, v252
	s_waitcnt lgkmcnt(0)
	v_add_f32_e32 v252, v252, v254
	ds_bpermute_b32 v254, v247, v252
	s_waitcnt lgkmcnt(0)
	v_add_f32_e32 v252, v252, v254
	ds_bpermute_b32 v254, v248, v252
	s_waitcnt lgkmcnt(0)
	v_add_f32_e32 v252, v252, v254
	ds_bpermute_b32 v254, v249, v252
	s_waitcnt lgkmcnt(0)
	v_add_f32_e32 v252, v252, v254
	ds_bpermute_b32 v254, v250, v252
	s_waitcnt lgkmcnt(0)
	v_add_f32_e32 v252, v252, v254
	ds_bpermute_b32 v254, v251, v252
	s_waitcnt lgkmcnt(0)
	v_add_f32_e32 v252, v252, v254
	v_mov_b32_e32 v254, 0x358637bd
	v_fmac_f32_e32 v254, 0x39800000, v252
	v_mul_f32_e32 v252, 0x4b800000, v254
	v_cmp_gt_f32_e32 vcc, s20, v254
	s_nop 1
	v_cndmask_b32_e32 v254, v254, v252, vcc
	v_rsq_f32_e32 v254, v254
	s_nop 0
	v_mul_f32_e32 v252, 0x45800000, v254
	v_cndmask_b32_e32 v252, v254, v252, vcc
	ds_read_b128 v[214:217], v238 offset:2048
	ds_read_b128 v[218:221], v238 offset:18432
	ds_read_b128 v[222:225], v238 offset:34816
	ds_read_b128 v[226:229], v238 offset:3072
	ds_read_b128 v[230:233], v238 offset:19456
	ds_read_b128 v[234:237], v238 offset:35840
	s_waitcnt lgkmcnt(6)
	v_pk_mul_f32 v[66:67], v[66:67], v[252:253] op_sel_hi:[1,0]
	v_pk_mul_f32 v[68:69], v[68:69], v[252:253] op_sel_hi:[1,0]
	v_pk_mul_f32 v[66:67], v[130:131], v[66:67]
	v_pk_mul_f32 v[68:69], v[132:133], v[68:69]
	v_pk_add_f32 v[138:139], v[138:139], 1.0 op_sel_hi:[1,0]
	v_pk_add_f32 v[140:141], v[140:141], 1.0 op_sel_hi:[1,0]
	v_pk_fma_f32 v[66:67], v[138:139], v[66:67], v[134:135]
	v_pk_fma_f32 v[68:69], v[140:141], v[68:69], v[136:137]
	s_nop 0
	v_cvt_pk_bf16_f32 v66, v66, v67
	v_cvt_pk_bf16_f32 v67, v68, v69
	global_store_dwordx2 v244, v[66:67], s[16:17] offset:0
	v_pk_mul_f32 v[70:71], v[70:71], v[252:253] op_sel_hi:[1,0]
	v_pk_mul_f32 v[72:73], v[72:73], v[252:253] op_sel_hi:[1,0]
	v_pk_mul_f32 v[70:71], v[142:143], v[70:71]
	v_pk_mul_f32 v[72:73], v[144:145], v[72:73]
	v_pk_add_f32 v[150:151], v[150:151], 1.0 op_sel_hi:[1,0]
	v_pk_add_f32 v[152:153], v[152:153], 1.0 op_sel_hi:[1,0]
	v_pk_fma_f32 v[70:71], v[150:151], v[70:71], v[146:147]
	v_pk_fma_f32 v[72:73], v[152:153], v[72:73], v[148:149]
	s_nop 0
	v_cvt_pk_bf16_f32 v70, v70, v71
	v_cvt_pk_bf16_f32 v71, v72, v73
	global_store_dwordx2 v244, v[70:71], s[16:17] offset:512
	ds_read_b128 v[130:133], v238 offset:4096
	ds_read_b128 v[134:137], v238 offset:20480
	ds_read_b128 v[138:141], v238 offset:36864
	ds_read_b128 v[142:145], v238 offset:5120
	ds_read_b128 v[146:149], v238 offset:21504
	ds_read_b128 v[150:153], v238 offset:37888
	s_waitcnt lgkmcnt(6)
	v_pk_mul_f32 v[74:75], v[74:75], v[252:253] op_sel_hi:[1,0]
	v_pk_mul_f32 v[76:77], v[76:77], v[252:253] op_sel_hi:[1,0]
	v_pk_mul_f32 v[74:75], v[214:215], v[74:75]
	v_pk_mul_f32 v[76:77], v[216:217], v[76:77]
	v_pk_add_f32 v[222:223], v[222:223], 1.0 op_sel_hi:[1,0]
	v_pk_add_f32 v[224:225], v[224:225], 1.0 op_sel_hi:[1,0]
	v_pk_fma_f32 v[74:75], v[222:223], v[74:75], v[218:219]
	v_pk_fma_f32 v[76:77], v[224:225], v[76:77], v[220:221]
	s_nop 0
	v_cvt_pk_bf16_f32 v74, v74, v75
	v_cvt_pk_bf16_f32 v75, v76, v77
	global_store_dwordx2 v244, v[74:75], s[16:17] offset:1024
	v_pk_mul_f32 v[78:79], v[78:79], v[252:253] op_sel_hi:[1,0]
	v_pk_mul_f32 v[80:81], v[80:81], v[252:253] op_sel_hi:[1,0]
	v_pk_mul_f32 v[78:79], v[226:227], v[78:79]
	v_pk_mul_f32 v[80:81], v[228:229], v[80:81]
	v_pk_add_f32 v[234:235], v[234:235], 1.0 op_sel_hi:[1,0]
	v_pk_add_f32 v[236:237], v[236:237], 1.0 op_sel_hi:[1,0]
	v_pk_fma_f32 v[78:79], v[234:235], v[78:79], v[230:231]
	v_pk_fma_f32 v[80:81], v[236:237], v[80:81], v[232:233]
	s_nop 0
	v_cvt_pk_bf16_f32 v78, v78, v79
	v_cvt_pk_bf16_f32 v79, v80, v81
	global_store_dwordx2 v244, v[78:79], s[16:17] offset:1536
	ds_read_b128 v[214:217], v238 offset:6144
	ds_read_b128 v[218:221], v238 offset:22528
	ds_read_b128 v[222:225], v238 offset:38912
	ds_read_b128 v[226:229], v238 offset:7168
	ds_read_b128 v[230:233], v238 offset:23552
	ds_read_b128 v[234:237], v238 offset:39936
	s_waitcnt lgkmcnt(6)
	v_pk_mul_f32 v[82:83], v[82:83], v[252:253] op_sel_hi:[1,0]
	v_pk_mul_f32 v[84:85], v[84:85], v[252:253] op_sel_hi:[1,0]
	v_pk_mul_f32 v[82:83], v[130:131], v[82:83]
	v_pk_mul_f32 v[84:85], v[132:133], v[84:85]
	v_pk_add_f32 v[138:139], v[138:139], 1.0 op_sel_hi:[1,0]
	v_pk_add_f32 v[140:141], v[140:141], 1.0 op_sel_hi:[1,0]
	v_pk_fma_f32 v[82:83], v[138:139], v[82:83], v[134:135]
	v_pk_fma_f32 v[84:85], v[140:141], v[84:85], v[136:137]
	s_nop 0
	v_cvt_pk_bf16_f32 v82, v82, v83
	v_cvt_pk_bf16_f32 v83, v84, v85
	global_store_dwordx2 v244, v[82:83], s[16:17] offset:2048
	v_pk_mul_f32 v[86:87], v[86:87], v[252:253] op_sel_hi:[1,0]
	v_pk_mul_f32 v[88:89], v[88:89], v[252:253] op_sel_hi:[1,0]
	v_pk_mul_f32 v[86:87], v[142:143], v[86:87]
	v_pk_mul_f32 v[88:89], v[144:145], v[88:89]
	v_pk_add_f32 v[150:151], v[150:151], 1.0 op_sel_hi:[1,0]
	v_pk_add_f32 v[152:153], v[152:153], 1.0 op_sel_hi:[1,0]
	v_pk_fma_f32 v[86:87], v[150:151], v[86:87], v[146:147]
	v_pk_fma_f32 v[88:89], v[152:153], v[88:89], v[148:149]
	s_nop 0
	v_cvt_pk_bf16_f32 v86, v86, v87
	v_cvt_pk_bf16_f32 v87, v88, v89
	global_store_dwordx2 v244, v[86:87], s[16:17] offset:2560
	ds_read_b128 v[130:133], v238 offset:8192
	ds_read_b128 v[134:137], v238 offset:24576
	ds_read_b128 v[138:141], v238 offset:40960
	ds_read_b128 v[142:145], v238 offset:9216
	ds_read_b128 v[146:149], v238 offset:25600
	ds_read_b128 v[150:153], v238 offset:41984
	s_waitcnt lgkmcnt(6)
	v_pk_mul_f32 v[90:91], v[90:91], v[252:253] op_sel_hi:[1,0]
	v_pk_mul_f32 v[92:93], v[92:93], v[252:253] op_sel_hi:[1,0]
	v_pk_mul_f32 v[90:91], v[214:215], v[90:91]
	v_pk_mul_f32 v[92:93], v[216:217], v[92:93]
	v_pk_add_f32 v[222:223], v[222:223], 1.0 op_sel_hi:[1,0]
	v_pk_add_f32 v[224:225], v[224:225], 1.0 op_sel_hi:[1,0]
	v_pk_fma_f32 v[90:91], v[222:223], v[90:91], v[218:219]
	v_pk_fma_f32 v[92:93], v[224:225], v[92:93], v[220:221]
	s_nop 0
	v_cvt_pk_bf16_f32 v90, v90, v91
	v_cvt_pk_bf16_f32 v91, v92, v93
	global_store_dwordx2 v244, v[90:91], s[16:17] offset:3072
	v_pk_mul_f32 v[94:95], v[94:95], v[252:253] op_sel_hi:[1,0]
	v_pk_mul_f32 v[96:97], v[96:97], v[252:253] op_sel_hi:[1,0]
	v_pk_mul_f32 v[94:95], v[226:227], v[94:95]
	v_pk_mul_f32 v[96:97], v[228:229], v[96:97]
	v_pk_add_f32 v[234:235], v[234:235], 1.0 op_sel_hi:[1,0]
	v_pk_add_f32 v[236:237], v[236:237], 1.0 op_sel_hi:[1,0]
	v_pk_fma_f32 v[94:95], v[234:235], v[94:95], v[230:231]
	v_pk_fma_f32 v[96:97], v[236:237], v[96:97], v[232:233]
	s_nop 0
	v_cvt_pk_bf16_f32 v94, v94, v95
	v_cvt_pk_bf16_f32 v95, v96, v97
	global_store_dwordx2 v244, v[94:95], s[16:17] offset:3584
	ds_read_b128 v[214:217], v238 offset:10240
	ds_read_b128 v[218:221], v238 offset:26624
	ds_read_b128 v[222:225], v238 offset:43008
	ds_read_b128 v[226:229], v238 offset:11264
	ds_read_b128 v[230:233], v238 offset:27648
	ds_read_b128 v[234:237], v238 offset:44032
	s_waitcnt lgkmcnt(6)
	v_pk_mul_f32 v[98:99], v[98:99], v[252:253] op_sel_hi:[1,0]
	v_pk_mul_f32 v[100:101], v[100:101], v[252:253] op_sel_hi:[1,0]
	v_pk_mul_f32 v[98:99], v[130:131], v[98:99]
	v_pk_mul_f32 v[100:101], v[132:133], v[100:101]
	v_pk_add_f32 v[138:139], v[138:139], 1.0 op_sel_hi:[1,0]
	v_pk_add_f32 v[140:141], v[140:141], 1.0 op_sel_hi:[1,0]
	v_pk_fma_f32 v[98:99], v[138:139], v[98:99], v[134:135]
	v_pk_fma_f32 v[100:101], v[140:141], v[100:101], v[136:137]
	s_nop 0
	v_cvt_pk_bf16_f32 v98, v98, v99
	v_cvt_pk_bf16_f32 v99, v100, v101
	global_store_dwordx2 v245, v[98:99], s[16:17] offset:0
	v_pk_mul_f32 v[102:103], v[102:103], v[252:253] op_sel_hi:[1,0]
	v_pk_mul_f32 v[104:105], v[104:105], v[252:253] op_sel_hi:[1,0]
	v_pk_mul_f32 v[102:103], v[142:143], v[102:103]
	v_pk_mul_f32 v[104:105], v[144:145], v[104:105]
	v_pk_add_f32 v[150:151], v[150:151], 1.0 op_sel_hi:[1,0]
	v_pk_add_f32 v[152:153], v[152:153], 1.0 op_sel_hi:[1,0]
	v_pk_fma_f32 v[102:103], v[150:151], v[102:103], v[146:147]
	v_pk_fma_f32 v[104:105], v[152:153], v[104:105], v[148:149]
	s_nop 0
	v_cvt_pk_bf16_f32 v102, v102, v103
	v_cvt_pk_bf16_f32 v103, v104, v105
	global_store_dwordx2 v245, v[102:103], s[16:17] offset:512
	ds_read_b128 v[130:133], v238 offset:12288
	ds_read_b128 v[134:137], v238 offset:28672
	ds_read_b128 v[138:141], v238 offset:45056
	ds_read_b128 v[142:145], v238 offset:13312
	ds_read_b128 v[146:149], v238 offset:29696
	ds_read_b128 v[150:153], v238 offset:46080
	s_waitcnt lgkmcnt(6)
	v_pk_mul_f32 v[106:107], v[106:107], v[252:253] op_sel_hi:[1,0]
	v_pk_mul_f32 v[108:109], v[108:109], v[252:253] op_sel_hi:[1,0]
	v_pk_mul_f32 v[106:107], v[214:215], v[106:107]
	v_pk_mul_f32 v[108:109], v[216:217], v[108:109]
	v_pk_add_f32 v[222:223], v[222:223], 1.0 op_sel_hi:[1,0]
	v_pk_add_f32 v[224:225], v[224:225], 1.0 op_sel_hi:[1,0]
	v_pk_fma_f32 v[106:107], v[222:223], v[106:107], v[218:219]
	v_pk_fma_f32 v[108:109], v[224:225], v[108:109], v[220:221]
	s_nop 0
	v_cvt_pk_bf16_f32 v106, v106, v107
	v_cvt_pk_bf16_f32 v107, v108, v109
	global_store_dwordx2 v245, v[106:107], s[16:17] offset:1024
	v_pk_mul_f32 v[110:111], v[110:111], v[252:253] op_sel_hi:[1,0]
	v_pk_mul_f32 v[112:113], v[112:113], v[252:253] op_sel_hi:[1,0]
	v_pk_mul_f32 v[110:111], v[226:227], v[110:111]
	v_pk_mul_f32 v[112:113], v[228:229], v[112:113]
	v_pk_add_f32 v[234:235], v[234:235], 1.0 op_sel_hi:[1,0]
	v_pk_add_f32 v[236:237], v[236:237], 1.0 op_sel_hi:[1,0]
	v_pk_fma_f32 v[110:111], v[234:235], v[110:111], v[230:231]
	v_pk_fma_f32 v[112:113], v[236:237], v[112:113], v[232:233]
	s_nop 0
	v_cvt_pk_bf16_f32 v110, v110, v111
	v_cvt_pk_bf16_f32 v111, v112, v113
	global_store_dwordx2 v245, v[110:111], s[16:17] offset:1536
	ds_read_b128 v[214:217], v238 offset:14336
	ds_read_b128 v[218:221], v238 offset:30720
	ds_read_b128 v[222:225], v238 offset:47104
	ds_read_b128 v[226:229], v238 offset:15360
	ds_read_b128 v[230:233], v238 offset:31744
	ds_read_b128 v[234:237], v238 offset:48128
	s_waitcnt lgkmcnt(6)
	v_pk_mul_f32 v[114:115], v[114:115], v[252:253] op_sel_hi:[1,0]
	v_pk_mul_f32 v[116:117], v[116:117], v[252:253] op_sel_hi:[1,0]
	v_pk_mul_f32 v[114:115], v[130:131], v[114:115]
	v_pk_mul_f32 v[116:117], v[132:133], v[116:117]
	v_pk_add_f32 v[138:139], v[138:139], 1.0 op_sel_hi:[1,0]
	v_pk_add_f32 v[140:141], v[140:141], 1.0 op_sel_hi:[1,0]
	v_pk_fma_f32 v[114:115], v[138:139], v[114:115], v[134:135]
	v_pk_fma_f32 v[116:117], v[140:141], v[116:117], v[136:137]
	s_nop 0
	v_cvt_pk_bf16_f32 v114, v114, v115
	v_cvt_pk_bf16_f32 v115, v116, v117
	global_store_dwordx2 v245, v[114:115], s[16:17] offset:2048
	v_pk_mul_f32 v[118:119], v[118:119], v[252:253] op_sel_hi:[1,0]
	v_pk_mul_f32 v[120:121], v[120:121], v[252:253] op_sel_hi:[1,0]
	v_pk_mul_f32 v[118:119], v[142:143], v[118:119]
	v_pk_mul_f32 v[120:121], v[144:145], v[120:121]
	v_pk_add_f32 v[150:151], v[150:151], 1.0 op_sel_hi:[1,0]
	v_pk_add_f32 v[152:153], v[152:153], 1.0 op_sel_hi:[1,0]
	v_pk_fma_f32 v[118:119], v[150:151], v[118:119], v[146:147]
	v_pk_fma_f32 v[120:121], v[152:153], v[120:121], v[148:149]
	s_nop 0
	v_cvt_pk_bf16_f32 v118, v118, v119
	v_cvt_pk_bf16_f32 v119, v120, v121
	global_store_dwordx2 v245, v[118:119], s[16:17] offset:2560
	s_waitcnt lgkmcnt(0)
	v_pk_mul_f32 v[122:123], v[122:123], v[252:253] op_sel_hi:[1,0]
	v_pk_mul_f32 v[124:125], v[124:125], v[252:253] op_sel_hi:[1,0]
	v_pk_mul_f32 v[122:123], v[214:215], v[122:123]
	v_pk_mul_f32 v[124:125], v[216:217], v[124:125]
	v_pk_add_f32 v[222:223], v[222:223], 1.0 op_sel_hi:[1,0]
	v_pk_add_f32 v[224:225], v[224:225], 1.0 op_sel_hi:[1,0]
	v_pk_fma_f32 v[122:123], v[222:223], v[122:123], v[218:219]
	v_pk_fma_f32 v[124:125], v[224:225], v[124:125], v[220:221]
	s_nop 0
	v_cvt_pk_bf16_f32 v122, v122, v123
	v_cvt_pk_bf16_f32 v123, v124, v125
	global_store_dwordx2 v245, v[122:123], s[16:17] offset:3072
	v_pk_mul_f32 v[126:127], v[126:127], v[252:253] op_sel_hi:[1,0]
	v_pk_mul_f32 v[128:129], v[128:129], v[252:253] op_sel_hi:[1,0]
	v_pk_mul_f32 v[126:127], v[226:227], v[126:127]
	v_pk_mul_f32 v[128:129], v[228:229], v[128:129]
	v_pk_add_f32 v[234:235], v[234:235], 1.0 op_sel_hi:[1,0]
	v_pk_add_f32 v[236:237], v[236:237], 1.0 op_sel_hi:[1,0]
	v_pk_fma_f32 v[126:127], v[234:235], v[126:127], v[230:231]
	v_pk_fma_f32 v[128:129], v[236:237], v[128:129], v[232:233]
	s_nop 0
	v_cvt_pk_bf16_f32 v126, v126, v127
	v_cvt_pk_bf16_f32 v127, v128, v129
	global_store_dwordx2 v245, v[126:127], s[16:17] offset:3584
	s_add_u32 s16, s16, 0x1000000
	s_addc_u32 s17, s17, 0
	s_waitcnt vmcnt(16)
	s_add_u32 s14, s14, 0x2000000
	s_addc_u32 s15, s15, 0
	global_load_dwordx4 v[66:69], v238, s[14:15] offset:0 nt
	global_load_dwordx4 v[70:73], v238, s[14:15] offset:1024 nt
	global_load_dwordx4 v[74:77], v238, s[14:15] offset:2048 nt
	global_load_dwordx4 v[78:81], v238, s[14:15] offset:3072 nt
	global_load_dwordx4 v[82:85], v241, s[14:15] offset:0 nt
	global_load_dwordx4 v[86:89], v241, s[14:15] offset:1024 nt
	global_load_dwordx4 v[90:93], v241, s[14:15] offset:2048 nt
	global_load_dwordx4 v[94:97], v241, s[14:15] offset:3072 nt
	global_load_dwordx4 v[98:101], v242, s[14:15] offset:0 nt
	global_load_dwordx4 v[102:105], v242, s[14:15] offset:1024 nt
	global_load_dwordx4 v[106:109], v242, s[14:15] offset:2048 nt
	global_load_dwordx4 v[110:113], v242, s[14:15] offset:3072 nt
	global_load_dwordx4 v[114:117], v243, s[14:15] offset:0 nt
	global_load_dwordx4 v[118:121], v243, s[14:15] offset:1024 nt
	global_load_dwordx4 v[122:125], v243, s[14:15] offset:2048 nt
	global_load_dwordx4 v[126:129], v243, s[14:15] offset:3072 nt
	ds_read_b128 v[130:133], v238 offset:0
	ds_read_b128 v[134:137], v238 offset:16384
	ds_read_b128 v[138:141], v238 offset:32768
	ds_read_b128 v[142:145], v238 offset:1024
	ds_read_b128 v[146:149], v238 offset:17408
	ds_read_b128 v[150:153], v238 offset:33792
	v_pk_mul_f32 v[156:157], v[2:3], v[2:3]
	v_pk_mul_f32 v[158:159], v[4:5], v[4:5]
	v_pk_fma_f32 v[156:157], v[6:7], v[6:7], v[156:157]
	v_pk_fma_f32 v[158:159], v[8:9], v[8:9], v[158:159]
	v_pk_fma_f32 v[156:157], v[10:11], v[10:11], v[156:157]
	v_pk_fma_f32 v[158:159], v[12:13], v[12:13], v[158:159]
	v_pk_fma_f32 v[156:157], v[14:15], v[14:15], v[156:157]
	v_pk_fma_f32 v[158:159], v[16:17], v[16:17], v[158:159]
	v_pk_fma_f32 v[156:157], v[18:19], v[18:19], v[156:157]
	v_pk_fma_f32 v[158:159], v[20:21], v[20:21], v[158:159]
	v_pk_fma_f32 v[156:157], v[22:23], v[22:23], v[156:157]
	v_pk_fma_f32 v[158:159], v[24:25], v[24:25], v[158:159]
	v_pk_fma_f32 v[156:157], v[26:27], v[26:27], v[156:157]
	v_pk_fma_f32 v[158:159], v[28:29], v[28:29], v[158:159]
	v_pk_fma_f32 v[156:157], v[30:31], v[30:31], v[156:157]
	v_pk_fma_f32 v[158:159], v[32:33], v[32:33], v[158:159]
	v_pk_fma_f32 v[156:157], v[34:35], v[34:35], v[156:157]
	v_pk_fma_f32 v[158:159], v[36:37], v[36:37], v[158:159]
	v_pk_fma_f32 v[156:157], v[38:39], v[38:39], v[156:157]
	v_pk_fma_f32 v[158:159], v[40:41], v[40:41], v[158:159]
	v_pk_fma_f32 v[156:157], v[42:43], v[42:43], v[156:157]
	v_pk_fma_f32 v[158:159], v[44:45], v[44:45], v[158:159]
	v_pk_fma_f32 v[156:157], v[46:47], v[46:47], v[156:157]
	v_pk_fma_f32 v[158:159], v[48:49], v[48:49], v[158:159]
	v_pk_fma_f32 v[156:157], v[50:51], v[50:51], v[156:157]
	v_pk_fma_f32 v[158:159], v[52:53], v[52:53], v[158:159]
	v_pk_fma_f32 v[156:157], v[54:55], v[54:55], v[156:157]
	v_pk_fma_f32 v[158:159], v[56:57], v[56:57], v[158:159]
	v_pk_fma_f32 v[156:157], v[58:59], v[58:59], v[156:157]
	v_pk_fma_f32 v[158:159], v[60:61], v[60:61], v[158:159]
	v_pk_fma_f32 v[156:157], v[62:63], v[62:63], v[156:157]
	v_pk_fma_f32 v[158:159], v[64:65], v[64:65], v[158:159]
	v_pk_add_f32 v[156:157], v[156:157], v[158:159]
	s_nop 0
	v_add_f32_e32 v252, v156, v157
	s_waitcnt lgkmcnt(0)
	ds_bpermute_b32 v254, v246, v252
	s_waitcnt lgkmcnt(0)
	v_add_f32_e32 v252, v252, v254
	ds_bpermute_b32 v254, v247, v252
	s_waitcnt lgkmcnt(0)
	v_add_f32_e32 v252, v252, v254
	ds_bpermute_b32 v254, v248, v252
	s_waitcnt lgkmcnt(0)
	v_add_f32_e32 v252, v252, v254
	ds_bpermute_b32 v254, v249, v252
	s_waitcnt lgkmcnt(0)
	v_add_f32_e32 v252, v252, v254
	ds_bpermute_b32 v254, v250, v252
	s_waitcnt lgkmcnt(0)
	v_add_f32_e32 v252, v252, v254
	ds_bpermute_b32 v254, v251, v252
	s_waitcnt lgkmcnt(0)
	v_add_f32_e32 v252, v252, v254
	v_mov_b32_e32 v254, 0x358637bd
	v_fmac_f32_e32 v254, 0x39800000, v252
	v_mul_f32_e32 v252, 0x4b800000, v254
	v_cmp_gt_f32_e32 vcc, s20, v254
	s_nop 1
	v_cndmask_b32_e32 v254, v254, v252, vcc
	v_rsq_f32_e32 v254, v254
	s_nop 0
	v_mul_f32_e32 v252, 0x45800000, v254
	v_cndmask_b32_e32 v252, v254, v252, vcc
	ds_read_b128 v[214:217], v238 offset:2048
	ds_read_b128 v[218:221], v238 offset:18432
	ds_read_b128 v[222:225], v238 offset:34816
	ds_read_b128 v[226:229], v238 offset:3072
	ds_read_b128 v[230:233], v238 offset:19456
	ds_read_b128 v[234:237], v238 offset:35840
	s_waitcnt lgkmcnt(6)
	v_pk_mul_f32 v[2:3], v[2:3], v[252:253] op_sel_hi:[1,0]
	v_pk_mul_f32 v[4:5], v[4:5], v[252:253] op_sel_hi:[1,0]
	v_pk_mul_f32 v[2:3], v[130:131], v[2:3]
	v_pk_mul_f32 v[4:5], v[132:133], v[4:5]
	v_pk_add_f32 v[138:139], v[138:139], 1.0 op_sel_hi:[1,0]
	v_pk_add_f32 v[140:141], v[140:141], 1.0 op_sel_hi:[1,0]
	v_pk_fma_f32 v[2:3], v[138:139], v[2:3], v[134:135]
	v_pk_fma_f32 v[4:5], v[140:141], v[4:5], v[136:137]
	s_nop 0
	v_cvt_pk_bf16_f32 v2, v2, v3
	v_cvt_pk_bf16_f32 v3, v4, v5
	global_store_dwordx2 v244, v[2:3], s[16:17] offset:0
	v_pk_mul_f32 v[6:7], v[6:7], v[252:253] op_sel_hi:[1,0]
	v_pk_mul_f32 v[8:9], v[8:9], v[252:253] op_sel_hi:[1,0]
	v_pk_mul_f32 v[6:7], v[142:143], v[6:7]
	v_pk_mul_f32 v[8:9], v[144:145], v[8:9]
	v_pk_add_f32 v[150:151], v[150:151], 1.0 op_sel_hi:[1,0]
	v_pk_add_f32 v[152:153], v[152:153], 1.0 op_sel_hi:[1,0]
	v_pk_fma_f32 v[6:7], v[150:151], v[6:7], v[146:147]
	v_pk_fma_f32 v[8:9], v[152:153], v[8:9], v[148:149]
	s_nop 0
	v_cvt_pk_bf16_f32 v6, v6, v7
	v_cvt_pk_bf16_f32 v7, v8, v9
	global_store_dwordx2 v244, v[6:7], s[16:17] offset:512
	ds_read_b128 v[130:133], v238 offset:4096
	ds_read_b128 v[134:137], v238 offset:20480
	ds_read_b128 v[138:141], v238 offset:36864
	ds_read_b128 v[142:145], v238 offset:5120
	ds_read_b128 v[146:149], v238 offset:21504
	ds_read_b128 v[150:153], v238 offset:37888
	s_waitcnt lgkmcnt(6)
	v_pk_mul_f32 v[10:11], v[10:11], v[252:253] op_sel_hi:[1,0]
	v_pk_mul_f32 v[12:13], v[12:13], v[252:253] op_sel_hi:[1,0]
	v_pk_mul_f32 v[10:11], v[214:215], v[10:11]
	v_pk_mul_f32 v[12:13], v[216:217], v[12:13]
	v_pk_add_f32 v[222:223], v[222:223], 1.0 op_sel_hi:[1,0]
	v_pk_add_f32 v[224:225], v[224:225], 1.0 op_sel_hi:[1,0]
	v_pk_fma_f32 v[10:11], v[222:223], v[10:11], v[218:219]
	v_pk_fma_f32 v[12:13], v[224:225], v[12:13], v[220:221]
	s_nop 0
	v_cvt_pk_bf16_f32 v10, v10, v11
	v_cvt_pk_bf16_f32 v11, v12, v13
	global_store_dwordx2 v244, v[10:11], s[16:17] offset:1024
	v_pk_mul_f32 v[14:15], v[14:15], v[252:253] op_sel_hi:[1,0]
	v_pk_mul_f32 v[16:17], v[16:17], v[252:253] op_sel_hi:[1,0]
	v_pk_mul_f32 v[14:15], v[226:227], v[14:15]
	v_pk_mul_f32 v[16:17], v[228:229], v[16:17]
	v_pk_add_f32 v[234:235], v[234:235], 1.0 op_sel_hi:[1,0]
	v_pk_add_f32 v[236:237], v[236:237], 1.0 op_sel_hi:[1,0]
	v_pk_fma_f32 v[14:15], v[234:235], v[14:15], v[230:231]
	v_pk_fma_f32 v[16:17], v[236:237], v[16:17], v[232:233]
	s_nop 0
	v_cvt_pk_bf16_f32 v14, v14, v15
	v_cvt_pk_bf16_f32 v15, v16, v17
	global_store_dwordx2 v244, v[14:15], s[16:17] offset:1536
	ds_read_b128 v[214:217], v238 offset:6144
	ds_read_b128 v[218:221], v238 offset:22528
	ds_read_b128 v[222:225], v238 offset:38912
	ds_read_b128 v[226:229], v238 offset:7168
	ds_read_b128 v[230:233], v238 offset:23552
	ds_read_b128 v[234:237], v238 offset:39936
	s_waitcnt lgkmcnt(6)
	v_pk_mul_f32 v[18:19], v[18:19], v[252:253] op_sel_hi:[1,0]
	v_pk_mul_f32 v[20:21], v[20:21], v[252:253] op_sel_hi:[1,0]
	v_pk_mul_f32 v[18:19], v[130:131], v[18:19]
	v_pk_mul_f32 v[20:21], v[132:133], v[20:21]
	v_pk_add_f32 v[138:139], v[138:139], 1.0 op_sel_hi:[1,0]
	v_pk_add_f32 v[140:141], v[140:141], 1.0 op_sel_hi:[1,0]
	v_pk_fma_f32 v[18:19], v[138:139], v[18:19], v[134:135]
	v_pk_fma_f32 v[20:21], v[140:141], v[20:21], v[136:137]
	s_nop 0
	v_cvt_pk_bf16_f32 v18, v18, v19
	v_cvt_pk_bf16_f32 v19, v20, v21
	global_store_dwordx2 v244, v[18:19], s[16:17] offset:2048
	v_pk_mul_f32 v[22:23], v[22:23], v[252:253] op_sel_hi:[1,0]
	v_pk_mul_f32 v[24:25], v[24:25], v[252:253] op_sel_hi:[1,0]
	v_pk_mul_f32 v[22:23], v[142:143], v[22:23]
	v_pk_mul_f32 v[24:25], v[144:145], v[24:25]
	v_pk_add_f32 v[150:151], v[150:151], 1.0 op_sel_hi:[1,0]
	v_pk_add_f32 v[152:153], v[152:153], 1.0 op_sel_hi:[1,0]
	v_pk_fma_f32 v[22:23], v[150:151], v[22:23], v[146:147]
	v_pk_fma_f32 v[24:25], v[152:153], v[24:25], v[148:149]
	s_nop 0
	v_cvt_pk_bf16_f32 v22, v22, v23
	v_cvt_pk_bf16_f32 v23, v24, v25
	global_store_dwordx2 v244, v[22:23], s[16:17] offset:2560
	ds_read_b128 v[130:133], v238 offset:8192
	ds_read_b128 v[134:137], v238 offset:24576
	ds_read_b128 v[138:141], v238 offset:40960
	ds_read_b128 v[142:145], v238 offset:9216
	ds_read_b128 v[146:149], v238 offset:25600
	ds_read_b128 v[150:153], v238 offset:41984
	s_waitcnt lgkmcnt(6)
	v_pk_mul_f32 v[26:27], v[26:27], v[252:253] op_sel_hi:[1,0]
	v_pk_mul_f32 v[28:29], v[28:29], v[252:253] op_sel_hi:[1,0]
	v_pk_mul_f32 v[26:27], v[214:215], v[26:27]
	v_pk_mul_f32 v[28:29], v[216:217], v[28:29]
	v_pk_add_f32 v[222:223], v[222:223], 1.0 op_sel_hi:[1,0]
	v_pk_add_f32 v[224:225], v[224:225], 1.0 op_sel_hi:[1,0]
	v_pk_fma_f32 v[26:27], v[222:223], v[26:27], v[218:219]
	v_pk_fma_f32 v[28:29], v[224:225], v[28:29], v[220:221]
	s_nop 0
	v_cvt_pk_bf16_f32 v26, v26, v27
	v_cvt_pk_bf16_f32 v27, v28, v29
	global_store_dwordx2 v244, v[26:27], s[16:17] offset:3072
	v_pk_mul_f32 v[30:31], v[30:31], v[252:253] op_sel_hi:[1,0]
	v_pk_mul_f32 v[32:33], v[32:33], v[252:253] op_sel_hi:[1,0]
	v_pk_mul_f32 v[30:31], v[226:227], v[30:31]
	v_pk_mul_f32 v[32:33], v[228:229], v[32:33]
	v_pk_add_f32 v[234:235], v[234:235], 1.0 op_sel_hi:[1,0]
	v_pk_add_f32 v[236:237], v[236:237], 1.0 op_sel_hi:[1,0]
	v_pk_fma_f32 v[30:31], v[234:235], v[30:31], v[230:231]
	v_pk_fma_f32 v[32:33], v[236:237], v[32:33], v[232:233]
	s_nop 0
	v_cvt_pk_bf16_f32 v30, v30, v31
	v_cvt_pk_bf16_f32 v31, v32, v33
	global_store_dwordx2 v244, v[30:31], s[16:17] offset:3584
	ds_read_b128 v[214:217], v238 offset:10240
	ds_read_b128 v[218:221], v238 offset:26624
	ds_read_b128 v[222:225], v238 offset:43008
	ds_read_b128 v[226:229], v238 offset:11264
	ds_read_b128 v[230:233], v238 offset:27648
	ds_read_b128 v[234:237], v238 offset:44032
	s_waitcnt lgkmcnt(6)
	v_pk_mul_f32 v[34:35], v[34:35], v[252:253] op_sel_hi:[1,0]
	v_pk_mul_f32 v[36:37], v[36:37], v[252:253] op_sel_hi:[1,0]
	v_pk_mul_f32 v[34:35], v[130:131], v[34:35]
	v_pk_mul_f32 v[36:37], v[132:133], v[36:37]
	v_pk_add_f32 v[138:139], v[138:139], 1.0 op_sel_hi:[1,0]
	v_pk_add_f32 v[140:141], v[140:141], 1.0 op_sel_hi:[1,0]
	v_pk_fma_f32 v[34:35], v[138:139], v[34:35], v[134:135]
	v_pk_fma_f32 v[36:37], v[140:141], v[36:37], v[136:137]
	s_nop 0
	v_cvt_pk_bf16_f32 v34, v34, v35
	v_cvt_pk_bf16_f32 v35, v36, v37
	global_store_dwordx2 v245, v[34:35], s[16:17] offset:0
	v_pk_mul_f32 v[38:39], v[38:39], v[252:253] op_sel_hi:[1,0]
	v_pk_mul_f32 v[40:41], v[40:41], v[252:253] op_sel_hi:[1,0]
	v_pk_mul_f32 v[38:39], v[142:143], v[38:39]
	v_pk_mul_f32 v[40:41], v[144:145], v[40:41]
	v_pk_add_f32 v[150:151], v[150:151], 1.0 op_sel_hi:[1,0]
	v_pk_add_f32 v[152:153], v[152:153], 1.0 op_sel_hi:[1,0]
	v_pk_fma_f32 v[38:39], v[150:151], v[38:39], v[146:147]
	v_pk_fma_f32 v[40:41], v[152:153], v[40:41], v[148:149]
	s_nop 0
	v_cvt_pk_bf16_f32 v38, v38, v39
	v_cvt_pk_bf16_f32 v39, v40, v41
	global_store_dwordx2 v245, v[38:39], s[16:17] offset:512
	ds_read_b128 v[130:133], v238 offset:12288
	ds_read_b128 v[134:137], v238 offset:28672
	ds_read_b128 v[138:141], v238 offset:45056
	ds_read_b128 v[142:145], v238 offset:13312
	ds_read_b128 v[146:149], v238 offset:29696
	ds_read_b128 v[150:153], v238 offset:46080
	s_waitcnt lgkmcnt(6)
	v_pk_mul_f32 v[42:43], v[42:43], v[252:253] op_sel_hi:[1,0]
	v_pk_mul_f32 v[44:45], v[44:45], v[252:253] op_sel_hi:[1,0]
	v_pk_mul_f32 v[42:43], v[214:215], v[42:43]
	v_pk_mul_f32 v[44:45], v[216:217], v[44:45]
	v_pk_add_f32 v[222:223], v[222:223], 1.0 op_sel_hi:[1,0]
	v_pk_add_f32 v[224:225], v[224:225], 1.0 op_sel_hi:[1,0]
	v_pk_fma_f32 v[42:43], v[222:223], v[42:43], v[218:219]
	v_pk_fma_f32 v[44:45], v[224:225], v[44:45], v[220:221]
	s_nop 0
	v_cvt_pk_bf16_f32 v42, v42, v43
	v_cvt_pk_bf16_f32 v43, v44, v45
	global_store_dwordx2 v245, v[42:43], s[16:17] offset:1024
	v_pk_mul_f32 v[46:47], v[46:47], v[252:253] op_sel_hi:[1,0]
	v_pk_mul_f32 v[48:49], v[48:49], v[252:253] op_sel_hi:[1,0]
	v_pk_mul_f32 v[46:47], v[226:227], v[46:47]
	v_pk_mul_f32 v[48:49], v[228:229], v[48:49]
	v_pk_add_f32 v[234:235], v[234:235], 1.0 op_sel_hi:[1,0]
	v_pk_add_f32 v[236:237], v[236:237], 1.0 op_sel_hi:[1,0]
	v_pk_fma_f32 v[46:47], v[234:235], v[46:47], v[230:231]
	v_pk_fma_f32 v[48:49], v[236:237], v[48:49], v[232:233]
	s_nop 0
	v_cvt_pk_bf16_f32 v46, v46, v47
	v_cvt_pk_bf16_f32 v47, v48, v49
	global_store_dwordx2 v245, v[46:47], s[16:17] offset:1536
	ds_read_b128 v[214:217], v238 offset:14336
	ds_read_b128 v[218:221], v238 offset:30720
	ds_read_b128 v[222:225], v238 offset:47104
	ds_read_b128 v[226:229], v238 offset:15360
	ds_read_b128 v[230:233], v238 offset:31744
	ds_read_b128 v[234:237], v238 offset:48128
	s_waitcnt lgkmcnt(6)
	v_pk_mul_f32 v[50:51], v[50:51], v[252:253] op_sel_hi:[1,0]
	v_pk_mul_f32 v[52:53], v[52:53], v[252:253] op_sel_hi:[1,0]
	v_pk_mul_f32 v[50:51], v[130:131], v[50:51]
	v_pk_mul_f32 v[52:53], v[132:133], v[52:53]
	v_pk_add_f32 v[138:139], v[138:139], 1.0 op_sel_hi:[1,0]
	v_pk_add_f32 v[140:141], v[140:141], 1.0 op_sel_hi:[1,0]
	v_pk_fma_f32 v[50:51], v[138:139], v[50:51], v[134:135]
	v_pk_fma_f32 v[52:53], v[140:141], v[52:53], v[136:137]
	s_nop 0
	v_cvt_pk_bf16_f32 v50, v50, v51
	v_cvt_pk_bf16_f32 v51, v52, v53
	global_store_dwordx2 v245, v[50:51], s[16:17] offset:2048
	v_pk_mul_f32 v[54:55], v[54:55], v[252:253] op_sel_hi:[1,0]
	v_pk_mul_f32 v[56:57], v[56:57], v[252:253] op_sel_hi:[1,0]
	v_pk_mul_f32 v[54:55], v[142:143], v[54:55]
	v_pk_mul_f32 v[56:57], v[144:145], v[56:57]
	v_pk_add_f32 v[150:151], v[150:151], 1.0 op_sel_hi:[1,0]
	v_pk_add_f32 v[152:153], v[152:153], 1.0 op_sel_hi:[1,0]
	v_pk_fma_f32 v[54:55], v[150:151], v[54:55], v[146:147]
	v_pk_fma_f32 v[56:57], v[152:153], v[56:57], v[148:149]
	s_nop 0
	v_cvt_pk_bf16_f32 v54, v54, v55
	v_cvt_pk_bf16_f32 v55, v56, v57
	global_store_dwordx2 v245, v[54:55], s[16:17] offset:2560
	s_waitcnt lgkmcnt(0)
	v_pk_mul_f32 v[58:59], v[58:59], v[252:253] op_sel_hi:[1,0]
	v_pk_mul_f32 v[60:61], v[60:61], v[252:253] op_sel_hi:[1,0]
	v_pk_mul_f32 v[58:59], v[214:215], v[58:59]
	v_pk_mul_f32 v[60:61], v[216:217], v[60:61]
	v_pk_add_f32 v[222:223], v[222:223], 1.0 op_sel_hi:[1,0]
	v_pk_add_f32 v[224:225], v[224:225], 1.0 op_sel_hi:[1,0]
	v_pk_fma_f32 v[58:59], v[222:223], v[58:59], v[218:219]
	v_pk_fma_f32 v[60:61], v[224:225], v[60:61], v[220:221]
	s_nop 0
	v_cvt_pk_bf16_f32 v58, v58, v59
	v_cvt_pk_bf16_f32 v59, v60, v61
	global_store_dwordx2 v245, v[58:59], s[16:17] offset:3072
	v_pk_mul_f32 v[62:63], v[62:63], v[252:253] op_sel_hi:[1,0]
	v_pk_mul_f32 v[64:65], v[64:65], v[252:253] op_sel_hi:[1,0]
	v_pk_mul_f32 v[62:63], v[226:227], v[62:63]
	v_pk_mul_f32 v[64:65], v[228:229], v[64:65]
	v_pk_add_f32 v[234:235], v[234:235], 1.0 op_sel_hi:[1,0]
	v_pk_add_f32 v[236:237], v[236:237], 1.0 op_sel_hi:[1,0]
	v_pk_fma_f32 v[62:63], v[234:235], v[62:63], v[230:231]
	v_pk_fma_f32 v[64:65], v[236:237], v[64:65], v[232:233]
	s_nop 0
	v_cvt_pk_bf16_f32 v62, v62, v63
	v_cvt_pk_bf16_f32 v63, v64, v65
	global_store_dwordx2 v245, v[62:63], s[16:17] offset:3584
	s_add_u32 s16, s16, 0x1000000
	s_addc_u32 s17, s17, 0
	s_waitcnt vmcnt(16)
	global_load_dwordx4 v[2:5], v238, s[42:43] offset:0 nt
	global_load_dwordx4 v[6:9], v238, s[42:43] offset:1024 nt
	global_load_dwordx4 v[10:13], v238, s[42:43] offset:2048 nt
	global_load_dwordx4 v[14:17], v238, s[42:43] offset:3072 nt
	global_load_dwordx4 v[18:21], v241, s[42:43] offset:0 nt
	global_load_dwordx4 v[22:25], v241, s[42:43] offset:1024 nt
	global_load_dwordx4 v[26:29], v241, s[42:43] offset:2048 nt
	global_load_dwordx4 v[30:33], v241, s[42:43] offset:3072 nt
	global_load_dwordx4 v[34:37], v242, s[42:43] offset:0 nt
	global_load_dwordx4 v[38:41], v242, s[42:43] offset:1024 nt
	global_load_dwordx4 v[42:45], v242, s[42:43] offset:2048 nt
	global_load_dwordx4 v[46:49], v242, s[42:43] offset:3072 nt
	global_load_dwordx4 v[50:53], v243, s[42:43] offset:0 nt
	global_load_dwordx4 v[54:57], v243, s[42:43] offset:1024 nt
	global_load_dwordx4 v[58:61], v243, s[42:43] offset:2048 nt
	global_load_dwordx4 v[62:65], v243, s[42:43] offset:3072 nt
	ds_read_b128 v[130:133], v238 offset:0
	ds_read_b128 v[134:137], v238 offset:16384
	ds_read_b128 v[138:141], v238 offset:32768
	ds_read_b128 v[142:145], v238 offset:1024
	ds_read_b128 v[146:149], v238 offset:17408
	ds_read_b128 v[150:153], v238 offset:33792
	v_pk_mul_f32 v[156:157], v[66:67], v[66:67]
	v_pk_mul_f32 v[158:159], v[68:69], v[68:69]
	v_pk_fma_f32 v[156:157], v[70:71], v[70:71], v[156:157]
	v_pk_fma_f32 v[158:159], v[72:73], v[72:73], v[158:159]
	v_pk_fma_f32 v[156:157], v[74:75], v[74:75], v[156:157]
	v_pk_fma_f32 v[158:159], v[76:77], v[76:77], v[158:159]
	v_pk_fma_f32 v[156:157], v[78:79], v[78:79], v[156:157]
	v_pk_fma_f32 v[158:159], v[80:81], v[80:81], v[158:159]
	v_pk_fma_f32 v[156:157], v[82:83], v[82:83], v[156:157]
	v_pk_fma_f32 v[158:159], v[84:85], v[84:85], v[158:159]
	v_pk_fma_f32 v[156:157], v[86:87], v[86:87], v[156:157]
	v_pk_fma_f32 v[158:159], v[88:89], v[88:89], v[158:159]
	v_pk_fma_f32 v[156:157], v[90:91], v[90:91], v[156:157]
	v_pk_fma_f32 v[158:159], v[92:93], v[92:93], v[158:159]
	v_pk_fma_f32 v[156:157], v[94:95], v[94:95], v[156:157]
	v_pk_fma_f32 v[158:159], v[96:97], v[96:97], v[158:159]
	v_pk_fma_f32 v[156:157], v[98:99], v[98:99], v[156:157]
	v_pk_fma_f32 v[158:159], v[100:101], v[100:101], v[158:159]
	v_pk_fma_f32 v[156:157], v[102:103], v[102:103], v[156:157]
	v_pk_fma_f32 v[158:159], v[104:105], v[104:105], v[158:159]
	v_pk_fma_f32 v[156:157], v[106:107], v[106:107], v[156:157]
	v_pk_fma_f32 v[158:159], v[108:109], v[108:109], v[158:159]
	v_pk_fma_f32 v[156:157], v[110:111], v[110:111], v[156:157]
	v_pk_fma_f32 v[158:159], v[112:113], v[112:113], v[158:159]
	v_pk_fma_f32 v[156:157], v[114:115], v[114:115], v[156:157]
	v_pk_fma_f32 v[158:159], v[116:117], v[116:117], v[158:159]
	v_pk_fma_f32 v[156:157], v[118:119], v[118:119], v[156:157]
	v_pk_fma_f32 v[158:159], v[120:121], v[120:121], v[158:159]
	v_pk_fma_f32 v[156:157], v[122:123], v[122:123], v[156:157]
	v_pk_fma_f32 v[158:159], v[124:125], v[124:125], v[158:159]
	v_pk_fma_f32 v[156:157], v[126:127], v[126:127], v[156:157]
	v_pk_fma_f32 v[158:159], v[128:129], v[128:129], v[158:159]
	v_pk_add_f32 v[156:157], v[156:157], v[158:159]
	s_nop 0
	v_add_f32_e32 v252, v156, v157
	s_waitcnt lgkmcnt(0)
	ds_bpermute_b32 v254, v246, v252
	s_waitcnt lgkmcnt(0)
	v_add_f32_e32 v252, v252, v254
	ds_bpermute_b32 v254, v247, v252
	s_waitcnt lgkmcnt(0)
	v_add_f32_e32 v252, v252, v254
	ds_bpermute_b32 v254, v248, v252
	s_waitcnt lgkmcnt(0)
	v_add_f32_e32 v252, v252, v254
	ds_bpermute_b32 v254, v249, v252
	s_waitcnt lgkmcnt(0)
	v_add_f32_e32 v252, v252, v254
	ds_bpermute_b32 v254, v250, v252
	s_waitcnt lgkmcnt(0)
	v_add_f32_e32 v252, v252, v254
	ds_bpermute_b32 v254, v251, v252
	s_waitcnt lgkmcnt(0)
	v_add_f32_e32 v252, v252, v254
	v_mov_b32_e32 v254, 0x358637bd
	v_fmac_f32_e32 v254, 0x39800000, v252
	v_mul_f32_e32 v252, 0x4b800000, v254
	v_cmp_gt_f32_e32 vcc, s20, v254
	s_nop 1
	v_cndmask_b32_e32 v254, v254, v252, vcc
	v_rsq_f32_e32 v254, v254
	s_nop 0
	v_mul_f32_e32 v252, 0x45800000, v254
	v_cndmask_b32_e32 v252, v254, v252, vcc
	ds_read_b128 v[214:217], v238 offset:2048
	ds_read_b128 v[218:221], v238 offset:18432
	ds_read_b128 v[222:225], v238 offset:34816
	ds_read_b128 v[226:229], v238 offset:3072
	ds_read_b128 v[230:233], v238 offset:19456
	ds_read_b128 v[234:237], v238 offset:35840
	s_waitcnt lgkmcnt(6)
	v_pk_mul_f32 v[66:67], v[66:67], v[252:253] op_sel_hi:[1,0]
	v_pk_mul_f32 v[68:69], v[68:69], v[252:253] op_sel_hi:[1,0]
	v_pk_mul_f32 v[66:67], v[130:131], v[66:67]
	v_pk_mul_f32 v[68:69], v[132:133], v[68:69]
	v_pk_add_f32 v[138:139], v[138:139], 1.0 op_sel_hi:[1,0]
	v_pk_add_f32 v[140:141], v[140:141], 1.0 op_sel_hi:[1,0]
	v_pk_fma_f32 v[66:67], v[138:139], v[66:67], v[134:135]
	v_pk_fma_f32 v[68:69], v[140:141], v[68:69], v[136:137]
	s_nop 0
	v_cvt_pk_bf16_f32 v66, v66, v67
	v_cvt_pk_bf16_f32 v67, v68, v69
	global_store_dwordx2 v244, v[66:67], s[16:17] offset:0
	v_pk_mul_f32 v[70:71], v[70:71], v[252:253] op_sel_hi:[1,0]
	v_pk_mul_f32 v[72:73], v[72:73], v[252:253] op_sel_hi:[1,0]
	v_pk_mul_f32 v[70:71], v[142:143], v[70:71]
	v_pk_mul_f32 v[72:73], v[144:145], v[72:73]
	v_pk_add_f32 v[150:151], v[150:151], 1.0 op_sel_hi:[1,0]
	v_pk_add_f32 v[152:153], v[152:153], 1.0 op_sel_hi:[1,0]
	v_pk_fma_f32 v[70:71], v[150:151], v[70:71], v[146:147]
	v_pk_fma_f32 v[72:73], v[152:153], v[72:73], v[148:149]
	s_nop 0
	v_cvt_pk_bf16_f32 v70, v70, v71
	v_cvt_pk_bf16_f32 v71, v72, v73
	global_store_dwordx2 v244, v[70:71], s[16:17] offset:512
	ds_read_b128 v[130:133], v238 offset:4096
	ds_read_b128 v[134:137], v238 offset:20480
	ds_read_b128 v[138:141], v238 offset:36864
	ds_read_b128 v[142:145], v238 offset:5120
	ds_read_b128 v[146:149], v238 offset:21504
	ds_read_b128 v[150:153], v238 offset:37888
	s_waitcnt lgkmcnt(6)
	v_pk_mul_f32 v[74:75], v[74:75], v[252:253] op_sel_hi:[1,0]
	v_pk_mul_f32 v[76:77], v[76:77], v[252:253] op_sel_hi:[1,0]
	v_pk_mul_f32 v[74:75], v[214:215], v[74:75]
	v_pk_mul_f32 v[76:77], v[216:217], v[76:77]
	v_pk_add_f32 v[222:223], v[222:223], 1.0 op_sel_hi:[1,0]
	v_pk_add_f32 v[224:225], v[224:225], 1.0 op_sel_hi:[1,0]
	v_pk_fma_f32 v[74:75], v[222:223], v[74:75], v[218:219]
	v_pk_fma_f32 v[76:77], v[224:225], v[76:77], v[220:221]
	s_nop 0
	v_cvt_pk_bf16_f32 v74, v74, v75
	v_cvt_pk_bf16_f32 v75, v76, v77
	global_store_dwordx2 v244, v[74:75], s[16:17] offset:1024
	v_pk_mul_f32 v[78:79], v[78:79], v[252:253] op_sel_hi:[1,0]
	v_pk_mul_f32 v[80:81], v[80:81], v[252:253] op_sel_hi:[1,0]
	v_pk_mul_f32 v[78:79], v[226:227], v[78:79]
	v_pk_mul_f32 v[80:81], v[228:229], v[80:81]
	v_pk_add_f32 v[234:235], v[234:235], 1.0 op_sel_hi:[1,0]
	v_pk_add_f32 v[236:237], v[236:237], 1.0 op_sel_hi:[1,0]
	v_pk_fma_f32 v[78:79], v[234:235], v[78:79], v[230:231]
	v_pk_fma_f32 v[80:81], v[236:237], v[80:81], v[232:233]
	s_nop 0
	v_cvt_pk_bf16_f32 v78, v78, v79
	v_cvt_pk_bf16_f32 v79, v80, v81
	global_store_dwordx2 v244, v[78:79], s[16:17] offset:1536
	ds_read_b128 v[214:217], v238 offset:6144
	ds_read_b128 v[218:221], v238 offset:22528
	ds_read_b128 v[222:225], v238 offset:38912
	ds_read_b128 v[226:229], v238 offset:7168
	ds_read_b128 v[230:233], v238 offset:23552
	ds_read_b128 v[234:237], v238 offset:39936
	s_waitcnt lgkmcnt(6)
	v_pk_mul_f32 v[82:83], v[82:83], v[252:253] op_sel_hi:[1,0]
	v_pk_mul_f32 v[84:85], v[84:85], v[252:253] op_sel_hi:[1,0]
	v_pk_mul_f32 v[82:83], v[130:131], v[82:83]
	v_pk_mul_f32 v[84:85], v[132:133], v[84:85]
	v_pk_add_f32 v[138:139], v[138:139], 1.0 op_sel_hi:[1,0]
	v_pk_add_f32 v[140:141], v[140:141], 1.0 op_sel_hi:[1,0]
	v_pk_fma_f32 v[82:83], v[138:139], v[82:83], v[134:135]
	v_pk_fma_f32 v[84:85], v[140:141], v[84:85], v[136:137]
	s_nop 0
	v_cvt_pk_bf16_f32 v82, v82, v83
	v_cvt_pk_bf16_f32 v83, v84, v85
	global_store_dwordx2 v244, v[82:83], s[16:17] offset:2048
	v_pk_mul_f32 v[86:87], v[86:87], v[252:253] op_sel_hi:[1,0]
	v_pk_mul_f32 v[88:89], v[88:89], v[252:253] op_sel_hi:[1,0]
	v_pk_mul_f32 v[86:87], v[142:143], v[86:87]
	v_pk_mul_f32 v[88:89], v[144:145], v[88:89]
	v_pk_add_f32 v[150:151], v[150:151], 1.0 op_sel_hi:[1,0]
	v_pk_add_f32 v[152:153], v[152:153], 1.0 op_sel_hi:[1,0]
	v_pk_fma_f32 v[86:87], v[150:151], v[86:87], v[146:147]
	v_pk_fma_f32 v[88:89], v[152:153], v[88:89], v[148:149]
	s_nop 0
	v_cvt_pk_bf16_f32 v86, v86, v87
	v_cvt_pk_bf16_f32 v87, v88, v89
	global_store_dwordx2 v244, v[86:87], s[16:17] offset:2560
	ds_read_b128 v[130:133], v238 offset:8192
	ds_read_b128 v[134:137], v238 offset:24576
	ds_read_b128 v[138:141], v238 offset:40960
	ds_read_b128 v[142:145], v238 offset:9216
	ds_read_b128 v[146:149], v238 offset:25600
	ds_read_b128 v[150:153], v238 offset:41984
	s_waitcnt lgkmcnt(6)
	v_pk_mul_f32 v[90:91], v[90:91], v[252:253] op_sel_hi:[1,0]
	v_pk_mul_f32 v[92:93], v[92:93], v[252:253] op_sel_hi:[1,0]
	v_pk_mul_f32 v[90:91], v[214:215], v[90:91]
	v_pk_mul_f32 v[92:93], v[216:217], v[92:93]
	v_pk_add_f32 v[222:223], v[222:223], 1.0 op_sel_hi:[1,0]
	v_pk_add_f32 v[224:225], v[224:225], 1.0 op_sel_hi:[1,0]
	v_pk_fma_f32 v[90:91], v[222:223], v[90:91], v[218:219]
	v_pk_fma_f32 v[92:93], v[224:225], v[92:93], v[220:221]
	s_nop 0
	v_cvt_pk_bf16_f32 v90, v90, v91
	v_cvt_pk_bf16_f32 v91, v92, v93
	global_store_dwordx2 v244, v[90:91], s[16:17] offset:3072
	v_pk_mul_f32 v[94:95], v[94:95], v[252:253] op_sel_hi:[1,0]
	v_pk_mul_f32 v[96:97], v[96:97], v[252:253] op_sel_hi:[1,0]
	v_pk_mul_f32 v[94:95], v[226:227], v[94:95]
	v_pk_mul_f32 v[96:97], v[228:229], v[96:97]
	v_pk_add_f32 v[234:235], v[234:235], 1.0 op_sel_hi:[1,0]
	v_pk_add_f32 v[236:237], v[236:237], 1.0 op_sel_hi:[1,0]
	v_pk_fma_f32 v[94:95], v[234:235], v[94:95], v[230:231]
	v_pk_fma_f32 v[96:97], v[236:237], v[96:97], v[232:233]
	s_nop 0
	v_cvt_pk_bf16_f32 v94, v94, v95
	v_cvt_pk_bf16_f32 v95, v96, v97
	global_store_dwordx2 v244, v[94:95], s[16:17] offset:3584
	ds_read_b128 v[214:217], v238 offset:10240
	ds_read_b128 v[218:221], v238 offset:26624
	ds_read_b128 v[222:225], v238 offset:43008
	ds_read_b128 v[226:229], v238 offset:11264
	ds_read_b128 v[230:233], v238 offset:27648
	ds_read_b128 v[234:237], v238 offset:44032
	s_waitcnt lgkmcnt(6)
	v_pk_mul_f32 v[98:99], v[98:99], v[252:253] op_sel_hi:[1,0]
	v_pk_mul_f32 v[100:101], v[100:101], v[252:253] op_sel_hi:[1,0]
	v_pk_mul_f32 v[98:99], v[130:131], v[98:99]
	v_pk_mul_f32 v[100:101], v[132:133], v[100:101]
	v_pk_add_f32 v[138:139], v[138:139], 1.0 op_sel_hi:[1,0]
	v_pk_add_f32 v[140:141], v[140:141], 1.0 op_sel_hi:[1,0]
	v_pk_fma_f32 v[98:99], v[138:139], v[98:99], v[134:135]
	v_pk_fma_f32 v[100:101], v[140:141], v[100:101], v[136:137]
	s_nop 0
	v_cvt_pk_bf16_f32 v98, v98, v99
	v_cvt_pk_bf16_f32 v99, v100, v101
	global_store_dwordx2 v245, v[98:99], s[16:17] offset:0
	v_pk_mul_f32 v[102:103], v[102:103], v[252:253] op_sel_hi:[1,0]
	v_pk_mul_f32 v[104:105], v[104:105], v[252:253] op_sel_hi:[1,0]
	v_pk_mul_f32 v[102:103], v[142:143], v[102:103]
	v_pk_mul_f32 v[104:105], v[144:145], v[104:105]
	v_pk_add_f32 v[150:151], v[150:151], 1.0 op_sel_hi:[1,0]
	v_pk_add_f32 v[152:153], v[152:153], 1.0 op_sel_hi:[1,0]
	v_pk_fma_f32 v[102:103], v[150:151], v[102:103], v[146:147]
	v_pk_fma_f32 v[104:105], v[152:153], v[104:105], v[148:149]
	s_nop 0
	v_cvt_pk_bf16_f32 v102, v102, v103
	v_cvt_pk_bf16_f32 v103, v104, v105
	global_store_dwordx2 v245, v[102:103], s[16:17] offset:512
	ds_read_b128 v[130:133], v238 offset:12288
	ds_read_b128 v[134:137], v238 offset:28672
	ds_read_b128 v[138:141], v238 offset:45056
	ds_read_b128 v[142:145], v238 offset:13312
	ds_read_b128 v[146:149], v238 offset:29696
	ds_read_b128 v[150:153], v238 offset:46080
	s_waitcnt lgkmcnt(6)
	v_pk_mul_f32 v[106:107], v[106:107], v[252:253] op_sel_hi:[1,0]
	v_pk_mul_f32 v[108:109], v[108:109], v[252:253] op_sel_hi:[1,0]
	v_pk_mul_f32 v[106:107], v[214:215], v[106:107]
	v_pk_mul_f32 v[108:109], v[216:217], v[108:109]
	v_pk_add_f32 v[222:223], v[222:223], 1.0 op_sel_hi:[1,0]
	v_pk_add_f32 v[224:225], v[224:225], 1.0 op_sel_hi:[1,0]
	v_pk_fma_f32 v[106:107], v[222:223], v[106:107], v[218:219]
	v_pk_fma_f32 v[108:109], v[224:225], v[108:109], v[220:221]
	s_nop 0
	v_cvt_pk_bf16_f32 v106, v106, v107
	v_cvt_pk_bf16_f32 v107, v108, v109
	global_store_dwordx2 v245, v[106:107], s[16:17] offset:1024
	v_pk_mul_f32 v[110:111], v[110:111], v[252:253] op_sel_hi:[1,0]
	v_pk_mul_f32 v[112:113], v[112:113], v[252:253] op_sel_hi:[1,0]
	v_pk_mul_f32 v[110:111], v[226:227], v[110:111]
	v_pk_mul_f32 v[112:113], v[228:229], v[112:113]
	v_pk_add_f32 v[234:235], v[234:235], 1.0 op_sel_hi:[1,0]
	v_pk_add_f32 v[236:237], v[236:237], 1.0 op_sel_hi:[1,0]
	v_pk_fma_f32 v[110:111], v[234:235], v[110:111], v[230:231]
	v_pk_fma_f32 v[112:113], v[236:237], v[112:113], v[232:233]
	s_nop 0
	v_cvt_pk_bf16_f32 v110, v110, v111
	v_cvt_pk_bf16_f32 v111, v112, v113
	global_store_dwordx2 v245, v[110:111], s[16:17] offset:1536
	ds_read_b128 v[214:217], v238 offset:14336
	ds_read_b128 v[218:221], v238 offset:30720
	ds_read_b128 v[222:225], v238 offset:47104
	ds_read_b128 v[226:229], v238 offset:15360
	ds_read_b128 v[230:233], v238 offset:31744
	ds_read_b128 v[234:237], v238 offset:48128
	s_waitcnt lgkmcnt(6)
	v_pk_mul_f32 v[114:115], v[114:115], v[252:253] op_sel_hi:[1,0]
	v_pk_mul_f32 v[116:117], v[116:117], v[252:253] op_sel_hi:[1,0]
	v_pk_mul_f32 v[114:115], v[130:131], v[114:115]
	v_pk_mul_f32 v[116:117], v[132:133], v[116:117]
	v_pk_add_f32 v[138:139], v[138:139], 1.0 op_sel_hi:[1,0]
	v_pk_add_f32 v[140:141], v[140:141], 1.0 op_sel_hi:[1,0]
	v_pk_fma_f32 v[114:115], v[138:139], v[114:115], v[134:135]
	v_pk_fma_f32 v[116:117], v[140:141], v[116:117], v[136:137]
	s_nop 0
	v_cvt_pk_bf16_f32 v114, v114, v115
	v_cvt_pk_bf16_f32 v115, v116, v117
	global_store_dwordx2 v245, v[114:115], s[16:17] offset:2048
	v_pk_mul_f32 v[118:119], v[118:119], v[252:253] op_sel_hi:[1,0]
	v_pk_mul_f32 v[120:121], v[120:121], v[252:253] op_sel_hi:[1,0]
	v_pk_mul_f32 v[118:119], v[142:143], v[118:119]
	v_pk_mul_f32 v[120:121], v[144:145], v[120:121]
	v_pk_add_f32 v[150:151], v[150:151], 1.0 op_sel_hi:[1,0]
	v_pk_add_f32 v[152:153], v[152:153], 1.0 op_sel_hi:[1,0]
	v_pk_fma_f32 v[118:119], v[150:151], v[118:119], v[146:147]
	v_pk_fma_f32 v[120:121], v[152:153], v[120:121], v[148:149]
	s_nop 0
	v_cvt_pk_bf16_f32 v118, v118, v119
	v_cvt_pk_bf16_f32 v119, v120, v121
	global_store_dwordx2 v245, v[118:119], s[16:17] offset:2560
	s_waitcnt lgkmcnt(0)
	v_pk_mul_f32 v[122:123], v[122:123], v[252:253] op_sel_hi:[1,0]
	v_pk_mul_f32 v[124:125], v[124:125], v[252:253] op_sel_hi:[1,0]
	v_pk_mul_f32 v[122:123], v[214:215], v[122:123]
	v_pk_mul_f32 v[124:125], v[216:217], v[124:125]
	v_pk_add_f32 v[222:223], v[222:223], 1.0 op_sel_hi:[1,0]
	v_pk_add_f32 v[224:225], v[224:225], 1.0 op_sel_hi:[1,0]
	v_pk_fma_f32 v[122:123], v[222:223], v[122:123], v[218:219]
	v_pk_fma_f32 v[124:125], v[224:225], v[124:125], v[220:221]
	s_nop 0
	v_cvt_pk_bf16_f32 v122, v122, v123
	v_cvt_pk_bf16_f32 v123, v124, v125
	global_store_dwordx2 v245, v[122:123], s[16:17] offset:3072
	v_pk_mul_f32 v[126:127], v[126:127], v[252:253] op_sel_hi:[1,0]
	v_pk_mul_f32 v[128:129], v[128:129], v[252:253] op_sel_hi:[1,0]
	v_pk_mul_f32 v[126:127], v[226:227], v[126:127]
	v_pk_mul_f32 v[128:129], v[228:229], v[128:129]
	v_pk_add_f32 v[234:235], v[234:235], 1.0 op_sel_hi:[1,0]
	v_pk_add_f32 v[236:237], v[236:237], 1.0 op_sel_hi:[1,0]
	v_pk_fma_f32 v[126:127], v[234:235], v[126:127], v[230:231]
	v_pk_fma_f32 v[128:129], v[236:237], v[128:129], v[232:233]
	s_nop 0
	v_cvt_pk_bf16_f32 v126, v126, v127
	v_cvt_pk_bf16_f32 v127, v128, v129
	global_store_dwordx2 v245, v[126:127], s[16:17] offset:3584
	s_add_u32 s16, s16, 0x1000000
	s_addc_u32 s17, s17, 0
	s_waitcnt vmcnt(16)
	s_add_u32 s42, s42, 0x2000000
	s_addc_u32 s43, s43, 0
	global_load_dwordx4 v[66:69], v238, s[42:43] offset:0 nt
	global_load_dwordx4 v[70:73], v238, s[42:43] offset:1024 nt
	global_load_dwordx4 v[74:77], v238, s[42:43] offset:2048 nt
	global_load_dwordx4 v[78:81], v238, s[42:43] offset:3072 nt
	global_load_dwordx4 v[82:85], v241, s[42:43] offset:0 nt
	global_load_dwordx4 v[86:89], v241, s[42:43] offset:1024 nt
	global_load_dwordx4 v[90:93], v241, s[42:43] offset:2048 nt
	global_load_dwordx4 v[94:97], v241, s[42:43] offset:3072 nt
	global_load_dwordx4 v[98:101], v242, s[42:43] offset:0 nt
	global_load_dwordx4 v[102:105], v242, s[42:43] offset:1024 nt
	global_load_dwordx4 v[106:109], v242, s[42:43] offset:2048 nt
	global_load_dwordx4 v[110:113], v242, s[42:43] offset:3072 nt
	global_load_dwordx4 v[114:117], v243, s[42:43] offset:0 nt
	global_load_dwordx4 v[118:121], v243, s[42:43] offset:1024 nt
	global_load_dwordx4 v[122:125], v243, s[42:43] offset:2048 nt
	global_load_dwordx4 v[126:129], v243, s[42:43] offset:3072 nt
	ds_read_b128 v[130:133], v238 offset:0
	ds_read_b128 v[134:137], v238 offset:49152
	ds_read_b128 v[138:141], v239 offset:0
	ds_read_b128 v[142:145], v238 offset:1024
	ds_read_b128 v[146:149], v238 offset:50176
	ds_read_b128 v[150:153], v239 offset:1024
	v_pk_mul_f32 v[156:157], v[2:3], v[2:3]
	v_pk_mul_f32 v[158:159], v[4:5], v[4:5]
	v_pk_fma_f32 v[156:157], v[6:7], v[6:7], v[156:157]
	v_pk_fma_f32 v[158:159], v[8:9], v[8:9], v[158:159]
	v_pk_fma_f32 v[156:157], v[10:11], v[10:11], v[156:157]
	v_pk_fma_f32 v[158:159], v[12:13], v[12:13], v[158:159]
	v_pk_fma_f32 v[156:157], v[14:15], v[14:15], v[156:157]
	v_pk_fma_f32 v[158:159], v[16:17], v[16:17], v[158:159]
	v_pk_fma_f32 v[156:157], v[18:19], v[18:19], v[156:157]
	v_pk_fma_f32 v[158:159], v[20:21], v[20:21], v[158:159]
	v_pk_fma_f32 v[156:157], v[22:23], v[22:23], v[156:157]
	v_pk_fma_f32 v[158:159], v[24:25], v[24:25], v[158:159]
	v_pk_fma_f32 v[156:157], v[26:27], v[26:27], v[156:157]
	v_pk_fma_f32 v[158:159], v[28:29], v[28:29], v[158:159]
	v_pk_fma_f32 v[156:157], v[30:31], v[30:31], v[156:157]
	v_pk_fma_f32 v[158:159], v[32:33], v[32:33], v[158:159]
	v_pk_fma_f32 v[156:157], v[34:35], v[34:35], v[156:157]
	v_pk_fma_f32 v[158:159], v[36:37], v[36:37], v[158:159]
	v_pk_fma_f32 v[156:157], v[38:39], v[38:39], v[156:157]
	v_pk_fma_f32 v[158:159], v[40:41], v[40:41], v[158:159]
	v_pk_fma_f32 v[156:157], v[42:43], v[42:43], v[156:157]
	v_pk_fma_f32 v[158:159], v[44:45], v[44:45], v[158:159]
	v_pk_fma_f32 v[156:157], v[46:47], v[46:47], v[156:157]
	v_pk_fma_f32 v[158:159], v[48:49], v[48:49], v[158:159]
	v_pk_fma_f32 v[156:157], v[50:51], v[50:51], v[156:157]
	v_pk_fma_f32 v[158:159], v[52:53], v[52:53], v[158:159]
	v_pk_fma_f32 v[156:157], v[54:55], v[54:55], v[156:157]
	v_pk_fma_f32 v[158:159], v[56:57], v[56:57], v[158:159]
	v_pk_fma_f32 v[156:157], v[58:59], v[58:59], v[156:157]
	v_pk_fma_f32 v[158:159], v[60:61], v[60:61], v[158:159]
	v_pk_fma_f32 v[156:157], v[62:63], v[62:63], v[156:157]
	v_pk_fma_f32 v[158:159], v[64:65], v[64:65], v[158:159]
	v_pk_add_f32 v[156:157], v[156:157], v[158:159]
	s_nop 0
	v_add_f32_e32 v252, v156, v157
	s_waitcnt lgkmcnt(0)
	ds_bpermute_b32 v254, v246, v252
	s_waitcnt lgkmcnt(0)
	v_add_f32_e32 v252, v252, v254
	ds_bpermute_b32 v254, v247, v252
	s_waitcnt lgkmcnt(0)
	v_add_f32_e32 v252, v252, v254
	ds_bpermute_b32 v254, v248, v252
	s_waitcnt lgkmcnt(0)
	v_add_f32_e32 v252, v252, v254
	ds_bpermute_b32 v254, v249, v252
	s_waitcnt lgkmcnt(0)
	v_add_f32_e32 v252, v252, v254
	ds_bpermute_b32 v254, v250, v252
	s_waitcnt lgkmcnt(0)
	v_add_f32_e32 v252, v252, v254
	ds_bpermute_b32 v254, v251, v252
	s_waitcnt lgkmcnt(0)
	v_add_f32_e32 v252, v252, v254
	v_mov_b32_e32 v254, 0x358637bd
	v_fmac_f32_e32 v254, 0x39800000, v252
	v_mul_f32_e32 v252, 0x4b800000, v254
	v_cmp_gt_f32_e32 vcc, s20, v254
	s_nop 1
	v_cndmask_b32_e32 v254, v254, v252, vcc
	v_rsq_f32_e32 v254, v254
	s_nop 0
	v_mul_f32_e32 v252, 0x45800000, v254
	v_cndmask_b32_e32 v252, v254, v252, vcc
	ds_read_b128 v[214:217], v238 offset:2048
	ds_read_b128 v[218:221], v238 offset:51200
	ds_read_b128 v[222:225], v239 offset:2048
	ds_read_b128 v[226:229], v238 offset:3072
	ds_read_b128 v[230:233], v238 offset:52224
	ds_read_b128 v[234:237], v239 offset:3072
	s_waitcnt lgkmcnt(6)
	v_pk_mul_f32 v[2:3], v[2:3], v[252:253] op_sel_hi:[1,0]
	v_pk_mul_f32 v[4:5], v[4:5], v[252:253] op_sel_hi:[1,0]
	v_pk_mul_f32 v[2:3], v[130:131], v[2:3]
	v_pk_mul_f32 v[4:5], v[132:133], v[4:5]
	v_pk_add_f32 v[138:139], v[138:139], 1.0 op_sel_hi:[1,0]
	v_pk_add_f32 v[140:141], v[140:141], 1.0 op_sel_hi:[1,0]
	v_pk_fma_f32 v[2:3], v[138:139], v[2:3], v[134:135]
	v_pk_fma_f32 v[4:5], v[140:141], v[4:5], v[136:137]
	s_nop 0
	v_cvt_pk_bf16_f32 v2, v2, v3
	v_cvt_pk_bf16_f32 v3, v4, v5
	global_store_dwordx2 v244, v[2:3], s[16:17] offset:0
	v_pk_mul_f32 v[6:7], v[6:7], v[252:253] op_sel_hi:[1,0]
	v_pk_mul_f32 v[8:9], v[8:9], v[252:253] op_sel_hi:[1,0]
	v_pk_mul_f32 v[6:7], v[142:143], v[6:7]
	v_pk_mul_f32 v[8:9], v[144:145], v[8:9]
	v_pk_add_f32 v[150:151], v[150:151], 1.0 op_sel_hi:[1,0]
	v_pk_add_f32 v[152:153], v[152:153], 1.0 op_sel_hi:[1,0]
	v_pk_fma_f32 v[6:7], v[150:151], v[6:7], v[146:147]
	v_pk_fma_f32 v[8:9], v[152:153], v[8:9], v[148:149]
	s_nop 0
	v_cvt_pk_bf16_f32 v6, v6, v7
	v_cvt_pk_bf16_f32 v7, v8, v9
	global_store_dwordx2 v244, v[6:7], s[16:17] offset:512
	ds_read_b128 v[130:133], v238 offset:4096
	ds_read_b128 v[134:137], v238 offset:53248
	ds_read_b128 v[138:141], v239 offset:4096
	ds_read_b128 v[142:145], v238 offset:5120
	ds_read_b128 v[146:149], v238 offset:54272
	ds_read_b128 v[150:153], v239 offset:5120
	s_waitcnt lgkmcnt(6)
	v_pk_mul_f32 v[10:11], v[10:11], v[252:253] op_sel_hi:[1,0]
	v_pk_mul_f32 v[12:13], v[12:13], v[252:253] op_sel_hi:[1,0]
	v_pk_mul_f32 v[10:11], v[214:215], v[10:11]
	v_pk_mul_f32 v[12:13], v[216:217], v[12:13]
	v_pk_add_f32 v[222:223], v[222:223], 1.0 op_sel_hi:[1,0]
	v_pk_add_f32 v[224:225], v[224:225], 1.0 op_sel_hi:[1,0]
	v_pk_fma_f32 v[10:11], v[222:223], v[10:11], v[218:219]
	v_pk_fma_f32 v[12:13], v[224:225], v[12:13], v[220:221]
	s_nop 0
	v_cvt_pk_bf16_f32 v10, v10, v11
	v_cvt_pk_bf16_f32 v11, v12, v13
	global_store_dwordx2 v244, v[10:11], s[16:17] offset:1024
	v_pk_mul_f32 v[14:15], v[14:15], v[252:253] op_sel_hi:[1,0]
	v_pk_mul_f32 v[16:17], v[16:17], v[252:253] op_sel_hi:[1,0]
	v_pk_mul_f32 v[14:15], v[226:227], v[14:15]
	v_pk_mul_f32 v[16:17], v[228:229], v[16:17]
	v_pk_add_f32 v[234:235], v[234:235], 1.0 op_sel_hi:[1,0]
	v_pk_add_f32 v[236:237], v[236:237], 1.0 op_sel_hi:[1,0]
	v_pk_fma_f32 v[14:15], v[234:235], v[14:15], v[230:231]
	v_pk_fma_f32 v[16:17], v[236:237], v[16:17], v[232:233]
	s_nop 0
	v_cvt_pk_bf16_f32 v14, v14, v15
	v_cvt_pk_bf16_f32 v15, v16, v17
	global_store_dwordx2 v244, v[14:15], s[16:17] offset:1536
	ds_read_b128 v[214:217], v238 offset:6144
	ds_read_b128 v[218:221], v238 offset:55296
	ds_read_b128 v[222:225], v239 offset:6144
	ds_read_b128 v[226:229], v238 offset:7168
	ds_read_b128 v[230:233], v238 offset:56320
	ds_read_b128 v[234:237], v239 offset:7168
	s_waitcnt lgkmcnt(6)
	v_pk_mul_f32 v[18:19], v[18:19], v[252:253] op_sel_hi:[1,0]
	v_pk_mul_f32 v[20:21], v[20:21], v[252:253] op_sel_hi:[1,0]
	v_pk_mul_f32 v[18:19], v[130:131], v[18:19]
	v_pk_mul_f32 v[20:21], v[132:133], v[20:21]
	v_pk_add_f32 v[138:139], v[138:139], 1.0 op_sel_hi:[1,0]
	v_pk_add_f32 v[140:141], v[140:141], 1.0 op_sel_hi:[1,0]
	v_pk_fma_f32 v[18:19], v[138:139], v[18:19], v[134:135]
	v_pk_fma_f32 v[20:21], v[140:141], v[20:21], v[136:137]
	s_nop 0
	v_cvt_pk_bf16_f32 v18, v18, v19
	v_cvt_pk_bf16_f32 v19, v20, v21
	global_store_dwordx2 v244, v[18:19], s[16:17] offset:2048
	v_pk_mul_f32 v[22:23], v[22:23], v[252:253] op_sel_hi:[1,0]
	v_pk_mul_f32 v[24:25], v[24:25], v[252:253] op_sel_hi:[1,0]
	v_pk_mul_f32 v[22:23], v[142:143], v[22:23]
	v_pk_mul_f32 v[24:25], v[144:145], v[24:25]
	v_pk_add_f32 v[150:151], v[150:151], 1.0 op_sel_hi:[1,0]
	v_pk_add_f32 v[152:153], v[152:153], 1.0 op_sel_hi:[1,0]
	v_pk_fma_f32 v[22:23], v[150:151], v[22:23], v[146:147]
	v_pk_fma_f32 v[24:25], v[152:153], v[24:25], v[148:149]
	s_nop 0
	v_cvt_pk_bf16_f32 v22, v22, v23
	v_cvt_pk_bf16_f32 v23, v24, v25
	global_store_dwordx2 v244, v[22:23], s[16:17] offset:2560
	ds_read_b128 v[130:133], v238 offset:8192
	ds_read_b128 v[134:137], v238 offset:57344
	ds_read_b128 v[138:141], v239 offset:8192
	ds_read_b128 v[142:145], v238 offset:9216
	ds_read_b128 v[146:149], v238 offset:58368
	ds_read_b128 v[150:153], v239 offset:9216
	s_waitcnt lgkmcnt(6)
	v_pk_mul_f32 v[26:27], v[26:27], v[252:253] op_sel_hi:[1,0]
	v_pk_mul_f32 v[28:29], v[28:29], v[252:253] op_sel_hi:[1,0]
	v_pk_mul_f32 v[26:27], v[214:215], v[26:27]
	v_pk_mul_f32 v[28:29], v[216:217], v[28:29]
	v_pk_add_f32 v[222:223], v[222:223], 1.0 op_sel_hi:[1,0]
	v_pk_add_f32 v[224:225], v[224:225], 1.0 op_sel_hi:[1,0]
	v_pk_fma_f32 v[26:27], v[222:223], v[26:27], v[218:219]
	v_pk_fma_f32 v[28:29], v[224:225], v[28:29], v[220:221]
	s_nop 0
	v_cvt_pk_bf16_f32 v26, v26, v27
	v_cvt_pk_bf16_f32 v27, v28, v29
	global_store_dwordx2 v244, v[26:27], s[16:17] offset:3072
	v_pk_mul_f32 v[30:31], v[30:31], v[252:253] op_sel_hi:[1,0]
	v_pk_mul_f32 v[32:33], v[32:33], v[252:253] op_sel_hi:[1,0]
	v_pk_mul_f32 v[30:31], v[226:227], v[30:31]
	v_pk_mul_f32 v[32:33], v[228:229], v[32:33]
	v_pk_add_f32 v[234:235], v[234:235], 1.0 op_sel_hi:[1,0]
	v_pk_add_f32 v[236:237], v[236:237], 1.0 op_sel_hi:[1,0]
	v_pk_fma_f32 v[30:31], v[234:235], v[30:31], v[230:231]
	v_pk_fma_f32 v[32:33], v[236:237], v[32:33], v[232:233]
	s_nop 0
	v_cvt_pk_bf16_f32 v30, v30, v31
	v_cvt_pk_bf16_f32 v31, v32, v33
	global_store_dwordx2 v244, v[30:31], s[16:17] offset:3584
	ds_read_b128 v[214:217], v238 offset:10240
	ds_read_b128 v[218:221], v238 offset:59392
	ds_read_b128 v[222:225], v239 offset:10240
	ds_read_b128 v[226:229], v238 offset:11264
	ds_read_b128 v[230:233], v238 offset:60416
	ds_read_b128 v[234:237], v239 offset:11264
	s_waitcnt lgkmcnt(6)
	v_pk_mul_f32 v[34:35], v[34:35], v[252:253] op_sel_hi:[1,0]
	v_pk_mul_f32 v[36:37], v[36:37], v[252:253] op_sel_hi:[1,0]
	v_pk_mul_f32 v[34:35], v[130:131], v[34:35]
	v_pk_mul_f32 v[36:37], v[132:133], v[36:37]
	v_pk_add_f32 v[138:139], v[138:139], 1.0 op_sel_hi:[1,0]
	v_pk_add_f32 v[140:141], v[140:141], 1.0 op_sel_hi:[1,0]
	v_pk_fma_f32 v[34:35], v[138:139], v[34:35], v[134:135]
	v_pk_fma_f32 v[36:37], v[140:141], v[36:37], v[136:137]
	s_nop 0
	v_cvt_pk_bf16_f32 v34, v34, v35
	v_cvt_pk_bf16_f32 v35, v36, v37
	global_store_dwordx2 v245, v[34:35], s[16:17] offset:0
	v_pk_mul_f32 v[38:39], v[38:39], v[252:253] op_sel_hi:[1,0]
	v_pk_mul_f32 v[40:41], v[40:41], v[252:253] op_sel_hi:[1,0]
	v_pk_mul_f32 v[38:39], v[142:143], v[38:39]
	v_pk_mul_f32 v[40:41], v[144:145], v[40:41]
	v_pk_add_f32 v[150:151], v[150:151], 1.0 op_sel_hi:[1,0]
	v_pk_add_f32 v[152:153], v[152:153], 1.0 op_sel_hi:[1,0]
	v_pk_fma_f32 v[38:39], v[150:151], v[38:39], v[146:147]
	v_pk_fma_f32 v[40:41], v[152:153], v[40:41], v[148:149]
	s_nop 0
	v_cvt_pk_bf16_f32 v38, v38, v39
	v_cvt_pk_bf16_f32 v39, v40, v41
	global_store_dwordx2 v245, v[38:39], s[16:17] offset:512
	ds_read_b128 v[130:133], v238 offset:12288
	ds_read_b128 v[134:137], v238 offset:61440
	ds_read_b128 v[138:141], v239 offset:12288
	ds_read_b128 v[142:145], v238 offset:13312
	ds_read_b128 v[146:149], v238 offset:62464
	ds_read_b128 v[150:153], v239 offset:13312
	s_waitcnt lgkmcnt(6)
	v_pk_mul_f32 v[42:43], v[42:43], v[252:253] op_sel_hi:[1,0]
	v_pk_mul_f32 v[44:45], v[44:45], v[252:253] op_sel_hi:[1,0]
	v_pk_mul_f32 v[42:43], v[214:215], v[42:43]
	v_pk_mul_f32 v[44:45], v[216:217], v[44:45]
	v_pk_add_f32 v[222:223], v[222:223], 1.0 op_sel_hi:[1,0]
	v_pk_add_f32 v[224:225], v[224:225], 1.0 op_sel_hi:[1,0]
	v_pk_fma_f32 v[42:43], v[222:223], v[42:43], v[218:219]
	v_pk_fma_f32 v[44:45], v[224:225], v[44:45], v[220:221]
	s_nop 0
	v_cvt_pk_bf16_f32 v42, v42, v43
	v_cvt_pk_bf16_f32 v43, v44, v45
	global_store_dwordx2 v245, v[42:43], s[16:17] offset:1024
	v_pk_mul_f32 v[46:47], v[46:47], v[252:253] op_sel_hi:[1,0]
	v_pk_mul_f32 v[48:49], v[48:49], v[252:253] op_sel_hi:[1,0]
	v_pk_mul_f32 v[46:47], v[226:227], v[46:47]
	v_pk_mul_f32 v[48:49], v[228:229], v[48:49]
	v_pk_add_f32 v[234:235], v[234:235], 1.0 op_sel_hi:[1,0]
	v_pk_add_f32 v[236:237], v[236:237], 1.0 op_sel_hi:[1,0]
	v_pk_fma_f32 v[46:47], v[234:235], v[46:47], v[230:231]
	v_pk_fma_f32 v[48:49], v[236:237], v[48:49], v[232:233]
	s_nop 0
	v_cvt_pk_bf16_f32 v46, v46, v47
	v_cvt_pk_bf16_f32 v47, v48, v49
	global_store_dwordx2 v245, v[46:47], s[16:17] offset:1536
	ds_read_b128 v[214:217], v238 offset:14336
	ds_read_b128 v[218:221], v238 offset:63488
	ds_read_b128 v[222:225], v239 offset:14336
	ds_read_b128 v[226:229], v238 offset:15360
	ds_read_b128 v[230:233], v238 offset:64512
	ds_read_b128 v[234:237], v239 offset:15360
	s_waitcnt lgkmcnt(6)
	v_pk_mul_f32 v[50:51], v[50:51], v[252:253] op_sel_hi:[1,0]
	v_pk_mul_f32 v[52:53], v[52:53], v[252:253] op_sel_hi:[1,0]
	v_pk_mul_f32 v[50:51], v[130:131], v[50:51]
	v_pk_mul_f32 v[52:53], v[132:133], v[52:53]
	v_pk_add_f32 v[138:139], v[138:139], 1.0 op_sel_hi:[1,0]
	v_pk_add_f32 v[140:141], v[140:141], 1.0 op_sel_hi:[1,0]
	v_pk_fma_f32 v[50:51], v[138:139], v[50:51], v[134:135]
	v_pk_fma_f32 v[52:53], v[140:141], v[52:53], v[136:137]
	s_nop 0
	v_cvt_pk_bf16_f32 v50, v50, v51
	v_cvt_pk_bf16_f32 v51, v52, v53
	global_store_dwordx2 v245, v[50:51], s[16:17] offset:2048
	v_pk_mul_f32 v[54:55], v[54:55], v[252:253] op_sel_hi:[1,0]
	v_pk_mul_f32 v[56:57], v[56:57], v[252:253] op_sel_hi:[1,0]
	v_pk_mul_f32 v[54:55], v[142:143], v[54:55]
	v_pk_mul_f32 v[56:57], v[144:145], v[56:57]
	v_pk_add_f32 v[150:151], v[150:151], 1.0 op_sel_hi:[1,0]
	v_pk_add_f32 v[152:153], v[152:153], 1.0 op_sel_hi:[1,0]
	v_pk_fma_f32 v[54:55], v[150:151], v[54:55], v[146:147]
	v_pk_fma_f32 v[56:57], v[152:153], v[56:57], v[148:149]
	s_nop 0
	v_cvt_pk_bf16_f32 v54, v54, v55
	v_cvt_pk_bf16_f32 v55, v56, v57
	global_store_dwordx2 v245, v[54:55], s[16:17] offset:2560
	s_waitcnt lgkmcnt(0)
	v_pk_mul_f32 v[58:59], v[58:59], v[252:253] op_sel_hi:[1,0]
	v_pk_mul_f32 v[60:61], v[60:61], v[252:253] op_sel_hi:[1,0]
	v_pk_mul_f32 v[58:59], v[214:215], v[58:59]
	v_pk_mul_f32 v[60:61], v[216:217], v[60:61]
	v_pk_add_f32 v[222:223], v[222:223], 1.0 op_sel_hi:[1,0]
	v_pk_add_f32 v[224:225], v[224:225], 1.0 op_sel_hi:[1,0]
	v_pk_fma_f32 v[58:59], v[222:223], v[58:59], v[218:219]
	v_pk_fma_f32 v[60:61], v[224:225], v[60:61], v[220:221]
	s_nop 0
	v_cvt_pk_bf16_f32 v58, v58, v59
	v_cvt_pk_bf16_f32 v59, v60, v61
	global_store_dwordx2 v245, v[58:59], s[16:17] offset:3072
	v_pk_mul_f32 v[62:63], v[62:63], v[252:253] op_sel_hi:[1,0]
	v_pk_mul_f32 v[64:65], v[64:65], v[252:253] op_sel_hi:[1,0]
	v_pk_mul_f32 v[62:63], v[226:227], v[62:63]
	v_pk_mul_f32 v[64:65], v[228:229], v[64:65]
	v_pk_add_f32 v[234:235], v[234:235], 1.0 op_sel_hi:[1,0]
	v_pk_add_f32 v[236:237], v[236:237], 1.0 op_sel_hi:[1,0]
	v_pk_fma_f32 v[62:63], v[234:235], v[62:63], v[230:231]
	v_pk_fma_f32 v[64:65], v[236:237], v[64:65], v[232:233]
	s_nop 0
	v_cvt_pk_bf16_f32 v62, v62, v63
	v_cvt_pk_bf16_f32 v63, v64, v65
	global_store_dwordx2 v245, v[62:63], s[16:17] offset:3584
	s_add_u32 s16, s16, 0x1000000
	s_addc_u32 s17, s17, 0
	s_waitcnt vmcnt(16)
	ds_read_b128 v[130:133], v238 offset:0
	ds_read_b128 v[134:137], v239 offset:16384
	ds_read_b128 v[138:141], v239 offset:32768
	ds_read_b128 v[142:145], v238 offset:1024
	ds_read_b128 v[146:149], v239 offset:17408
	ds_read_b128 v[150:153], v239 offset:33792
	v_pk_mul_f32 v[156:157], v[66:67], v[66:67]
	v_pk_mul_f32 v[158:159], v[68:69], v[68:69]
	v_pk_fma_f32 v[156:157], v[70:71], v[70:71], v[156:157]
	v_pk_fma_f32 v[158:159], v[72:73], v[72:73], v[158:159]
	v_pk_fma_f32 v[156:157], v[74:75], v[74:75], v[156:157]
	v_pk_fma_f32 v[158:159], v[76:77], v[76:77], v[158:159]
	v_pk_fma_f32 v[156:157], v[78:79], v[78:79], v[156:157]
	v_pk_fma_f32 v[158:159], v[80:81], v[80:81], v[158:159]
	v_pk_fma_f32 v[156:157], v[82:83], v[82:83], v[156:157]
	v_pk_fma_f32 v[158:159], v[84:85], v[84:85], v[158:159]
	v_pk_fma_f32 v[156:157], v[86:87], v[86:87], v[156:157]
	v_pk_fma_f32 v[158:159], v[88:89], v[88:89], v[158:159]
	v_pk_fma_f32 v[156:157], v[90:91], v[90:91], v[156:157]
	v_pk_fma_f32 v[158:159], v[92:93], v[92:93], v[158:159]
	v_pk_fma_f32 v[156:157], v[94:95], v[94:95], v[156:157]
	v_pk_fma_f32 v[158:159], v[96:97], v[96:97], v[158:159]
	v_pk_fma_f32 v[156:157], v[98:99], v[98:99], v[156:157]
	v_pk_fma_f32 v[158:159], v[100:101], v[100:101], v[158:159]
	v_pk_fma_f32 v[156:157], v[102:103], v[102:103], v[156:157]
	v_pk_fma_f32 v[158:159], v[104:105], v[104:105], v[158:159]
	v_pk_fma_f32 v[156:157], v[106:107], v[106:107], v[156:157]
	v_pk_fma_f32 v[158:159], v[108:109], v[108:109], v[158:159]
	v_pk_fma_f32 v[156:157], v[110:111], v[110:111], v[156:157]
	v_pk_fma_f32 v[158:159], v[112:113], v[112:113], v[158:159]
	v_pk_fma_f32 v[156:157], v[114:115], v[114:115], v[156:157]
	v_pk_fma_f32 v[158:159], v[116:117], v[116:117], v[158:159]
	v_pk_fma_f32 v[156:157], v[118:119], v[118:119], v[156:157]
	v_pk_fma_f32 v[158:159], v[120:121], v[120:121], v[158:159]
	v_pk_fma_f32 v[156:157], v[122:123], v[122:123], v[156:157]
	v_pk_fma_f32 v[158:159], v[124:125], v[124:125], v[158:159]
	v_pk_fma_f32 v[156:157], v[126:127], v[126:127], v[156:157]
	v_pk_fma_f32 v[158:159], v[128:129], v[128:129], v[158:159]
	v_pk_add_f32 v[156:157], v[156:157], v[158:159]
	s_nop 0
	v_add_f32_e32 v252, v156, v157
	s_waitcnt lgkmcnt(0)
	ds_bpermute_b32 v254, v246, v252
	s_waitcnt lgkmcnt(0)
	v_add_f32_e32 v252, v252, v254
	ds_bpermute_b32 v254, v247, v252
	s_waitcnt lgkmcnt(0)
	v_add_f32_e32 v252, v252, v254
	ds_bpermute_b32 v254, v248, v252
	s_waitcnt lgkmcnt(0)
	v_add_f32_e32 v252, v252, v254
	ds_bpermute_b32 v254, v249, v252
	s_waitcnt lgkmcnt(0)
	v_add_f32_e32 v252, v252, v254
	ds_bpermute_b32 v254, v250, v252
	s_waitcnt lgkmcnt(0)
	v_add_f32_e32 v252, v252, v254
	ds_bpermute_b32 v254, v251, v252
	s_waitcnt lgkmcnt(0)
	v_add_f32_e32 v252, v252, v254
	v_mov_b32_e32 v254, 0x358637bd
	v_fmac_f32_e32 v254, 0x39800000, v252
	v_mul_f32_e32 v252, 0x4b800000, v254
	v_cmp_gt_f32_e32 vcc, s20, v254
	s_nop 1
	v_cndmask_b32_e32 v254, v254, v252, vcc
	v_rsq_f32_e32 v254, v254
	s_nop 0
	v_mul_f32_e32 v252, 0x45800000, v254
	v_cndmask_b32_e32 v252, v254, v252, vcc
	ds_read_b128 v[214:217], v238 offset:2048
	ds_read_b128 v[218:221], v239 offset:18432
	ds_read_b128 v[222:225], v239 offset:34816
	ds_read_b128 v[226:229], v238 offset:3072
	ds_read_b128 v[230:233], v239 offset:19456
	ds_read_b128 v[234:237], v239 offset:35840
	s_waitcnt lgkmcnt(6)
	v_pk_mul_f32 v[66:67], v[66:67], v[252:253] op_sel_hi:[1,0]
	v_pk_mul_f32 v[68:69], v[68:69], v[252:253] op_sel_hi:[1,0]
	v_pk_mul_f32 v[66:67], v[130:131], v[66:67]
	v_pk_mul_f32 v[68:69], v[132:133], v[68:69]
	v_pk_add_f32 v[138:139], v[138:139], 1.0 op_sel_hi:[1,0]
	v_pk_add_f32 v[140:141], v[140:141], 1.0 op_sel_hi:[1,0]
	v_pk_fma_f32 v[66:67], v[138:139], v[66:67], v[134:135]
	v_pk_fma_f32 v[68:69], v[140:141], v[68:69], v[136:137]
	s_nop 0
	v_cvt_pk_bf16_f32 v66, v66, v67
	v_cvt_pk_bf16_f32 v67, v68, v69
	global_store_dwordx2 v244, v[66:67], s[16:17] offset:0
	v_pk_mul_f32 v[70:71], v[70:71], v[252:253] op_sel_hi:[1,0]
	v_pk_mul_f32 v[72:73], v[72:73], v[252:253] op_sel_hi:[1,0]
	v_pk_mul_f32 v[70:71], v[142:143], v[70:71]
	v_pk_mul_f32 v[72:73], v[144:145], v[72:73]
	v_pk_add_f32 v[150:151], v[150:151], 1.0 op_sel_hi:[1,0]
	v_pk_add_f32 v[152:153], v[152:153], 1.0 op_sel_hi:[1,0]
	v_pk_fma_f32 v[70:71], v[150:151], v[70:71], v[146:147]
	v_pk_fma_f32 v[72:73], v[152:153], v[72:73], v[148:149]
	s_nop 0
	v_cvt_pk_bf16_f32 v70, v70, v71
	v_cvt_pk_bf16_f32 v71, v72, v73
	global_store_dwordx2 v244, v[70:71], s[16:17] offset:512
	ds_read_b128 v[130:133], v238 offset:4096
	ds_read_b128 v[134:137], v239 offset:20480
	ds_read_b128 v[138:141], v239 offset:36864
	ds_read_b128 v[142:145], v238 offset:5120
	ds_read_b128 v[146:149], v239 offset:21504
	ds_read_b128 v[150:153], v239 offset:37888
	s_waitcnt lgkmcnt(6)
	v_pk_mul_f32 v[74:75], v[74:75], v[252:253] op_sel_hi:[1,0]
	v_pk_mul_f32 v[76:77], v[76:77], v[252:253] op_sel_hi:[1,0]
	v_pk_mul_f32 v[74:75], v[214:215], v[74:75]
	v_pk_mul_f32 v[76:77], v[216:217], v[76:77]
	v_pk_add_f32 v[222:223], v[222:223], 1.0 op_sel_hi:[1,0]
	v_pk_add_f32 v[224:225], v[224:225], 1.0 op_sel_hi:[1,0]
	v_pk_fma_f32 v[74:75], v[222:223], v[74:75], v[218:219]
	v_pk_fma_f32 v[76:77], v[224:225], v[76:77], v[220:221]
	s_nop 0
	v_cvt_pk_bf16_f32 v74, v74, v75
	v_cvt_pk_bf16_f32 v75, v76, v77
	global_store_dwordx2 v244, v[74:75], s[16:17] offset:1024
	v_pk_mul_f32 v[78:79], v[78:79], v[252:253] op_sel_hi:[1,0]
	v_pk_mul_f32 v[80:81], v[80:81], v[252:253] op_sel_hi:[1,0]
	v_pk_mul_f32 v[78:79], v[226:227], v[78:79]
	v_pk_mul_f32 v[80:81], v[228:229], v[80:81]
	v_pk_add_f32 v[234:235], v[234:235], 1.0 op_sel_hi:[1,0]
	v_pk_add_f32 v[236:237], v[236:237], 1.0 op_sel_hi:[1,0]
	v_pk_fma_f32 v[78:79], v[234:235], v[78:79], v[230:231]
	v_pk_fma_f32 v[80:81], v[236:237], v[80:81], v[232:233]
	s_nop 0
	v_cvt_pk_bf16_f32 v78, v78, v79
	v_cvt_pk_bf16_f32 v79, v80, v81
	global_store_dwordx2 v244, v[78:79], s[16:17] offset:1536
	ds_read_b128 v[214:217], v238 offset:6144
	ds_read_b128 v[218:221], v239 offset:22528
	ds_read_b128 v[222:225], v239 offset:38912
	ds_read_b128 v[226:229], v238 offset:7168
	ds_read_b128 v[230:233], v239 offset:23552
	ds_read_b128 v[234:237], v239 offset:39936
	s_waitcnt lgkmcnt(6)
	v_pk_mul_f32 v[82:83], v[82:83], v[252:253] op_sel_hi:[1,0]
	v_pk_mul_f32 v[84:85], v[84:85], v[252:253] op_sel_hi:[1,0]
	v_pk_mul_f32 v[82:83], v[130:131], v[82:83]
	v_pk_mul_f32 v[84:85], v[132:133], v[84:85]
	v_pk_add_f32 v[138:139], v[138:139], 1.0 op_sel_hi:[1,0]
	v_pk_add_f32 v[140:141], v[140:141], 1.0 op_sel_hi:[1,0]
	v_pk_fma_f32 v[82:83], v[138:139], v[82:83], v[134:135]
	v_pk_fma_f32 v[84:85], v[140:141], v[84:85], v[136:137]
	s_nop 0
	v_cvt_pk_bf16_f32 v82, v82, v83
	v_cvt_pk_bf16_f32 v83, v84, v85
	global_store_dwordx2 v244, v[82:83], s[16:17] offset:2048
	v_pk_mul_f32 v[86:87], v[86:87], v[252:253] op_sel_hi:[1,0]
	v_pk_mul_f32 v[88:89], v[88:89], v[252:253] op_sel_hi:[1,0]
	v_pk_mul_f32 v[86:87], v[142:143], v[86:87]
	v_pk_mul_f32 v[88:89], v[144:145], v[88:89]
	v_pk_add_f32 v[150:151], v[150:151], 1.0 op_sel_hi:[1,0]
	v_pk_add_f32 v[152:153], v[152:153], 1.0 op_sel_hi:[1,0]
	v_pk_fma_f32 v[86:87], v[150:151], v[86:87], v[146:147]
	v_pk_fma_f32 v[88:89], v[152:153], v[88:89], v[148:149]
	s_nop 0
	v_cvt_pk_bf16_f32 v86, v86, v87
	v_cvt_pk_bf16_f32 v87, v88, v89
	global_store_dwordx2 v244, v[86:87], s[16:17] offset:2560
	ds_read_b128 v[130:133], v238 offset:8192
	ds_read_b128 v[134:137], v239 offset:24576
	ds_read_b128 v[138:141], v239 offset:40960
	ds_read_b128 v[142:145], v238 offset:9216
	ds_read_b128 v[146:149], v239 offset:25600
	ds_read_b128 v[150:153], v239 offset:41984
	s_waitcnt lgkmcnt(6)
	v_pk_mul_f32 v[90:91], v[90:91], v[252:253] op_sel_hi:[1,0]
	v_pk_mul_f32 v[92:93], v[92:93], v[252:253] op_sel_hi:[1,0]
	v_pk_mul_f32 v[90:91], v[214:215], v[90:91]
	v_pk_mul_f32 v[92:93], v[216:217], v[92:93]
	v_pk_add_f32 v[222:223], v[222:223], 1.0 op_sel_hi:[1,0]
	v_pk_add_f32 v[224:225], v[224:225], 1.0 op_sel_hi:[1,0]
	v_pk_fma_f32 v[90:91], v[222:223], v[90:91], v[218:219]
	v_pk_fma_f32 v[92:93], v[224:225], v[92:93], v[220:221]
	s_nop 0
	v_cvt_pk_bf16_f32 v90, v90, v91
	v_cvt_pk_bf16_f32 v91, v92, v93
	global_store_dwordx2 v244, v[90:91], s[16:17] offset:3072
	v_pk_mul_f32 v[94:95], v[94:95], v[252:253] op_sel_hi:[1,0]
	v_pk_mul_f32 v[96:97], v[96:97], v[252:253] op_sel_hi:[1,0]
	v_pk_mul_f32 v[94:95], v[226:227], v[94:95]
	v_pk_mul_f32 v[96:97], v[228:229], v[96:97]
	v_pk_add_f32 v[234:235], v[234:235], 1.0 op_sel_hi:[1,0]
	v_pk_add_f32 v[236:237], v[236:237], 1.0 op_sel_hi:[1,0]
	v_pk_fma_f32 v[94:95], v[234:235], v[94:95], v[230:231]
	v_pk_fma_f32 v[96:97], v[236:237], v[96:97], v[232:233]
	s_nop 0
	v_cvt_pk_bf16_f32 v94, v94, v95
	v_cvt_pk_bf16_f32 v95, v96, v97
	global_store_dwordx2 v244, v[94:95], s[16:17] offset:3584
	ds_read_b128 v[214:217], v238 offset:10240
	ds_read_b128 v[218:221], v239 offset:26624
	ds_read_b128 v[222:225], v239 offset:43008
	ds_read_b128 v[226:229], v238 offset:11264
	ds_read_b128 v[230:233], v239 offset:27648
	ds_read_b128 v[234:237], v239 offset:44032
	s_waitcnt lgkmcnt(6)
	v_pk_mul_f32 v[98:99], v[98:99], v[252:253] op_sel_hi:[1,0]
	v_pk_mul_f32 v[100:101], v[100:101], v[252:253] op_sel_hi:[1,0]
	v_pk_mul_f32 v[98:99], v[130:131], v[98:99]
	v_pk_mul_f32 v[100:101], v[132:133], v[100:101]
	v_pk_add_f32 v[138:139], v[138:139], 1.0 op_sel_hi:[1,0]
	v_pk_add_f32 v[140:141], v[140:141], 1.0 op_sel_hi:[1,0]
	v_pk_fma_f32 v[98:99], v[138:139], v[98:99], v[134:135]
	v_pk_fma_f32 v[100:101], v[140:141], v[100:101], v[136:137]
	s_nop 0
	v_cvt_pk_bf16_f32 v98, v98, v99
	v_cvt_pk_bf16_f32 v99, v100, v101
	global_store_dwordx2 v245, v[98:99], s[16:17] offset:0
	v_pk_mul_f32 v[102:103], v[102:103], v[252:253] op_sel_hi:[1,0]
	v_pk_mul_f32 v[104:105], v[104:105], v[252:253] op_sel_hi:[1,0]
	v_pk_mul_f32 v[102:103], v[142:143], v[102:103]
	v_pk_mul_f32 v[104:105], v[144:145], v[104:105]
	v_pk_add_f32 v[150:151], v[150:151], 1.0 op_sel_hi:[1,0]
	v_pk_add_f32 v[152:153], v[152:153], 1.0 op_sel_hi:[1,0]
	v_pk_fma_f32 v[102:103], v[150:151], v[102:103], v[146:147]
	v_pk_fma_f32 v[104:105], v[152:153], v[104:105], v[148:149]
	s_nop 0
	v_cvt_pk_bf16_f32 v102, v102, v103
	v_cvt_pk_bf16_f32 v103, v104, v105
	global_store_dwordx2 v245, v[102:103], s[16:17] offset:512
	ds_read_b128 v[130:133], v238 offset:12288
	ds_read_b128 v[134:137], v239 offset:28672
	ds_read_b128 v[138:141], v239 offset:45056
	ds_read_b128 v[142:145], v238 offset:13312
	ds_read_b128 v[146:149], v239 offset:29696
	ds_read_b128 v[150:153], v239 offset:46080
	s_waitcnt lgkmcnt(6)
	v_pk_mul_f32 v[106:107], v[106:107], v[252:253] op_sel_hi:[1,0]
	v_pk_mul_f32 v[108:109], v[108:109], v[252:253] op_sel_hi:[1,0]
	v_pk_mul_f32 v[106:107], v[214:215], v[106:107]
	v_pk_mul_f32 v[108:109], v[216:217], v[108:109]
	v_pk_add_f32 v[222:223], v[222:223], 1.0 op_sel_hi:[1,0]
	v_pk_add_f32 v[224:225], v[224:225], 1.0 op_sel_hi:[1,0]
	v_pk_fma_f32 v[106:107], v[222:223], v[106:107], v[218:219]
	v_pk_fma_f32 v[108:109], v[224:225], v[108:109], v[220:221]
	s_nop 0
	v_cvt_pk_bf16_f32 v106, v106, v107
	v_cvt_pk_bf16_f32 v107, v108, v109
	global_store_dwordx2 v245, v[106:107], s[16:17] offset:1024
	v_pk_mul_f32 v[110:111], v[110:111], v[252:253] op_sel_hi:[1,0]
	v_pk_mul_f32 v[112:113], v[112:113], v[252:253] op_sel_hi:[1,0]
	v_pk_mul_f32 v[110:111], v[226:227], v[110:111]
	v_pk_mul_f32 v[112:113], v[228:229], v[112:113]
	v_pk_add_f32 v[234:235], v[234:235], 1.0 op_sel_hi:[1,0]
	v_pk_add_f32 v[236:237], v[236:237], 1.0 op_sel_hi:[1,0]
	v_pk_fma_f32 v[110:111], v[234:235], v[110:111], v[230:231]
	v_pk_fma_f32 v[112:113], v[236:237], v[112:113], v[232:233]
	s_nop 0
	v_cvt_pk_bf16_f32 v110, v110, v111
	v_cvt_pk_bf16_f32 v111, v112, v113
	global_store_dwordx2 v245, v[110:111], s[16:17] offset:1536
	ds_read_b128 v[214:217], v238 offset:14336
	ds_read_b128 v[218:221], v239 offset:30720
	ds_read_b128 v[222:225], v239 offset:47104
	ds_read_b128 v[226:229], v238 offset:15360
	ds_read_b128 v[230:233], v239 offset:31744
	ds_read_b128 v[234:237], v239 offset:48128
	s_waitcnt lgkmcnt(6)
	v_pk_mul_f32 v[114:115], v[114:115], v[252:253] op_sel_hi:[1,0]
	v_pk_mul_f32 v[116:117], v[116:117], v[252:253] op_sel_hi:[1,0]
	v_pk_mul_f32 v[114:115], v[130:131], v[114:115]
	v_pk_mul_f32 v[116:117], v[132:133], v[116:117]
	v_pk_add_f32 v[138:139], v[138:139], 1.0 op_sel_hi:[1,0]
	v_pk_add_f32 v[140:141], v[140:141], 1.0 op_sel_hi:[1,0]
	v_pk_fma_f32 v[114:115], v[138:139], v[114:115], v[134:135]
	v_pk_fma_f32 v[116:117], v[140:141], v[116:117], v[136:137]
	s_nop 0
	v_cvt_pk_bf16_f32 v114, v114, v115
	v_cvt_pk_bf16_f32 v115, v116, v117
	global_store_dwordx2 v245, v[114:115], s[16:17] offset:2048
	v_pk_mul_f32 v[118:119], v[118:119], v[252:253] op_sel_hi:[1,0]
	v_pk_mul_f32 v[120:121], v[120:121], v[252:253] op_sel_hi:[1,0]
	v_pk_mul_f32 v[118:119], v[142:143], v[118:119]
	v_pk_mul_f32 v[120:121], v[144:145], v[120:121]
	v_pk_add_f32 v[150:151], v[150:151], 1.0 op_sel_hi:[1,0]
	v_pk_add_f32 v[152:153], v[152:153], 1.0 op_sel_hi:[1,0]
	v_pk_fma_f32 v[118:119], v[150:151], v[118:119], v[146:147]
	v_pk_fma_f32 v[120:121], v[152:153], v[120:121], v[148:149]
	s_nop 0
	v_cvt_pk_bf16_f32 v118, v118, v119
	v_cvt_pk_bf16_f32 v119, v120, v121
	global_store_dwordx2 v245, v[118:119], s[16:17] offset:2560
	s_waitcnt lgkmcnt(0)
	v_pk_mul_f32 v[122:123], v[122:123], v[252:253] op_sel_hi:[1,0]
	v_pk_mul_f32 v[124:125], v[124:125], v[252:253] op_sel_hi:[1,0]
	v_pk_mul_f32 v[122:123], v[214:215], v[122:123]
	v_pk_mul_f32 v[124:125], v[216:217], v[124:125]
	v_pk_add_f32 v[222:223], v[222:223], 1.0 op_sel_hi:[1,0]
	v_pk_add_f32 v[224:225], v[224:225], 1.0 op_sel_hi:[1,0]
	v_pk_fma_f32 v[122:123], v[222:223], v[122:123], v[218:219]
	v_pk_fma_f32 v[124:125], v[224:225], v[124:125], v[220:221]
	s_nop 0
	v_cvt_pk_bf16_f32 v122, v122, v123
	v_cvt_pk_bf16_f32 v123, v124, v125
	global_store_dwordx2 v245, v[122:123], s[16:17] offset:3072
	v_pk_mul_f32 v[126:127], v[126:127], v[252:253] op_sel_hi:[1,0]
	v_pk_mul_f32 v[128:129], v[128:129], v[252:253] op_sel_hi:[1,0]
	v_pk_mul_f32 v[126:127], v[226:227], v[126:127]
	v_pk_mul_f32 v[128:129], v[228:229], v[128:129]
	v_pk_add_f32 v[234:235], v[234:235], 1.0 op_sel_hi:[1,0]
	v_pk_add_f32 v[236:237], v[236:237], 1.0 op_sel_hi:[1,0]
	v_pk_fma_f32 v[126:127], v[234:235], v[126:127], v[230:231]
	v_pk_fma_f32 v[128:129], v[236:237], v[128:129], v[232:233]
	s_nop 0
	v_cvt_pk_bf16_f32 v126, v126, v127
	v_cvt_pk_bf16_f32 v127, v128, v129
	global_store_dwordx2 v245, v[126:127], s[16:17] offset:3584
	s_branch .LBB0_104
.Lh1_old:
	v_mbcnt_lo_u32_b32 v1, -1, 0
	v_mbcnt_hi_u32_b32 v2, -1, v1
	v_and_b32_e32 v1, 64, v2
	v_add_u32_e32 v3, 64, v1
	v_xor_b32_e32 v1, 1, v2
	v_cmp_lt_i32_e32 vcc, v1, v3
	v_xor_b32_e32 v4, 2, v2
	v_readlane_b32 s8, v255, 2
	v_cndmask_b32_e32 v1, v2, v1, vcc
	v_cmp_lt_i32_e32 vcc, v4, v3
	v_mov_b32_e32 v67, 0
	v_lshlrev_b32_e32 v66, 4, v174
	v_cndmask_b32_e32 v4, v2, v4, vcc
	v_lshlrev_b32_e32 v97, 2, v4
	v_xor_b32_e32 v4, 4, v2
	v_cmp_lt_i32_e32 vcc, v4, v3
	v_readlane_b32 s12, v255, 6
	v_readlane_b32 s13, v255, 7
	v_cndmask_b32_e32 v4, v2, v4, vcc
	v_lshlrev_b32_e32 v98, 2, v4
	v_xor_b32_e32 v4, 8, v2
	v_cmp_lt_i32_e32 vcc, v4, v3
	v_lshl_add_u64 v[68:69], s[12:13], 0, v[66:67]
	v_readlane_b32 s9, v255, 3
	v_cndmask_b32_e32 v4, v2, v4, vcc
	v_lshlrev_b32_e32 v99, 2, v4
	v_xor_b32_e32 v4, 16, v2
	v_cmp_lt_i32_e32 vcc, v4, v3
	s_ashr_i32 s5, s4, 31
	s_lshl_b32 s6, s33, 3
	v_cndmask_b32_e32 v4, v2, v4, vcc
	v_lshlrev_b32_e32 v100, 2, v4
	v_xor_b32_e32 v4, 32, v2
	v_cmp_lt_i32_e32 vcc, v4, v3
	s_lshl_b64 s[8:9], s[4:5], 13
	s_add_u32 s8, s70, s8
	v_cndmask_b32_e32 v2, v2, v4, vcc
	v_lshlrev_b32_e32 v101, 2, v2
	v_lshlrev_b32_e32 v2, 2, v174
	v_or_b32_e32 v10, 0x400, v2
	v_lshlrev_b32_e32 v66, 2, v10
	v_or_b32_e32 v12, 0x500, v2
	v_lshl_add_u64 v[70:71], s[12:13], 0, v[66:67]
	v_lshlrev_b32_e32 v66, 2, v12
	v_or_b32_e32 v14, 0x600, v2
	v_lshl_add_u64 v[72:73], s[12:13], 0, v[66:67]
	v_lshlrev_b32_e32 v66, 2, v14
	v_or_b32_e32 v16, 0x700, v2
	v_lshl_add_u64 v[74:75], s[12:13], 0, v[66:67]
	v_lshlrev_b32_e32 v66, 2, v16
	v_or_b32_e32 v18, 0x800, v2
	v_lshl_add_u64 v[76:77], s[12:13], 0, v[66:67]
	v_lshlrev_b32_e32 v66, 2, v18
	v_or_b32_e32 v20, 0x900, v2
	v_lshl_add_u64 v[78:79], s[12:13], 0, v[66:67]
	v_lshlrev_b32_e32 v66, 2, v20
	v_or_b32_e32 v22, 0xa00, v2
	v_lshl_add_u64 v[80:81], s[12:13], 0, v[66:67]
	v_lshlrev_b32_e32 v66, 2, v22
	v_or_b32_e32 v24, 0xb00, v2
	v_lshl_add_u64 v[82:83], s[12:13], 0, v[66:67]
	v_lshlrev_b32_e32 v66, 2, v24
	v_or_b32_e32 v26, 0xc00, v2
	v_lshl_add_u64 v[84:85], s[12:13], 0, v[66:67]
	v_lshlrev_b32_e32 v66, 2, v26
	v_or_b32_e32 v28, 0xd00, v2
	v_lshl_add_u64 v[86:87], s[12:13], 0, v[66:67]
	v_lshlrev_b32_e32 v66, 2, v28
	v_or_b32_e32 v30, 0xe00, v2
	v_lshl_add_u64 v[88:89], s[12:13], 0, v[66:67]
	v_lshlrev_b32_e32 v66, 2, v30
	v_or_b32_e32 v32, 0xf00, v2
	v_lshl_add_u64 v[90:91], s[12:13], 0, v[66:67]
	v_lshlrev_b32_e32 v66, 2, v32
	v_lshl_add_u64 v[92:93], s[12:13], 0, v[66:67]
	v_lshlrev_b32_e32 v66, 3, v174
	s_addc_u32 s9, s71, s9
	v_readlane_b32 s10, v255, 4
	v_readlane_b32 s11, v255, 5
	v_or_b32_e32 v4, 0x100, v2
	v_or_b32_e32 v6, 0x200, v2
	v_or_b32_e32 v8, 0x300, v2
	v_lshl_add_u64 v[34:35], s[8:9], 0, v[66:67]
	s_mov_b64 s[8:9], 0x3f000000
	s_ashr_i32 s7, s6, 31
	v_lshlrev_b32_e32 v1, 2, v1
	v_lshl_add_u64 v[94:95], v[34:35], 0, s[8:9]
	s_lshl_b64 s[8:9], s[6:7], 13
	s_movk_i32 s3, 0x2000
	v_lshlrev_b32_e32 v66, 4, v174
	s_movk_i32 s10, 0x1000
	s_movk_i32 s11, 0x3000
	v_mov_b32_e32 v102, 0x358637bd
	s_mov_b32 s30, 0x800000
	v_lshlrev_b32_e32 v103, 2, v2
	v_lshlrev_b32_e32 v104, 2, v4
	v_lshlrev_b32_e32 v105, 2, v6
	v_lshlrev_b32_e32 v106, 2, v8
	v_lshlrev_b32_e32 v107, 2, v10
	v_lshlrev_b32_e32 v108, 2, v12
	v_lshlrev_b32_e32 v109, 2, v14
	v_lshlrev_b32_e32 v110, 2, v16
	v_lshlrev_b32_e32 v111, 2, v18
	v_lshlrev_b32_e32 v112, 2, v20
	v_lshlrev_b32_e32 v113, 2, v22
	v_lshlrev_b32_e32 v114, 2, v24
	v_lshlrev_b32_e32 v115, 2, v26
	v_lshlrev_b32_e32 v116, 2, v28
	v_lshlrev_b32_e32 v117, 2, v30
	v_lshlrev_b32_e32 v118, 2, v32
	v_readlane_b32 s14, v255, 8
	v_readlane_b32 s15, v255, 9
	v_readlane_b32 s16, v255, 10
	v_readlane_b32 s17, v255, 11
	v_readlane_b32 s18, v255, 12
	v_readlane_b32 s19, v255, 13
	v_readlane_b32 s20, v255, 14
	v_readlane_b32 s21, v255, 15
	v_readlane_b32 s22, v255, 16
	v_readlane_b32 s23, v255, 17

.LBB0_984:
	s_cmp_lt_i32 s72, 15
	s_cselect_b64 s[4:5], -1, 0
	s_and_b64 s[0:1], s[4:5], s[0:1]
	s_andn2_b64 vcc, exec, s[0:1]
	s_cbranch_vccnz .LBB0_988
	s_lshl_b32 s0, s2, 3
	s_add_i32 s0, s96, s0
	s_cmpk_gt_i32 s0, 0x2fff
	s_cbranch_scc1 .LBB0_988
	s_cmp_lg_u32 s33, 0x100
	s_cbranch_scc1 .LrB_old
	v_readlane_b32 s10, v255, 12
	v_readlane_b32 s11, v255, 13
	v_lshl_add_u32 v180, s96, 6, v174
	v_lshlrev_b32_e32 v180, 4, v180
	v_add_u32_e32 v181, 0x2000, v180
	s_lshr_b32 s3, s2, 7
	s_add_u32 s12, s28, 0x14000
	s_addc_u32 s13, s29, 0
	s_add_i32 s5, s3, 1
	s_mul_i32 s5, s5, 0x18000
	s_add_u32 s14, s12, s5
	s_addc_u32 s15, s13, 0
	s_add_i32 s5, s3, 3
	s_mul_i32 s5, s5, 0x18000
	s_add_u32 s16, s12, s5
	s_addc_u32 s17, s13, 0
	s_nop 4
	global_load_dwordx4 v[2:5], v180, s[10:11]
	global_load_dwordx4 v[6:9], v181, s[10:11]
	global_load_dwordx4 v[10:13], v180, s[12:13]
	global_load_dwordx4 v[14:17], v181, s[12:13]
	global_load_dwordx4 v[18:21], v180, s[14:15]
	global_load_dwordx4 v[22:25], v181, s[14:15]
	global_load_dwordx4 v[26:29], v180, s[16:17]
	global_load_dwordx4 v[30:33], v181, s[16:17]
	s_waitcnt vmcnt(0)
	ds_write_b128 v180, v[2:5] offset:0
	ds_write_b128 v180, v[6:9] offset:8192
	ds_write_b128 v180, v[10:13] offset:16384
	ds_write_b128 v180, v[14:17] offset:24576
	ds_write_b128 v180, v[18:21] offset:32768
	ds_write_b128 v180, v[22:25] offset:40960
	ds_write_b128 v180, v[26:29] offset:49152
	ds_write_b128 v180, v[30:33] offset:57344
	v_lshlrev_b32_e32 v238, 4, v174
	v_add_u32_e32 v241, 0x1000, v238
	v_add_u32_e32 v242, 0x2000, v238
	v_add_u32_e32 v243, 0x3000, v238
	v_lshlrev_b32_e32 v244, 3, v174
	v_add_u32_e32 v245, 0x1000, v244
	v_xor_b32_e32 v246, 1, v174
	v_lshlrev_b32_e32 v246, 2, v246
	v_xor_b32_e32 v247, 2, v174
	v_lshlrev_b32_e32 v247, 2, v247
	v_xor_b32_e32 v248, 4, v174
	v_lshlrev_b32_e32 v248, 2, v248
	v_xor_b32_e32 v249, 8, v174
	v_lshlrev_b32_e32 v249, 2, v249
	v_xor_b32_e32 v250, 16, v174
	v_lshlrev_b32_e32 v250, 2, v250
	v_xor_b32_e32 v251, 32, v174
	v_lshlrev_b32_e32 v251, 2, v251
	s_mov_b32 s20, 0x800000
	s_lshl_b32 s5, s0, 13
	s_add_u32 s18, s70, s5
	s_addc_u32 s19, s71, 0
	s_add_u32 s22, s18, 0x51000000
	s_addc_u32 s23, s19, 0
	s_add_u32 s24, s18, 0x3f000000
	s_addc_u32 s25, s19, 0
	s_lshl_b32 s5, s0, 14
	s_add_u32 s30, s68, s5
	s_addc_u32 s31, s69, 0
	s_waitcnt lgkmcnt(0)
	s_barrier
	global_load_dwordx2 v[2:3], v244, s[22:23] offset:0
	global_load_dwordx2 v[4:5], v244, s[22:23] offset:512
	global_load_dwordx2 v[6:7], v244, s[22:23] offset:1024
	global_load_dwordx2 v[8:9], v244, s[22:23] offset:1536
	global_load_dwordx2 v[10:11], v244, s[22:23] offset:2048
	global_load_dwordx2 v[12:13], v244, s[22:23] offset:2560
	global_load_dwordx2 v[14:15], v244, s[22:23] offset:3072
	global_load_dwordx2 v[16:17], v244, s[22:23] offset:3584
	global_load_dwordx2 v[18:19], v245, s[22:23] offset:0
	global_load_dwordx2 v[20:21], v245, s[22:23] offset:512
	global_load_dwordx2 v[22:23], v245, s[22:23] offset:1024
	global_load_dwordx2 v[24:25], v245, s[22:23] offset:1536
	global_load_dwordx2 v[26:27], v245, s[22:23] offset:2048
	global_load_dwordx2 v[28:29], v245, s[22:23] offset:2560
	global_load_dwordx2 v[30:31], v245, s[22:23] offset:3072
	global_load_dwordx2 v[32:33], v245, s[22:23] offset:3584
	global_load_dwordx2 v[34:35], v244, s[24:25] offset:0
	global_load_dwordx2 v[36:37], v244, s[24:25] offset:512
	global_load_dwordx2 v[38:39], v244, s[24:25] offset:1024
	global_load_dwordx2 v[40:41], v244, s[24:25] offset:1536
	global_load_dwordx2 v[42:43], v244, s[24:25] offset:2048
	global_load_dwordx2 v[44:45], v244, s[24:25] offset:2560
	global_load_dwordx2 v[46:47], v244, s[24:25] offset:3072
	global_load_dwordx2 v[48:49], v244, s[24:25] offset:3584
	global_load_dwordx2 v[50:51], v245, s[24:25] offset:0
	global_load_dwordx2 v[52:53], v245, s[24:25] offset:512
	global_load_dwordx2 v[54:55], v245, s[24:25] offset:1024
	global_load_dwordx2 v[56:57], v245, s[24:25] offset:1536
	global_load_dwordx2 v[58:59], v245, s[24:25] offset:2048
	global_load_dwordx2 v[60:61], v245, s[24:25] offset:2560
	global_load_dwordx2 v[62:63], v245, s[24:25] offset:3072
	global_load_dwordx2 v[64:65], v245, s[24:25] offset:3584
	s_waitcnt vmcnt(0)
	s_add_u32 s22, s22, 0x1000000
	s_addc_u32 s23, s23, 0
	s_add_u32 s24, s24, 0x1000000
	s_addc_u32 s25, s25, 0
	global_load_dwordx2 v[66:67], v244, s[22:23] offset:0
	global_load_dwordx2 v[68:69], v244, s[22:23] offset:512
	global_load_dwordx2 v[70:71], v244, s[22:23] offset:1024
	global_load_dwordx2 v[72:73], v244, s[22:23] offset:1536
	global_load_dwordx2 v[74:75], v244, s[22:23] offset:2048
	global_load_dwordx2 v[76:77], v244, s[22:23] offset:2560
	global_load_dwordx2 v[78:79], v244, s[22:23] offset:3072
	global_load_dwordx2 v[80:81], v244, s[22:23] offset:3584
	global_load_dwordx2 v[82:83], v245, s[22:23] offset:0
	global_load_dwordx2 v[84:85], v245, s[22:23] offset:512
	global_load_dwordx2 v[86:87], v245, s[22:23] offset:1024
	global_load_dwordx2 v[88:89], v245, s[22:23] offset:1536
	global_load_dwordx2 v[90:91], v245, s[22:23] offset:2048
	global_load_dwordx2 v[92:93], v245, s[22:23] offset:2560
	global_load_dwordx2 v[94:95], v245, s[22:23] offset:3072
	global_load_dwordx2 v[96:97], v245, s[22:23] offset:3584
	global_load_dwordx2 v[98:99], v244, s[24:25] offset:0
	global_load_dwordx2 v[100:101], v244, s[24:25] offset:512
	global_load_dwordx2 v[102:103], v244, s[24:25] offset:1024
	global_load_dwordx2 v[104:105], v244, s[24:25] offset:1536
	global_load_dwordx2 v[106:107], v244, s[24:25] offset:2048
	global_load_dwordx2 v[108:109], v244, s[24:25] offset:2560
	global_load_dwordx2 v[110:111], v244, s[24:25] offset:3072
	global_load_dwordx2 v[112:113], v244, s[24:25] offset:3584
	global_load_dwordx2 v[114:115], v245, s[24:25] offset:0
	global_load_dwordx2 v[116:117], v245, s[24:25] offset:512
	global_load_dwordx2 v[118:119], v245, s[24:25] offset:1024
	global_load_dwordx2 v[120:121], v245, s[24:25] offset:1536
	global_load_dwordx2 v[122:123], v245, s[24:25] offset:2048
	global_load_dwordx2 v[124:125], v245, s[24:25] offset:2560
	global_load_dwordx2 v[126:127], v245, s[24:25] offset:3072
	global_load_dwordx2 v[128:129], v245, s[24:25] offset:3584
	ds_read_b128 v[130:133], v238 offset:0
	ds_read_b128 v[134:137], v238 offset:16384
	ds_read_b128 v[138:141], v238 offset:1024
	ds_read_b128 v[142:145], v238 offset:17408
	v_lshlrev_b32_e32 v162, 16, v2
	v_and_b32_e32 v163, 0xffff0000, v2
	v_lshlrev_b32_e32 v164, 16, v3
	v_and_b32_e32 v165, 0xffff0000, v3
	v_pk_mul_f32 v[176:177], v[162:163], v[162:163]
	v_pk_mul_f32 v[178:179], v[164:165], v[164:165]
	v_lshlrev_b32_e32 v166, 16, v4
	v_and_b32_e32 v167, 0xffff0000, v4
	v_lshlrev_b32_e32 v168, 16, v5
	v_and_b32_e32 v169, 0xffff0000, v5
	v_pk_fma_f32 v[176:177], v[166:167], v[166:167], v[176:177]
	v_pk_fma_f32 v[178:179], v[168:169], v[168:169], v[178:179]
	v_lshlrev_b32_e32 v162, 16, v6
	v_and_b32_e32 v163, 0xffff0000, v6
	v_lshlrev_b32_e32 v164, 16, v7
	v_and_b32_e32 v165, 0xffff0000, v7
	v_pk_fma_f32 v[176:177], v[162:163], v[162:163], v[176:177]
	v_pk_fma_f32 v[178:179], v[164:165], v[164:165], v[178:179]
	v_lshlrev_b32_e32 v166, 16, v8
	v_and_b32_e32 v167, 0xffff0000, v8
	v_lshlrev_b32_e32 v168, 16, v9
	v_and_b32_e32 v169, 0xffff0000, v9
	v_pk_fma_f32 v[176:177], v[166:167], v[166:167], v[176:177]
	v_pk_fma_f32 v[178:179], v[168:169], v[168:169], v[178:179]
	v_lshlrev_b32_e32 v162, 16, v10
	v_and_b32_e32 v163, 0xffff0000, v10
	v_lshlrev_b32_e32 v164, 16, v11
	v_and_b32_e32 v165, 0xffff0000, v11
	v_pk_fma_f32 v[176:177], v[162:163], v[162:163], v[176:177]
	v_pk_fma_f32 v[178:179], v[164:165], v[164:165], v[178:179]
	v_lshlrev_b32_e32 v166, 16, v12
	v_and_b32_e32 v167, 0xffff0000, v12
	v_lshlrev_b32_e32 v168, 16, v13
	v_and_b32_e32 v169, 0xffff0000, v13
	v_pk_fma_f32 v[176:177], v[166:167], v[166:167], v[176:177]
	v_pk_fma_f32 v[178:179], v[168:169], v[168:169], v[178:179]
	v_lshlrev_b32_e32 v162, 16, v14
	v_and_b32_e32 v163, 0xffff0000, v14
	v_lshlrev_b32_e32 v164, 16, v15
	v_and_b32_e32 v165, 0xffff0000, v15
	v_pk_fma_f32 v[176:177], v[162:163], v[162:163], v[176:177]
	v_pk_fma_f32 v[178:179], v[164:165], v[164:165], v[178:179]
	v_lshlrev_b32_e32 v166, 16, v16
	v_and_b32_e32 v167, 0xffff0000, v16
	v_lshlrev_b32_e32 v168, 16, v17
	v_and_b32_e32 v169, 0xffff0000, v17
	v_pk_fma_f32 v[176:177], v[166:167], v[166:167], v[176:177]
	v_pk_fma_f32 v[178:179], v[168:169], v[168:169], v[178:179]
	v_lshlrev_b32_e32 v162, 16, v18
	v_and_b32_e32 v163, 0xffff0000, v18
	v_lshlrev_b32_e32 v164, 16, v19
	v_and_b32_e32 v165, 0xffff0000, v19
	v_pk_fma_f32 v[176:177], v[162:163], v[162:163], v[176:177]
	v_pk_fma_f32 v[178:179], v[164:165], v[164:165], v[178:179]
	v_lshlrev_b32_e32 v166, 16, v20
	v_and_b32_e32 v167, 0xffff0000, v20
	v_lshlrev_b32_e32 v168, 16, v21
	v_and_b32_e32 v169, 0xffff0000, v21
	v_pk_fma_f32 v[176:177], v[166:167], v[166:167], v[176:177]
	v_pk_fma_f32 v[178:179], v[168:169], v[168:169], v[178:179]
	v_lshlrev_b32_e32 v162, 16, v22
	v_and_b32_e32 v163, 0xffff0000, v22
	v_lshlrev_b32_e32 v164, 16, v23
	v_and_b32_e32 v165, 0xffff0000, v23
	v_pk_fma_f32 v[176:177], v[162:163], v[162:163], v[176:177]
	v_pk_fma_f32 v[178:179], v[164:165], v[164:165], v[178:179]
	v_lshlrev_b32_e32 v166, 16, v24
	v_and_b32_e32 v167, 0xffff0000, v24
	v_lshlrev_b32_e32 v168, 16, v25
	v_and_b32_e32 v169, 0xffff0000, v25
	v_pk_fma_f32 v[176:177], v[166:167], v[166:167], v[176:177]
	v_pk_fma_f32 v[178:179], v[168:169], v[168:169], v[178:179]
	v_lshlrev_b32_e32 v162, 16, v26
	v_and_b32_e32 v163, 0xffff0000, v26
	v_lshlrev_b32_e32 v164, 16, v27
	v_and_b32_e32 v165, 0xffff0000, v27
	v_pk_fma_f32 v[176:177], v[162:163], v[162:163], v[176:177]
	v_pk_fma_f32 v[178:179], v[164:165], v[164:165], v[178:179]
	v_lshlrev_b32_e32 v166, 16, v28
	v_and_b32_e32 v167, 0xffff0000, v28
	v_lshlrev_b32_e32 v168, 16, v29
	v_and_b32_e32 v169, 0xffff0000, v29
	v_pk_fma_f32 v[176:177], v[166:167], v[166:167], v[176:177]
	v_pk_fma_f32 v[178:179], v[168:169], v[168:169], v[178:179]
	v_lshlrev_b32_e32 v162, 16, v30
	v_and_b32_e32 v163, 0xffff0000, v30
	v_lshlrev_b32_e32 v164, 16, v31
	v_and_b32_e32 v165, 0xffff0000, v31
	v_pk_fma_f32 v[176:177], v[162:163], v[162:163], v[176:177]
	v_pk_fma_f32 v[178:179], v[164:165], v[164:165], v[178:179]
	v_lshlrev_b32_e32 v166, 16, v32
	v_and_b32_e32 v167, 0xffff0000, v32
	v_lshlrev_b32_e32 v168, 16, v33
	v_and_b32_e32 v169, 0xffff0000, v33
	v_pk_fma_f32 v[176:177], v[166:167], v[166:167], v[176:177]
	v_pk_fma_f32 v[178:179], v[168:169], v[168:169], v[178:179]
	v_pk_add_f32 v[176:177], v[176:177], v[178:179]
	s_nop 0
	v_add_f32_e32 v252, v176, v177
	s_waitcnt lgkmcnt(0)
	ds_bpermute_b32 v254, v246, v252
	s_waitcnt lgkmcnt(0)
	v_add_f32_e32 v252, v252, v254
	ds_bpermute_b32 v254, v247, v252
	s_waitcnt lgkmcnt(0)
	v_add_f32_e32 v252, v252, v254
	ds_bpermute_b32 v254, v248, v252
	s_waitcnt lgkmcnt(0)
	v_add_f32_e32 v252, v252, v254
	ds_bpermute_b32 v254, v249, v252
	s_waitcnt lgkmcnt(0)
	v_add_f32_e32 v252, v252, v254
	ds_bpermute_b32 v254, v250, v252
	s_waitcnt lgkmcnt(0)
	v_add_f32_e32 v252, v252, v254
	ds_bpermute_b32 v254, v251, v252
	s_waitcnt lgkmcnt(0)
	v_add_f32_e32 v252, v252, v254
	v_mov_b32_e32 v254, 0x358637bd
	v_fmac_f32_e32 v254, 0x39800000, v252
	v_mul_f32_e32 v252, 0x4b800000, v254
	v_cmp_gt_f32_e32 vcc, s20, v254
	s_nop 1
	v_cndmask_b32_e32 v254, v254, v252, vcc
	v_rsq_f32_e32 v254, v254
	s_nop 0
	v_mul_f32_e32 v252, 0x45800000, v254
	v_cndmask_b32_e32 v252, v254, v252, vcc
	ds_read_b128 v[146:149], v238 offset:2048
	ds_read_b128 v[150:153], v238 offset:18432
	ds_read_b128 v[154:157], v238 offset:3072
	ds_read_b128 v[158:161], v238 offset:19456
	s_waitcnt lgkmcnt(4)
	v_lshlrev_b32_e32 v162, 16, v2
	v_and_b32_e32 v163, 0xffff0000, v2
	v_lshlrev_b32_e32 v164, 16, v3
	v_and_b32_e32 v165, 0xffff0000, v3
	v_lshlrev_b32_e32 v166, 16, v34
	v_and_b32_e32 v167, 0xffff0000, v34
	v_lshlrev_b32_e32 v168, 16, v35
	v_and_b32_e32 v169, 0xffff0000, v35
	v_pk_mul_f32 v[162:163], v[162:163], v[252:253] op_sel_hi:[1,0]
	v_pk_mul_f32 v[164:165], v[164:165], v[252:253] op_sel_hi:[1,0]
	v_pk_mul_f32 v[162:163], v[162:163], v[130:131]
	v_pk_mul_f32 v[164:165], v[164:165], v[132:133]
	v_pk_fma_f32 v[162:163], v[134:135], v[162:163], v[166:167]
	v_pk_fma_f32 v[164:165], v[136:137], v[164:165], v[168:169]
	s_nop 0
	global_store_dwordx4 v238, v[162:165], s[30:31] offset:0 nt
	s_nop 1
	v_lshlrev_b32_e32 v162, 16, v4
	v_and_b32_e32 v163, 0xffff0000, v4
	v_lshlrev_b32_e32 v164, 16, v5
	v_and_b32_e32 v165, 0xffff0000, v5
	v_lshlrev_b32_e32 v166, 16, v36
	v_and_b32_e32 v167, 0xffff0000, v36
	v_lshlrev_b32_e32 v168, 16, v37
	v_and_b32_e32 v169, 0xffff0000, v37
	v_pk_mul_f32 v[162:163], v[162:163], v[252:253] op_sel_hi:[1,0]
	v_pk_mul_f32 v[164:165], v[164:165], v[252:253] op_sel_hi:[1,0]
	v_pk_mul_f32 v[162:163], v[162:163], v[138:139]
	v_pk_mul_f32 v[164:165], v[164:165], v[140:141]
	v_pk_fma_f32 v[162:163], v[142:143], v[162:163], v[166:167]
	v_pk_fma_f32 v[164:165], v[144:145], v[164:165], v[168:169]
	s_nop 0
	global_store_dwordx4 v238, v[162:165], s[30:31] offset:1024 nt
	s_nop 1
	ds_read_b128 v[130:133], v238 offset:4096
	ds_read_b128 v[134:137], v238 offset:20480
	ds_read_b128 v[138:141], v238 offset:5120
	ds_read_b128 v[142:145], v238 offset:21504
	s_waitcnt lgkmcnt(4)
	v_lshlrev_b32_e32 v162, 16, v6
	v_and_b32_e32 v163, 0xffff0000, v6
	v_lshlrev_b32_e32 v164, 16, v7
	v_and_b32_e32 v165, 0xffff0000, v7
	v_lshlrev_b32_e32 v166, 16, v38
	v_and_b32_e32 v167, 0xffff0000, v38
	v_lshlrev_b32_e32 v168, 16, v39
	v_and_b32_e32 v169, 0xffff0000, v39
	v_pk_mul_f32 v[162:163], v[162:163], v[252:253] op_sel_hi:[1,0]
	v_pk_mul_f32 v[164:165], v[164:165], v[252:253] op_sel_hi:[1,0]
	v_pk_mul_f32 v[162:163], v[162:163], v[146:147]
	v_pk_mul_f32 v[164:165], v[164:165], v[148:149]
	v_pk_fma_f32 v[162:163], v[150:151], v[162:163], v[166:167]
	v_pk_fma_f32 v[164:165], v[152:153], v[164:165], v[168:169]
	s_nop 0
	global_store_dwordx4 v238, v[162:165], s[30:31] offset:2048 nt
	s_nop 1
	v_lshlrev_b32_e32 v162, 16, v8
	v_and_b32_e32 v163, 0xffff0000, v8
	v_lshlrev_b32_e32 v164, 16, v9
	v_and_b32_e32 v165, 0xffff0000, v9
	v_lshlrev_b32_e32 v166, 16, v40
	v_and_b32_e32 v167, 0xffff0000, v40
	v_lshlrev_b32_e32 v168, 16, v41
	v_and_b32_e32 v169, 0xffff0000, v41
	v_pk_mul_f32 v[162:163], v[162:163], v[252:253] op_sel_hi:[1,0]
	v_pk_mul_f32 v[164:165], v[164:165], v[252:253] op_sel_hi:[1,0]
	v_pk_mul_f32 v[162:163], v[162:163], v[154:155]
	v_pk_mul_f32 v[164:165], v[164:165], v[156:157]
	v_pk_fma_f32 v[162:163], v[158:159], v[162:163], v[166:167]
	v_pk_fma_f32 v[164:165], v[160:161], v[164:165], v[168:169]
	s_nop 0
	global_store_dwordx4 v238, v[162:165], s[30:31] offset:3072 nt
	s_nop 1
	ds_read_b128 v[146:149], v238 offset:6144
	ds_read_b128 v[150:153], v238 offset:22528
	ds_read_b128 v[154:157], v238 offset:7168
	ds_read_b128 v[158:161], v238 offset:23552
	s_waitcnt lgkmcnt(4)
	v_lshlrev_b32_e32 v162, 16, v10
	v_and_b32_e32 v163, 0xffff0000, v10
	v_lshlrev_b32_e32 v164, 16, v11
	v_and_b32_e32 v165, 0xffff0000, v11
	v_lshlrev_b32_e32 v166, 16, v42
	v_and_b32_e32 v167, 0xffff0000, v42
	v_lshlrev_b32_e32 v168, 16, v43
	v_and_b32_e32 v169, 0xffff0000, v43
	v_pk_mul_f32 v[162:163], v[162:163], v[252:253] op_sel_hi:[1,0]
	v_pk_mul_f32 v[164:165], v[164:165], v[252:253] op_sel_hi:[1,0]
	v_pk_mul_f32 v[162:163], v[162:163], v[130:131]
	v_pk_mul_f32 v[164:165], v[164:165], v[132:133]
	v_pk_fma_f32 v[162:163], v[134:135], v[162:163], v[166:167]
	v_pk_fma_f32 v[164:165], v[136:137], v[164:165], v[168:169]
	s_nop 0
	global_store_dwordx4 v241, v[162:165], s[30:31] offset:0 nt
	s_nop 1
	v_lshlrev_b32_e32 v162, 16, v12
	v_and_b32_e32 v163, 0xffff0000, v12
	v_lshlrev_b32_e32 v164, 16, v13
	v_and_b32_e32 v165, 0xffff0000, v13
	v_lshlrev_b32_e32 v166, 16, v44
	v_and_b32_e32 v167, 0xffff0000, v44
	v_lshlrev_b32_e32 v168, 16, v45
	v_and_b32_e32 v169, 0xffff0000, v45
	v_pk_mul_f32 v[162:163], v[162:163], v[252:253] op_sel_hi:[1,0]
	v_pk_mul_f32 v[164:165], v[164:165], v[252:253] op_sel_hi:[1,0]
	v_pk_mul_f32 v[162:163], v[162:163], v[138:139]
	v_pk_mul_f32 v[164:165], v[164:165], v[140:141]
	v_pk_fma_f32 v[162:163], v[142:143], v[162:163], v[166:167]
	v_pk_fma_f32 v[164:165], v[144:145], v[164:165], v[168:169]
	s_nop 0
	global_store_dwordx4 v241, v[162:165], s[30:31] offset:1024 nt
	s_nop 1
	ds_read_b128 v[130:133], v238 offset:8192
	ds_read_b128 v[134:137], v238 offset:24576
	ds_read_b128 v[138:141], v238 offset:9216
	ds_read_b128 v[142:145], v238 offset:25600
	s_waitcnt lgkmcnt(4)
	v_lshlrev_b32_e32 v162, 16, v14
	v_and_b32_e32 v163, 0xffff0000, v14
	v_lshlrev_b32_e32 v164, 16, v15
	v_and_b32_e32 v165, 0xffff0000, v15
	v_lshlrev_b32_e32 v166, 16, v46
	v_and_b32_e32 v167, 0xffff0000, v46
	v_lshlrev_b32_e32 v168, 16, v47
	v_and_b32_e32 v169, 0xffff0000, v47
	v_pk_mul_f32 v[162:163], v[162:163], v[252:253] op_sel_hi:[1,0]
	v_pk_mul_f32 v[164:165], v[164:165], v[252:253] op_sel_hi:[1,0]
	v_pk_mul_f32 v[162:163], v[162:163], v[146:147]
	v_pk_mul_f32 v[164:165], v[164:165], v[148:149]
	v_pk_fma_f32 v[162:163], v[150:151], v[162:163], v[166:167]
	v_pk_fma_f32 v[164:165], v[152:153], v[164:165], v[168:169]
	s_nop 0
	global_store_dwordx4 v241, v[162:165], s[30:31] offset:2048 nt
	s_nop 1
	v_lshlrev_b32_e32 v162, 16, v16
	v_and_b32_e32 v163, 0xffff0000, v16
	v_lshlrev_b32_e32 v164, 16, v17
	v_and_b32_e32 v165, 0xffff0000, v17
	v_lshlrev_b32_e32 v166, 16, v48
	v_and_b32_e32 v167, 0xffff0000, v48
	v_lshlrev_b32_e32 v168, 16, v49
	v_and_b32_e32 v169, 0xffff0000, v49
	v_pk_mul_f32 v[162:163], v[162:163], v[252:253] op_sel_hi:[1,0]
	v_pk_mul_f32 v[164:165], v[164:165], v[252:253] op_sel_hi:[1,0]
	v_pk_mul_f32 v[162:163], v[162:163], v[154:155]
	v_pk_mul_f32 v[164:165], v[164:165], v[156:157]
	v_pk_fma_f32 v[162:163], v[158:159], v[162:163], v[166:167]
	v_pk_fma_f32 v[164:165], v[160:161], v[164:165], v[168:169]
	s_nop 0
	global_store_dwordx4 v241, v[162:165], s[30:31] offset:3072 nt
	s_nop 1
	ds_read_b128 v[146:149], v238 offset:10240
	ds_read_b128 v[150:153], v238 offset:26624
	ds_read_b128 v[154:157], v238 offset:11264
	ds_read_b128 v[158:161], v238 offset:27648
	s_waitcnt lgkmcnt(4)
	v_lshlrev_b32_e32 v162, 16, v18
	v_and_b32_e32 v163, 0xffff0000, v18
	v_lshlrev_b32_e32 v164, 16, v19
	v_and_b32_e32 v165, 0xffff0000, v19
	v_lshlrev_b32_e32 v166, 16, v50
	v_and_b32_e32 v167, 0xffff0000, v50
	v_lshlrev_b32_e32 v168, 16, v51
	v_and_b32_e32 v169, 0xffff0000, v51
	v_pk_mul_f32 v[162:163], v[162:163], v[252:253] op_sel_hi:[1,0]
	v_pk_mul_f32 v[164:165], v[164:165], v[252:253] op_sel_hi:[1,0]
	v_pk_mul_f32 v[162:163], v[162:163], v[130:131]
	v_pk_mul_f32 v[164:165], v[164:165], v[132:133]
	v_pk_fma_f32 v[162:163], v[134:135], v[162:163], v[166:167]
	v_pk_fma_f32 v[164:165], v[136:137], v[164:165], v[168:169]
	s_nop 0
	global_store_dwordx4 v242, v[162:165], s[30:31] offset:0 nt
	s_nop 1
	v_lshlrev_b32_e32 v162, 16, v20
	v_and_b32_e32 v163, 0xffff0000, v20
	v_lshlrev_b32_e32 v164, 16, v21
	v_and_b32_e32 v165, 0xffff0000, v21
	v_lshlrev_b32_e32 v166, 16, v52
	v_and_b32_e32 v167, 0xffff0000, v52
	v_lshlrev_b32_e32 v168, 16, v53
	v_and_b32_e32 v169, 0xffff0000, v53
	v_pk_mul_f32 v[162:163], v[162:163], v[252:253] op_sel_hi:[1,0]
	v_pk_mul_f32 v[164:165], v[164:165], v[252:253] op_sel_hi:[1,0]
	v_pk_mul_f32 v[162:163], v[162:163], v[138:139]
	v_pk_mul_f32 v[164:165], v[164:165], v[140:141]
	v_pk_fma_f32 v[162:163], v[142:143], v[162:163], v[166:167]
	v_pk_fma_f32 v[164:165], v[144:145], v[164:165], v[168:169]
	s_nop 0
	global_store_dwordx4 v242, v[162:165], s[30:31] offset:1024 nt
	s_nop 1
	ds_read_b128 v[130:133], v238 offset:12288
	ds_read_b128 v[134:137], v238 offset:28672
	ds_read_b128 v[138:141], v238 offset:13312
	ds_read_b128 v[142:145], v238 offset:29696
	s_waitcnt lgkmcnt(4)
	v_lshlrev_b32_e32 v162, 16, v22
	v_and_b32_e32 v163, 0xffff0000, v22
	v_lshlrev_b32_e32 v164, 16, v23
	v_and_b32_e32 v165, 0xffff0000, v23
	v_lshlrev_b32_e32 v166, 16, v54
	v_and_b32_e32 v167, 0xffff0000, v54
	v_lshlrev_b32_e32 v168, 16, v55
	v_and_b32_e32 v169, 0xffff0000, v55
	v_pk_mul_f32 v[162:163], v[162:163], v[252:253] op_sel_hi:[1,0]
	v_pk_mul_f32 v[164:165], v[164:165], v[252:253] op_sel_hi:[1,0]
	v_pk_mul_f32 v[162:163], v[162:163], v[146:147]
	v_pk_mul_f32 v[164:165], v[164:165], v[148:149]
	v_pk_fma_f32 v[162:163], v[150:151], v[162:163], v[166:167]
	v_pk_fma_f32 v[164:165], v[152:153], v[164:165], v[168:169]
	s_nop 0
	global_store_dwordx4 v242, v[162:165], s[30:31] offset:2048 nt
	s_nop 1
	v_lshlrev_b32_e32 v162, 16, v24
	v_and_b32_e32 v163, 0xffff0000, v24
	v_lshlrev_b32_e32 v164, 16, v25
	v_and_b32_e32 v165, 0xffff0000, v25
	v_lshlrev_b32_e32 v166, 16, v56
	v_and_b32_e32 v167, 0xffff0000, v56
	v_lshlrev_b32_e32 v168, 16, v57
	v_and_b32_e32 v169, 0xffff0000, v57
	v_pk_mul_f32 v[162:163], v[162:163], v[252:253] op_sel_hi:[1,0]
	v_pk_mul_f32 v[164:165], v[164:165], v[252:253] op_sel_hi:[1,0]
	v_pk_mul_f32 v[162:163], v[162:163], v[154:155]
	v_pk_mul_f32 v[164:165], v[164:165], v[156:157]
	v_pk_fma_f32 v[162:163], v[158:159], v[162:163], v[166:167]
	v_pk_fma_f32 v[164:165], v[160:161], v[164:165], v[168:169]
	s_nop 0
	global_store_dwordx4 v242, v[162:165], s[30:31] offset:3072 nt
	s_nop 1
	ds_read_b128 v[146:149], v238 offset:14336
	ds_read_b128 v[150:153], v238 offset:30720
	ds_read_b128 v[154:157], v238 offset:15360
	ds_read_b128 v[158:161], v238 offset:31744
	s_waitcnt lgkmcnt(4)
	v_lshlrev_b32_e32 v162, 16, v26
	v_and_b32_e32 v163, 0xffff0000, v26
	v_lshlrev_b32_e32 v164, 16, v27
	v_and_b32_e32 v165, 0xffff0000, v27
	v_lshlrev_b32_e32 v166, 16, v58
	v_and_b32_e32 v167, 0xffff0000, v58
	v_lshlrev_b32_e32 v168, 16, v59
	v_and_b32_e32 v169, 0xffff0000, v59
	v_pk_mul_f32 v[162:163], v[162:163], v[252:253] op_sel_hi:[1,0]
	v_pk_mul_f32 v[164:165], v[164:165], v[252:253] op_sel_hi:[1,0]
	v_pk_mul_f32 v[162:163], v[162:163], v[130:131]
	v_pk_mul_f32 v[164:165], v[164:165], v[132:133]
	v_pk_fma_f32 v[162:163], v[134:135], v[162:163], v[166:167]
	v_pk_fma_f32 v[164:165], v[136:137], v[164:165], v[168:169]
	s_nop 0
	global_store_dwordx4 v243, v[162:165], s[30:31] offset:0 nt
	s_nop 1
	v_lshlrev_b32_e32 v162, 16, v28
	v_and_b32_e32 v163, 0xffff0000, v28
	v_lshlrev_b32_e32 v164, 16, v29
	v_and_b32_e32 v165, 0xffff0000, v29
	v_lshlrev_b32_e32 v166, 16, v60
	v_and_b32_e32 v167, 0xffff0000, v60
	v_lshlrev_b32_e32 v168, 16, v61
	v_and_b32_e32 v169, 0xffff0000, v61
	v_pk_mul_f32 v[162:163], v[162:163], v[252:253] op_sel_hi:[1,0]
	v_pk_mul_f32 v[164:165], v[164:165], v[252:253] op_sel_hi:[1,0]
	v_pk_mul_f32 v[162:163], v[162:163], v[138:139]
	v_pk_mul_f32 v[164:165], v[164:165], v[140:141]
	v_pk_fma_f32 v[162:163], v[142:143], v[162:163], v[166:167]
	v_pk_fma_f32 v[164:165], v[144:145], v[164:165], v[168:169]
	s_nop 0
	global_store_dwordx4 v243, v[162:165], s[30:31] offset:1024 nt
	s_nop 1
	s_waitcnt lgkmcnt(0)
	v_lshlrev_b32_e32 v162, 16, v30
	v_and_b32_e32 v163, 0xffff0000, v30
	v_lshlrev_b32_e32 v164, 16, v31
	v_and_b32_e32 v165, 0xffff0000, v31
	v_lshlrev_b32_e32 v166, 16, v62
	v_and_b32_e32 v167, 0xffff0000, v62
	v_lshlrev_b32_e32 v168, 16, v63
	v_and_b32_e32 v169, 0xffff0000, v63
	v_pk_mul_f32 v[162:163], v[162:163], v[252:253] op_sel_hi:[1,0]
	v_pk_mul_f32 v[164:165], v[164:165], v[252:253] op_sel_hi:[1,0]
	v_pk_mul_f32 v[162:163], v[162:163], v[146:147]
	v_pk_mul_f32 v[164:165], v[164:165], v[148:149]
	v_pk_fma_f32 v[162:163], v[150:151], v[162:163], v[166:167]
	v_pk_fma_f32 v[164:165], v[152:153], v[164:165], v[168:169]
	s_nop 0
	global_store_dwordx4 v243, v[162:165], s[30:31] offset:2048 nt
	s_nop 1
	v_lshlrev_b32_e32 v162, 16, v32
	v_and_b32_e32 v163, 0xffff0000, v32
	v_lshlrev_b32_e32 v164, 16, v33
	v_and_b32_e32 v165, 0xffff0000, v33
	v_lshlrev_b32_e32 v166, 16, v64
	v_and_b32_e32 v167, 0xffff0000, v64
	v_lshlrev_b32_e32 v168, 16, v65
	v_and_b32_e32 v169, 0xffff0000, v65
	v_pk_mul_f32 v[162:163], v[162:163], v[252:253] op_sel_hi:[1,0]
	v_pk_mul_f32 v[164:165], v[164:165], v[252:253] op_sel_hi:[1,0]
	v_pk_mul_f32 v[162:163], v[162:163], v[154:155]
	v_pk_mul_f32 v[164:165], v[164:165], v[156:157]
	v_pk_fma_f32 v[162:163], v[158:159], v[162:163], v[166:167]
	v_pk_fma_f32 v[164:165], v[160:161], v[164:165], v[168:169]
	s_nop 0
	global_store_dwordx4 v243, v[162:165], s[30:31] offset:3072 nt
	s_nop 1
	s_add_u32 s30, s30, 0x2000000
	s_addc_u32 s31, s31, 0
	s_waitcnt vmcnt(16)
	s_add_u32 s22, s22, 0x1000000
	s_addc_u32 s23, s23, 0
	s_add_u32 s24, s24, 0x1000000
	s_addc_u32 s25, s25, 0
	global_load_dwordx2 v[2:3], v244, s[22:23] offset:0
	global_load_dwordx2 v[4:5], v244, s[22:23] offset:512
	global_load_dwordx2 v[6:7], v244, s[22:23] offset:1024
	global_load_dwordx2 v[8:9], v244, s[22:23] offset:1536
	global_load_dwordx2 v[10:11], v244, s[22:23] offset:2048
	global_load_dwordx2 v[12:13], v244, s[22:23] offset:2560
	global_load_dwordx2 v[14:15], v244, s[22:23] offset:3072
	global_load_dwordx2 v[16:17], v244, s[22:23] offset:3584
	global_load_dwordx2 v[18:19], v245, s[22:23] offset:0
	global_load_dwordx2 v[20:21], v245, s[22:23] offset:512
	global_load_dwordx2 v[22:23], v245, s[22:23] offset:1024
	global_load_dwordx2 v[24:25], v245, s[22:23] offset:1536
	global_load_dwordx2 v[26:27], v245, s[22:23] offset:2048
	global_load_dwordx2 v[28:29], v245, s[22:23] offset:2560
	global_load_dwordx2 v[30:31], v245, s[22:23] offset:3072
	global_load_dwordx2 v[32:33], v245, s[22:23] offset:3584
	global_load_dwordx2 v[34:35], v244, s[24:25] offset:0
	global_load_dwordx2 v[36:37], v244, s[24:25] offset:512
	global_load_dwordx2 v[38:39], v244, s[24:25] offset:1024
	global_load_dwordx2 v[40:41], v244, s[24:25] offset:1536
	global_load_dwordx2 v[42:43], v244, s[24:25] offset:2048
	global_load_dwordx2 v[44:45], v244, s[24:25] offset:2560
	global_load_dwordx2 v[46:47], v244, s[24:25] offset:3072
	global_load_dwordx2 v[48:49], v244, s[24:25] offset:3584
	global_load_dwordx2 v[50:51], v245, s[24:25] offset:0
	global_load_dwordx2 v[52:53], v245, s[24:25] offset:512
	global_load_dwordx2 v[54:55], v245, s[24:25] offset:1024
	global_load_dwordx2 v[56:57], v245, s[24:25] offset:1536
	global_load_dwordx2 v[58:59], v245, s[24:25] offset:2048
	global_load_dwordx2 v[60:61], v245, s[24:25] offset:2560
	global_load_dwordx2 v[62:63], v245, s[24:25] offset:3072
	global_load_dwordx2 v[64:65], v245, s[24:25] offset:3584
	ds_read_b128 v[130:133], v238 offset:0
	ds_read_b128 v[134:137], v238 offset:16384
	ds_read_b128 v[138:141], v238 offset:1024
	ds_read_b128 v[142:145], v238 offset:17408
	v_lshlrev_b32_e32 v162, 16, v66
	v_and_b32_e32 v163, 0xffff0000, v66
	v_lshlrev_b32_e32 v164, 16, v67
	v_and_b32_e32 v165, 0xffff0000, v67
	v_pk_mul_f32 v[176:177], v[162:163], v[162:163]
	v_pk_mul_f32 v[178:179], v[164:165], v[164:165]
	v_lshlrev_b32_e32 v166, 16, v68
	v_and_b32_e32 v167, 0xffff0000, v68
	v_lshlrev_b32_e32 v168, 16, v69
	v_and_b32_e32 v169, 0xffff0000, v69
	v_pk_fma_f32 v[176:177], v[166:167], v[166:167], v[176:177]
	v_pk_fma_f32 v[178:179], v[168:169], v[168:169], v[178:179]
	v_lshlrev_b32_e32 v162, 16, v70
	v_and_b32_e32 v163, 0xffff0000, v70
	v_lshlrev_b32_e32 v164, 16, v71
	v_and_b32_e32 v165, 0xffff0000, v71
	v_pk_fma_f32 v[176:177], v[162:163], v[162:163], v[176:177]
	v_pk_fma_f32 v[178:179], v[164:165], v[164:165], v[178:179]
	v_lshlrev_b32_e32 v166, 16, v72
	v_and_b32_e32 v167, 0xffff0000, v72
	v_lshlrev_b32_e32 v168, 16, v73
	v_and_b32_e32 v169, 0xffff0000, v73
	v_pk_fma_f32 v[176:177], v[166:167], v[166:167], v[176:177]
	v_pk_fma_f32 v[178:179], v[168:169], v[168:169], v[178:179]
	v_lshlrev_b32_e32 v162, 16, v74
	v_and_b32_e32 v163, 0xffff0000, v74
	v_lshlrev_b32_e32 v164, 16, v75
	v_and_b32_e32 v165, 0xffff0000, v75
	v_pk_fma_f32 v[176:177], v[162:163], v[162:163], v[176:177]
	v_pk_fma_f32 v[178:179], v[164:165], v[164:165], v[178:179]
	v_lshlrev_b32_e32 v166, 16, v76
	v_and_b32_e32 v167, 0xffff0000, v76
	v_lshlrev_b32_e32 v168, 16, v77
	v_and_b32_e32 v169, 0xffff0000, v77
	v_pk_fma_f32 v[176:177], v[166:167], v[166:167], v[176:177]
	v_pk_fma_f32 v[178:179], v[168:169], v[168:169], v[178:179]
	v_lshlrev_b32_e32 v162, 16, v78
	v_and_b32_e32 v163, 0xffff0000, v78
	v_lshlrev_b32_e32 v164, 16, v79
	v_and_b32_e32 v165, 0xffff0000, v79
	v_pk_fma_f32 v[176:177], v[162:163], v[162:163], v[176:177]
	v_pk_fma_f32 v[178:179], v[164:165], v[164:165], v[178:179]
	v_lshlrev_b32_e32 v166, 16, v80
	v_and_b32_e32 v167, 0xffff0000, v80
	v_lshlrev_b32_e32 v168, 16, v81
	v_and_b32_e32 v169, 0xffff0000, v81
	v_pk_fma_f32 v[176:177], v[166:167], v[166:167], v[176:177]
	v_pk_fma_f32 v[178:179], v[168:169], v[168:169], v[178:179]
	v_lshlrev_b32_e32 v162, 16, v82
	v_and_b32_e32 v163, 0xffff0000, v82
	v_lshlrev_b32_e32 v164, 16, v83
	v_and_b32_e32 v165, 0xffff0000, v83
	v_pk_fma_f32 v[176:177], v[162:163], v[162:163], v[176:177]
	v_pk_fma_f32 v[178:179], v[164:165], v[164:165], v[178:179]
	v_lshlrev_b32_e32 v166, 16, v84
	v_and_b32_e32 v167, 0xffff0000, v84
	v_lshlrev_b32_e32 v168, 16, v85
	v_and_b32_e32 v169, 0xffff0000, v85
	v_pk_fma_f32 v[176:177], v[166:167], v[166:167], v[176:177]
	v_pk_fma_f32 v[178:179], v[168:169], v[168:169], v[178:179]
	v_lshlrev_b32_e32 v162, 16, v86
	v_and_b32_e32 v163, 0xffff0000, v86
	v_lshlrev_b32_e32 v164, 16, v87
	v_and_b32_e32 v165, 0xffff0000, v87
	v_pk_fma_f32 v[176:177], v[162:163], v[162:163], v[176:177]
	v_pk_fma_f32 v[178:179], v[164:165], v[164:165], v[178:179]
	v_lshlrev_b32_e32 v166, 16, v88
	v_and_b32_e32 v167, 0xffff0000, v88
	v_lshlrev_b32_e32 v168, 16, v89
	v_and_b32_e32 v169, 0xffff0000, v89
	v_pk_fma_f32 v[176:177], v[166:167], v[166:167], v[176:177]
	v_pk_fma_f32 v[178:179], v[168:169], v[168:169], v[178:179]
	v_lshlrev_b32_e32 v162, 16, v90
	v_and_b32_e32 v163, 0xffff0000, v90
	v_lshlrev_b32_e32 v164, 16, v91
	v_and_b32_e32 v165, 0xffff0000, v91
	v_pk_fma_f32 v[176:177], v[162:163], v[162:163], v[176:177]
	v_pk_fma_f32 v[178:179], v[164:165], v[164:165], v[178:179]
	v_lshlrev_b32_e32 v166, 16, v92
	v_and_b32_e32 v167, 0xffff0000, v92
	v_lshlrev_b32_e32 v168, 16, v93
	v_and_b32_e32 v169, 0xffff0000, v93
	v_pk_fma_f32 v[176:177], v[166:167], v[166:167], v[176:177]
	v_pk_fma_f32 v[178:179], v[168:169], v[168:169], v[178:179]
	v_lshlrev_b32_e32 v162, 16, v94
	v_and_b32_e32 v163, 0xffff0000, v94
	v_lshlrev_b32_e32 v164, 16, v95
	v_and_b32_e32 v165, 0xffff0000, v95
	v_pk_fma_f32 v[176:177], v[162:163], v[162:163], v[176:177]
	v_pk_fma_f32 v[178:179], v[164:165], v[164:165], v[178:179]
	v_lshlrev_b32_e32 v166, 16, v96
	v_and_b32_e32 v167, 0xffff0000, v96
	v_lshlrev_b32_e32 v168, 16, v97
	v_and_b32_e32 v169, 0xffff0000, v97
	v_pk_fma_f32 v[176:177], v[166:167], v[166:167], v[176:177]
	v_pk_fma_f32 v[178:179], v[168:169], v[168:169], v[178:179]
	v_pk_add_f32 v[176:177], v[176:177], v[178:179]
	s_nop 0
	v_add_f32_e32 v252, v176, v177
	s_waitcnt lgkmcnt(0)
	ds_bpermute_b32 v254, v246, v252
	s_waitcnt lgkmcnt(0)
	v_add_f32_e32 v252, v252, v254
	ds_bpermute_b32 v254, v247, v252
	s_waitcnt lgkmcnt(0)
	v_add_f32_e32 v252, v252, v254
	ds_bpermute_b32 v254, v248, v252
	s_waitcnt lgkmcnt(0)
	v_add_f32_e32 v252, v252, v254
	ds_bpermute_b32 v254, v249, v252
	s_waitcnt lgkmcnt(0)
	v_add_f32_e32 v252, v252, v254
	ds_bpermute_b32 v254, v250, v252
	s_waitcnt lgkmcnt(0)
	v_add_f32_e32 v252, v252, v254
	ds_bpermute_b32 v254, v251, v252
	s_waitcnt lgkmcnt(0)
	v_add_f32_e32 v252, v252, v254
	v_mov_b32_e32 v254, 0x358637bd
	v_fmac_f32_e32 v254, 0x39800000, v252
	v_mul_f32_e32 v252, 0x4b800000, v254
	v_cmp_gt_f32_e32 vcc, s20, v254
	s_nop 1
	v_cndmask_b32_e32 v254, v254, v252, vcc
	v_rsq_f32_e32 v254, v254
	s_nop 0
	v_mul_f32_e32 v252, 0x45800000, v254
	v_cndmask_b32_e32 v252, v254, v252, vcc
	ds_read_b128 v[146:149], v238 offset:2048
	ds_read_b128 v[150:153], v238 offset:18432
	ds_read_b128 v[154:157], v238 offset:3072
	ds_read_b128 v[158:161], v238 offset:19456
	s_waitcnt lgkmcnt(4)
	v_lshlrev_b32_e32 v162, 16, v66
	v_and_b32_e32 v163, 0xffff0000, v66
	v_lshlrev_b32_e32 v164, 16, v67
	v_and_b32_e32 v165, 0xffff0000, v67
	v_lshlrev_b32_e32 v166, 16, v98
	v_and_b32_e32 v167, 0xffff0000, v98
	v_lshlrev_b32_e32 v168, 16, v99
	v_and_b32_e32 v169, 0xffff0000, v99
	v_pk_mul_f32 v[162:163], v[162:163], v[252:253] op_sel_hi:[1,0]
	v_pk_mul_f32 v[164:165], v[164:165], v[252:253] op_sel_hi:[1,0]
	v_pk_mul_f32 v[162:163], v[162:163], v[130:131]
	v_pk_mul_f32 v[164:165], v[164:165], v[132:133]
	v_pk_fma_f32 v[162:163], v[134:135], v[162:163], v[166:167]
	v_pk_fma_f32 v[164:165], v[136:137], v[164:165], v[168:169]
	s_nop 0
	global_store_dwordx4 v238, v[162:165], s[30:31] offset:0 nt
	s_nop 1
	v_lshlrev_b32_e32 v162, 16, v68
	v_and_b32_e32 v163, 0xffff0000, v68
	v_lshlrev_b32_e32 v164, 16, v69
	v_and_b32_e32 v165, 0xffff0000, v69
	v_lshlrev_b32_e32 v166, 16, v100
	v_and_b32_e32 v167, 0xffff0000, v100
	v_lshlrev_b32_e32 v168, 16, v101
	v_and_b32_e32 v169, 0xffff0000, v101
	v_pk_mul_f32 v[162:163], v[162:163], v[252:253] op_sel_hi:[1,0]
	v_pk_mul_f32 v[164:165], v[164:165], v[252:253] op_sel_hi:[1,0]
	v_pk_mul_f32 v[162:163], v[162:163], v[138:139]
	v_pk_mul_f32 v[164:165], v[164:165], v[140:141]
	v_pk_fma_f32 v[162:163], v[142:143], v[162:163], v[166:167]
	v_pk_fma_f32 v[164:165], v[144:145], v[164:165], v[168:169]
	s_nop 0
	global_store_dwordx4 v238, v[162:165], s[30:31] offset:1024 nt
	s_nop 1
	ds_read_b128 v[130:133], v238 offset:4096
	ds_read_b128 v[134:137], v238 offset:20480
	ds_read_b128 v[138:141], v238 offset:5120
	ds_read_b128 v[142:145], v238 offset:21504
	s_waitcnt lgkmcnt(4)
	v_lshlrev_b32_e32 v162, 16, v70
	v_and_b32_e32 v163, 0xffff0000, v70
	v_lshlrev_b32_e32 v164, 16, v71
	v_and_b32_e32 v165, 0xffff0000, v71
	v_lshlrev_b32_e32 v166, 16, v102
	v_and_b32_e32 v167, 0xffff0000, v102
	v_lshlrev_b32_e32 v168, 16, v103
	v_and_b32_e32 v169, 0xffff0000, v103
	v_pk_mul_f32 v[162:163], v[162:163], v[252:253] op_sel_hi:[1,0]
	v_pk_mul_f32 v[164:165], v[164:165], v[252:253] op_sel_hi:[1,0]
	v_pk_mul_f32 v[162:163], v[162:163], v[146:147]
	v_pk_mul_f32 v[164:165], v[164:165], v[148:149]
	v_pk_fma_f32 v[162:163], v[150:151], v[162:163], v[166:167]
	v_pk_fma_f32 v[164:165], v[152:153], v[164:165], v[168:169]
	s_nop 0
	global_store_dwordx4 v238, v[162:165], s[30:31] offset:2048 nt
	s_nop 1
	v_lshlrev_b32_e32 v162, 16, v72
	v_and_b32_e32 v163, 0xffff0000, v72
	v_lshlrev_b32_e32 v164, 16, v73
	v_and_b32_e32 v165, 0xffff0000, v73
	v_lshlrev_b32_e32 v166, 16, v104
	v_and_b32_e32 v167, 0xffff0000, v104
	v_lshlrev_b32_e32 v168, 16, v105
	v_and_b32_e32 v169, 0xffff0000, v105
	v_pk_mul_f32 v[162:163], v[162:163], v[252:253] op_sel_hi:[1,0]
	v_pk_mul_f32 v[164:165], v[164:165], v[252:253] op_sel_hi:[1,0]
	v_pk_mul_f32 v[162:163], v[162:163], v[154:155]
	v_pk_mul_f32 v[164:165], v[164:165], v[156:157]
	v_pk_fma_f32 v[162:163], v[158:159], v[162:163], v[166:167]
	v_pk_fma_f32 v[164:165], v[160:161], v[164:165], v[168:169]
	s_nop 0
	global_store_dwordx4 v238, v[162:165], s[30:31] offset:3072 nt
	s_nop 1
	ds_read_b128 v[146:149], v238 offset:6144
	ds_read_b128 v[150:153], v238 offset:22528
	ds_read_b128 v[154:157], v238 offset:7168
	ds_read_b128 v[158:161], v238 offset:23552
	s_waitcnt lgkmcnt(4)
	v_lshlrev_b32_e32 v162, 16, v74
	v_and_b32_e32 v163, 0xffff0000, v74
	v_lshlrev_b32_e32 v164, 16, v75
	v_and_b32_e32 v165, 0xffff0000, v75
	v_lshlrev_b32_e32 v166, 16, v106
	v_and_b32_e32 v167, 0xffff0000, v106
	v_lshlrev_b32_e32 v168, 16, v107
	v_and_b32_e32 v169, 0xffff0000, v107
	v_pk_mul_f32 v[162:163], v[162:163], v[252:253] op_sel_hi:[1,0]
	v_pk_mul_f32 v[164:165], v[164:165], v[252:253] op_sel_hi:[1,0]
	v_pk_mul_f32 v[162:163], v[162:163], v[130:131]
	v_pk_mul_f32 v[164:165], v[164:165], v[132:133]
	v_pk_fma_f32 v[162:163], v[134:135], v[162:163], v[166:167]
	v_pk_fma_f32 v[164:165], v[136:137], v[164:165], v[168:169]
	s_nop 0
	global_store_dwordx4 v241, v[162:165], s[30:31] offset:0 nt
	s_nop 1
	v_lshlrev_b32_e32 v162, 16, v76
	v_and_b32_e32 v163, 0xffff0000, v76
	v_lshlrev_b32_e32 v164, 16, v77
	v_and_b32_e32 v165, 0xffff0000, v77
	v_lshlrev_b32_e32 v166, 16, v108
	v_and_b32_e32 v167, 0xffff0000, v108
	v_lshlrev_b32_e32 v168, 16, v109
	v_and_b32_e32 v169, 0xffff0000, v109
	v_pk_mul_f32 v[162:163], v[162:163], v[252:253] op_sel_hi:[1,0]
	v_pk_mul_f32 v[164:165], v[164:165], v[252:253] op_sel_hi:[1,0]
	v_pk_mul_f32 v[162:163], v[162:163], v[138:139]
	v_pk_mul_f32 v[164:165], v[164:165], v[140:141]
	v_pk_fma_f32 v[162:163], v[142:143], v[162:163], v[166:167]
	v_pk_fma_f32 v[164:165], v[144:145], v[164:165], v[168:169]
	s_nop 0
	global_store_dwordx4 v241, v[162:165], s[30:31] offset:1024 nt
	s_nop 1
	ds_read_b128 v[130:133], v238 offset:8192
	ds_read_b128 v[134:137], v238 offset:24576
	ds_read_b128 v[138:141], v238 offset:9216
	ds_read_b128 v[142:145], v238 offset:25600
	s_waitcnt lgkmcnt(4)
	v_lshlrev_b32_e32 v162, 16, v78
	v_and_b32_e32 v163, 0xffff0000, v78
	v_lshlrev_b32_e32 v164, 16, v79
	v_and_b32_e32 v165, 0xffff0000, v79
	v_lshlrev_b32_e32 v166, 16, v110
	v_and_b32_e32 v167, 0xffff0000, v110
	v_lshlrev_b32_e32 v168, 16, v111
	v_and_b32_e32 v169, 0xffff0000, v111
	v_pk_mul_f32 v[162:163], v[162:163], v[252:253] op_sel_hi:[1,0]
	v_pk_mul_f32 v[164:165], v[164:165], v[252:253] op_sel_hi:[1,0]
	v_pk_mul_f32 v[162:163], v[162:163], v[146:147]
	v_pk_mul_f32 v[164:165], v[164:165], v[148:149]
	v_pk_fma_f32 v[162:163], v[150:151], v[162:163], v[166:167]
	v_pk_fma_f32 v[164:165], v[152:153], v[164:165], v[168:169]
	s_nop 0
	global_store_dwordx4 v241, v[162:165], s[30:31] offset:2048 nt
	s_nop 1
	v_lshlrev_b32_e32 v162, 16, v80
	v_and_b32_e32 v163, 0xffff0000, v80
	v_lshlrev_b32_e32 v164, 16, v81
	v_and_b32_e32 v165, 0xffff0000, v81
	v_lshlrev_b32_e32 v166, 16, v112
	v_and_b32_e32 v167, 0xffff0000, v112
	v_lshlrev_b32_e32 v168, 16, v113
	v_and_b32_e32 v169, 0xffff0000, v113
	v_pk_mul_f32 v[162:163], v[162:163], v[252:253] op_sel_hi:[1,0]
	v_pk_mul_f32 v[164:165], v[164:165], v[252:253] op_sel_hi:[1,0]
	v_pk_mul_f32 v[162:163], v[162:163], v[154:155]
	v_pk_mul_f32 v[164:165], v[164:165], v[156:157]
	v_pk_fma_f32 v[162:163], v[158:159], v[162:163], v[166:167]
	v_pk_fma_f32 v[164:165], v[160:161], v[164:165], v[168:169]
	s_nop 0
	global_store_dwordx4 v241, v[162:165], s[30:31] offset:3072 nt
	s_nop 1
	ds_read_b128 v[146:149], v238 offset:10240
	ds_read_b128 v[150:153], v238 offset:26624
	ds_read_b128 v[154:157], v238 offset:11264
	ds_read_b128 v[158:161], v238 offset:27648
	s_waitcnt lgkmcnt(4)
	v_lshlrev_b32_e32 v162, 16, v82
	v_and_b32_e32 v163, 0xffff0000, v82
	v_lshlrev_b32_e32 v164, 16, v83
	v_and_b32_e32 v165, 0xffff0000, v83
	v_lshlrev_b32_e32 v166, 16, v114
	v_and_b32_e32 v167, 0xffff0000, v114
	v_lshlrev_b32_e32 v168, 16, v115
	v_and_b32_e32 v169, 0xffff0000, v115
	v_pk_mul_f32 v[162:163], v[162:163], v[252:253] op_sel_hi:[1,0]
	v_pk_mul_f32 v[164:165], v[164:165], v[252:253] op_sel_hi:[1,0]
	v_pk_mul_f32 v[162:163], v[162:163], v[130:131]
	v_pk_mul_f32 v[164:165], v[164:165], v[132:133]
	v_pk_fma_f32 v[162:163], v[134:135], v[162:163], v[166:167]
	v_pk_fma_f32 v[164:165], v[136:137], v[164:165], v[168:169]
	s_nop 0
	global_store_dwordx4 v242, v[162:165], s[30:31] offset:0 nt
	s_nop 1
	v_lshlrev_b32_e32 v162, 16, v84
	v_and_b32_e32 v163, 0xffff0000, v84
	v_lshlrev_b32_e32 v164, 16, v85
	v_and_b32_e32 v165, 0xffff0000, v85
	v_lshlrev_b32_e32 v166, 16, v116
	v_and_b32_e32 v167, 0xffff0000, v116
	v_lshlrev_b32_e32 v168, 16, v117
	v_and_b32_e32 v169, 0xffff0000, v117
	v_pk_mul_f32 v[162:163], v[162:163], v[252:253] op_sel_hi:[1,0]
	v_pk_mul_f32 v[164:165], v[164:165], v[252:253] op_sel_hi:[1,0]
	v_pk_mul_f32 v[162:163], v[162:163], v[138:139]
	v_pk_mul_f32 v[164:165], v[164:165], v[140:141]
	v_pk_fma_f32 v[162:163], v[142:143], v[162:163], v[166:167]
	v_pk_fma_f32 v[164:165], v[144:145], v[164:165], v[168:169]
	s_nop 0
	global_store_dwordx4 v242, v[162:165], s[30:31] offset:1024 nt
	s_nop 1
	ds_read_b128 v[130:133], v238 offset:12288
	ds_read_b128 v[134:137], v238 offset:28672
	ds_read_b128 v[138:141], v238 offset:13312
	ds_read_b128 v[142:145], v238 offset:29696
	s_waitcnt lgkmcnt(4)
	v_lshlrev_b32_e32 v162, 16, v86
	v_and_b32_e32 v163, 0xffff0000, v86
	v_lshlrev_b32_e32 v164, 16, v87
	v_and_b32_e32 v165, 0xffff0000, v87
	v_lshlrev_b32_e32 v166, 16, v118
	v_and_b32_e32 v167, 0xffff0000, v118
	v_lshlrev_b32_e32 v168, 16, v119
	v_and_b32_e32 v169, 0xffff0000, v119
	v_pk_mul_f32 v[162:163], v[162:163], v[252:253] op_sel_hi:[1,0]
	v_pk_mul_f32 v[164:165], v[164:165], v[252:253] op_sel_hi:[1,0]
	v_pk_mul_f32 v[162:163], v[162:163], v[146:147]
	v_pk_mul_f32 v[164:165], v[164:165], v[148:149]
	v_pk_fma_f32 v[162:163], v[150:151], v[162:163], v[166:167]
	v_pk_fma_f32 v[164:165], v[152:153], v[164:165], v[168:169]
	s_nop 0
	global_store_dwordx4 v242, v[162:165], s[30:31] offset:2048 nt
	s_nop 1
	v_lshlrev_b32_e32 v162, 16, v88
	v_and_b32_e32 v163, 0xffff0000, v88
	v_lshlrev_b32_e32 v164, 16, v89
	v_and_b32_e32 v165, 0xffff0000, v89
	v_lshlrev_b32_e32 v166, 16, v120
	v_and_b32_e32 v167, 0xffff0000, v120
	v_lshlrev_b32_e32 v168, 16, v121
	v_and_b32_e32 v169, 0xffff0000, v121
	v_pk_mul_f32 v[162:163], v[162:163], v[252:253] op_sel_hi:[1,0]
	v_pk_mul_f32 v[164:165], v[164:165], v[252:253] op_sel_hi:[1,0]
	v_pk_mul_f32 v[162:163], v[162:163], v[154:155]
	v_pk_mul_f32 v[164:165], v[164:165], v[156:157]
	v_pk_fma_f32 v[162:163], v[158:159], v[162:163], v[166:167]
	v_pk_fma_f32 v[164:165], v[160:161], v[164:165], v[168:169]
	s_nop 0
	global_store_dwordx4 v242, v[162:165], s[30:31] offset:3072 nt
	s_nop 1
	ds_read_b128 v[146:149], v238 offset:14336
	ds_read_b128 v[150:153], v238 offset:30720
	ds_read_b128 v[154:157], v238 offset:15360
	ds_read_b128 v[158:161], v238 offset:31744
	s_waitcnt lgkmcnt(4)
	v_lshlrev_b32_e32 v162, 16, v90
	v_and_b32_e32 v163, 0xffff0000, v90
	v_lshlrev_b32_e32 v164, 16, v91
	v_and_b32_e32 v165, 0xffff0000, v91
	v_lshlrev_b32_e32 v166, 16, v122
	v_and_b32_e32 v167, 0xffff0000, v122
	v_lshlrev_b32_e32 v168, 16, v123
	v_and_b32_e32 v169, 0xffff0000, v123
	v_pk_mul_f32 v[162:163], v[162:163], v[252:253] op_sel_hi:[1,0]
	v_pk_mul_f32 v[164:165], v[164:165], v[252:253] op_sel_hi:[1,0]
	v_pk_mul_f32 v[162:163], v[162:163], v[130:131]
	v_pk_mul_f32 v[164:165], v[164:165], v[132:133]
	v_pk_fma_f32 v[162:163], v[134:135], v[162:163], v[166:167]
	v_pk_fma_f32 v[164:165], v[136:137], v[164:165], v[168:169]
	s_nop 0
	global_store_dwordx4 v243, v[162:165], s[30:31] offset:0 nt
	s_nop 1
	v_lshlrev_b32_e32 v162, 16, v92
	v_and_b32_e32 v163, 0xffff0000, v92
	v_lshlrev_b32_e32 v164, 16, v93
	v_and_b32_e32 v165, 0xffff0000, v93
	v_lshlrev_b32_e32 v166, 16, v124
	v_and_b32_e32 v167, 0xffff0000, v124
	v_lshlrev_b32_e32 v168, 16, v125
	v_and_b32_e32 v169, 0xffff0000, v125
	v_pk_mul_f32 v[162:163], v[162:163], v[252:253] op_sel_hi:[1,0]
	v_pk_mul_f32 v[164:165], v[164:165], v[252:253] op_sel_hi:[1,0]
	v_pk_mul_f32 v[162:163], v[162:163], v[138:139]
	v_pk_mul_f32 v[164:165], v[164:165], v[140:141]
	v_pk_fma_f32 v[162:163], v[142:143], v[162:163], v[166:167]
	v_pk_fma_f32 v[164:165], v[144:145], v[164:165], v[168:169]
	s_nop 0
	global_store_dwordx4 v243, v[162:165], s[30:31] offset:1024 nt
	s_nop 1
	s_waitcnt lgkmcnt(0)
	v_lshlrev_b32_e32 v162, 16, v94
	v_and_b32_e32 v163, 0xffff0000, v94
	v_lshlrev_b32_e32 v164, 16, v95
	v_and_b32_e32 v165, 0xffff0000, v95
	v_lshlrev_b32_e32 v166, 16, v126
	v_and_b32_e32 v167, 0xffff0000, v126
	v_lshlrev_b32_e32 v168, 16, v127
	v_and_b32_e32 v169, 0xffff0000, v127
	v_pk_mul_f32 v[162:163], v[162:163], v[252:253] op_sel_hi:[1,0]
	v_pk_mul_f32 v[164:165], v[164:165], v[252:253] op_sel_hi:[1,0]
	v_pk_mul_f32 v[162:163], v[162:163], v[146:147]
	v_pk_mul_f32 v[164:165], v[164:165], v[148:149]
	v_pk_fma_f32 v[162:163], v[150:151], v[162:163], v[166:167]
	v_pk_fma_f32 v[164:165], v[152:153], v[164:165], v[168:169]
	s_nop 0
	global_store_dwordx4 v243, v[162:165], s[30:31] offset:2048 nt
	s_nop 1
	v_lshlrev_b32_e32 v162, 16, v96
	v_and_b32_e32 v163, 0xffff0000, v96
	v_lshlrev_b32_e32 v164, 16, v97
	v_and_b32_e32 v165, 0xffff0000, v97
	v_lshlrev_b32_e32 v166, 16, v128
	v_and_b32_e32 v167, 0xffff0000, v128
	v_lshlrev_b32_e32 v168, 16, v129
	v_and_b32_e32 v169, 0xffff0000, v129
	v_pk_mul_f32 v[162:163], v[162:163], v[252:253] op_sel_hi:[1,0]
	v_pk_mul_f32 v[164:165], v[164:165], v[252:253] op_sel_hi:[1,0]
	v_pk_mul_f32 v[162:163], v[162:163], v[154:155]
	v_pk_mul_f32 v[164:165], v[164:165], v[156:157]
	v_pk_fma_f32 v[162:163], v[158:159], v[162:163], v[166:167]
	v_pk_fma_f32 v[164:165], v[160:161], v[164:165], v[168:169]
	s_nop 0
	global_store_dwordx4 v243, v[162:165], s[30:31] offset:3072 nt
	s_nop 1
	s_add_u32 s30, s30, 0x2000000
	s_addc_u32 s31, s31, 0
	s_waitcnt vmcnt(16)
	s_add_u32 s22, s22, 0x1000000
	s_addc_u32 s23, s23, 0
	s_add_u32 s24, s24, 0x1000000
	s_addc_u32 s25, s25, 0
	global_load_dwordx2 v[66:67], v244, s[22:23] offset:0
	global_load_dwordx2 v[68:69], v244, s[22:23] offset:512
	global_load_dwordx2 v[70:71], v244, s[22:23] offset:1024
	global_load_dwordx2 v[72:73], v244, s[22:23] offset:1536
	global_load_dwordx2 v[74:75], v244, s[22:23] offset:2048
	global_load_dwordx2 v[76:77], v244, s[22:23] offset:2560
	global_load_dwordx2 v[78:79], v244, s[22:23] offset:3072
	global_load_dwordx2 v[80:81], v244, s[22:23] offset:3584
	global_load_dwordx2 v[82:83], v245, s[22:23] offset:0
	global_load_dwordx2 v[84:85], v245, s[22:23] offset:512
	global_load_dwordx2 v[86:87], v245, s[22:23] offset:1024
	global_load_dwordx2 v[88:89], v245, s[22:23] offset:1536
	global_load_dwordx2 v[90:91], v245, s[22:23] offset:2048
	global_load_dwordx2 v[92:93], v245, s[22:23] offset:2560
	global_load_dwordx2 v[94:95], v245, s[22:23] offset:3072
	global_load_dwordx2 v[96:97], v245, s[22:23] offset:3584
	global_load_dwordx2 v[98:99], v244, s[24:25] offset:0
	global_load_dwordx2 v[100:101], v244, s[24:25] offset:512
	global_load_dwordx2 v[102:103], v244, s[24:25] offset:1024
	global_load_dwordx2 v[104:105], v244, s[24:25] offset:1536
	global_load_dwordx2 v[106:107], v244, s[24:25] offset:2048
	global_load_dwordx2 v[108:109], v244, s[24:25] offset:2560
	global_load_dwordx2 v[110:111], v244, s[24:25] offset:3072
	global_load_dwordx2 v[112:113], v244, s[24:25] offset:3584
	global_load_dwordx2 v[114:115], v245, s[24:25] offset:0
	global_load_dwordx2 v[116:117], v245, s[24:25] offset:512
	global_load_dwordx2 v[118:119], v245, s[24:25] offset:1024
	global_load_dwordx2 v[120:121], v245, s[24:25] offset:1536
	global_load_dwordx2 v[122:123], v245, s[24:25] offset:2048
	global_load_dwordx2 v[124:125], v245, s[24:25] offset:2560
	global_load_dwordx2 v[126:127], v245, s[24:25] offset:3072
	global_load_dwordx2 v[128:129], v245, s[24:25] offset:3584
	ds_read_b128 v[130:133], v238 offset:0
	ds_read_b128 v[134:137], v238 offset:16384
	ds_read_b128 v[138:141], v238 offset:1024
	ds_read_b128 v[142:145], v238 offset:17408
	v_lshlrev_b32_e32 v162, 16, v2
	v_and_b32_e32 v163, 0xffff0000, v2
	v_lshlrev_b32_e32 v164, 16, v3
	v_and_b32_e32 v165, 0xffff0000, v3
	v_pk_mul_f32 v[176:177], v[162:163], v[162:163]
	v_pk_mul_f32 v[178:179], v[164:165], v[164:165]
	v_lshlrev_b32_e32 v166, 16, v4
	v_and_b32_e32 v167, 0xffff0000, v4
	v_lshlrev_b32_e32 v168, 16, v5
	v_and_b32_e32 v169, 0xffff0000, v5
	v_pk_fma_f32 v[176:177], v[166:167], v[166:167], v[176:177]
	v_pk_fma_f32 v[178:179], v[168:169], v[168:169], v[178:179]
	v_lshlrev_b32_e32 v162, 16, v6
	v_and_b32_e32 v163, 0xffff0000, v6
	v_lshlrev_b32_e32 v164, 16, v7
	v_and_b32_e32 v165, 0xffff0000, v7
	v_pk_fma_f32 v[176:177], v[162:163], v[162:163], v[176:177]
	v_pk_fma_f32 v[178:179], v[164:165], v[164:165], v[178:179]
	v_lshlrev_b32_e32 v166, 16, v8
	v_and_b32_e32 v167, 0xffff0000, v8
	v_lshlrev_b32_e32 v168, 16, v9
	v_and_b32_e32 v169, 0xffff0000, v9
	v_pk_fma_f32 v[176:177], v[166:167], v[166:167], v[176:177]
	v_pk_fma_f32 v[178:179], v[168:169], v[168:169], v[178:179]
	v_lshlrev_b32_e32 v162, 16, v10
	v_and_b32_e32 v163, 0xffff0000, v10
	v_lshlrev_b32_e32 v164, 16, v11
	v_and_b32_e32 v165, 0xffff0000, v11
	v_pk_fma_f32 v[176:177], v[162:163], v[162:163], v[176:177]
	v_pk_fma_f32 v[178:179], v[164:165], v[164:165], v[178:179]
	v_lshlrev_b32_e32 v166, 16, v12
	v_and_b32_e32 v167, 0xffff0000, v12
	v_lshlrev_b32_e32 v168, 16, v13
	v_and_b32_e32 v169, 0xffff0000, v13
	v_pk_fma_f32 v[176:177], v[166:167], v[166:167], v[176:177]
	v_pk_fma_f32 v[178:179], v[168:169], v[168:169], v[178:179]
	v_lshlrev_b32_e32 v162, 16, v14
	v_and_b32_e32 v163, 0xffff0000, v14
	v_lshlrev_b32_e32 v164, 16, v15
	v_and_b32_e32 v165, 0xffff0000, v15
	v_pk_fma_f32 v[176:177], v[162:163], v[162:163], v[176:177]
	v_pk_fma_f32 v[178:179], v[164:165], v[164:165], v[178:179]
	v_lshlrev_b32_e32 v166, 16, v16
	v_and_b32_e32 v167, 0xffff0000, v16
	v_lshlrev_b32_e32 v168, 16, v17
	v_and_b32_e32 v169, 0xffff0000, v17
	v_pk_fma_f32 v[176:177], v[166:167], v[166:167], v[176:177]
	v_pk_fma_f32 v[178:179], v[168:169], v[168:169], v[178:179]
	v_lshlrev_b32_e32 v162, 16, v18
	v_and_b32_e32 v163, 0xffff0000, v18
	v_lshlrev_b32_e32 v164, 16, v19
	v_and_b32_e32 v165, 0xffff0000, v19
	v_pk_fma_f32 v[176:177], v[162:163], v[162:163], v[176:177]
	v_pk_fma_f32 v[178:179], v[164:165], v[164:165], v[178:179]
	v_lshlrev_b32_e32 v166, 16, v20
	v_and_b32_e32 v167, 0xffff0000, v20
	v_lshlrev_b32_e32 v168, 16, v21
	v_and_b32_e32 v169, 0xffff0000, v21
	v_pk_fma_f32 v[176:177], v[166:167], v[166:167], v[176:177]
	v_pk_fma_f32 v[178:179], v[168:169], v[168:169], v[178:179]
	v_lshlrev_b32_e32 v162, 16, v22
	v_and_b32_e32 v163, 0xffff0000, v22
	v_lshlrev_b32_e32 v164, 16, v23
	v_and_b32_e32 v165, 0xffff0000, v23
	v_pk_fma_f32 v[176:177], v[162:163], v[162:163], v[176:177]
	v_pk_fma_f32 v[178:179], v[164:165], v[164:165], v[178:179]
	v_lshlrev_b32_e32 v166, 16, v24
	v_and_b32_e32 v167, 0xffff0000, v24
	v_lshlrev_b32_e32 v168, 16, v25
	v_and_b32_e32 v169, 0xffff0000, v25
	v_pk_fma_f32 v[176:177], v[166:167], v[166:167], v[176:177]
	v_pk_fma_f32 v[178:179], v[168:169], v[168:169], v[178:179]
	v_lshlrev_b32_e32 v162, 16, v26
	v_and_b32_e32 v163, 0xffff0000, v26
	v_lshlrev_b32_e32 v164, 16, v27
	v_and_b32_e32 v165, 0xffff0000, v27
	v_pk_fma_f32 v[176:177], v[162:163], v[162:163], v[176:177]
	v_pk_fma_f32 v[178:179], v[164:165], v[164:165], v[178:179]
	v_lshlrev_b32_e32 v166, 16, v28
	v_and_b32_e32 v167, 0xffff0000, v28
	v_lshlrev_b32_e32 v168, 16, v29
	v_and_b32_e32 v169, 0xffff0000, v29
	v_pk_fma_f32 v[176:177], v[166:167], v[166:167], v[176:177]
	v_pk_fma_f32 v[178:179], v[168:169], v[168:169], v[178:179]
	v_lshlrev_b32_e32 v162, 16, v30
	v_and_b32_e32 v163, 0xffff0000, v30
	v_lshlrev_b32_e32 v164, 16, v31
	v_and_b32_e32 v165, 0xffff0000, v31
	v_pk_fma_f32 v[176:177], v[162:163], v[162:163], v[176:177]
	v_pk_fma_f32 v[178:179], v[164:165], v[164:165], v[178:179]
	v_lshlrev_b32_e32 v166, 16, v32
	v_and_b32_e32 v167, 0xffff0000, v32
	v_lshlrev_b32_e32 v168, 16, v33
	v_and_b32_e32 v169, 0xffff0000, v33
	v_pk_fma_f32 v[176:177], v[166:167], v[166:167], v[176:177]
	v_pk_fma_f32 v[178:179], v[168:169], v[168:169], v[178:179]
	v_pk_add_f32 v[176:177], v[176:177], v[178:179]
	s_nop 0
	v_add_f32_e32 v252, v176, v177
	s_waitcnt lgkmcnt(0)
	ds_bpermute_b32 v254, v246, v252
	s_waitcnt lgkmcnt(0)
	v_add_f32_e32 v252, v252, v254
	ds_bpermute_b32 v254, v247, v252
	s_waitcnt lgkmcnt(0)
	v_add_f32_e32 v252, v252, v254
	ds_bpermute_b32 v254, v248, v252
	s_waitcnt lgkmcnt(0)
	v_add_f32_e32 v252, v252, v254
	ds_bpermute_b32 v254, v249, v252
	s_waitcnt lgkmcnt(0)
	v_add_f32_e32 v252, v252, v254
	ds_bpermute_b32 v254, v250, v252
	s_waitcnt lgkmcnt(0)
	v_add_f32_e32 v252, v252, v254
	ds_bpermute_b32 v254, v251, v252
	s_waitcnt lgkmcnt(0)
	v_add_f32_e32 v252, v252, v254
	v_mov_b32_e32 v254, 0x358637bd
	v_fmac_f32_e32 v254, 0x39800000, v252
	v_mul_f32_e32 v252, 0x4b800000, v254
	v_cmp_gt_f32_e32 vcc, s20, v254
	s_nop 1
	v_cndmask_b32_e32 v254, v254, v252, vcc
	v_rsq_f32_e32 v254, v254
	s_nop 0
	v_mul_f32_e32 v252, 0x45800000, v254
	v_cndmask_b32_e32 v252, v254, v252, vcc
	ds_read_b128 v[146:149], v238 offset:2048
	ds_read_b128 v[150:153], v238 offset:18432
	ds_read_b128 v[154:157], v238 offset:3072
	ds_read_b128 v[158:161], v238 offset:19456
	s_waitcnt lgkmcnt(4)
	v_lshlrev_b32_e32 v162, 16, v2
	v_and_b32_e32 v163, 0xffff0000, v2
	v_lshlrev_b32_e32 v164, 16, v3
	v_and_b32_e32 v165, 0xffff0000, v3
	v_lshlrev_b32_e32 v166, 16, v34
	v_and_b32_e32 v167, 0xffff0000, v34
	v_lshlrev_b32_e32 v168, 16, v35
	v_and_b32_e32 v169, 0xffff0000, v35
	v_pk_mul_f32 v[162:163], v[162:163], v[252:253] op_sel_hi:[1,0]
	v_pk_mul_f32 v[164:165], v[164:165], v[252:253] op_sel_hi:[1,0]
	v_pk_mul_f32 v[162:163], v[162:163], v[130:131]
	v_pk_mul_f32 v[164:165], v[164:165], v[132:133]
	v_pk_fma_f32 v[162:163], v[134:135], v[162:163], v[166:167]
	v_pk_fma_f32 v[164:165], v[136:137], v[164:165], v[168:169]
	s_nop 0
	global_store_dwordx4 v238, v[162:165], s[30:31] offset:0 nt
	s_nop 1
	v_lshlrev_b32_e32 v162, 16, v4
	v_and_b32_e32 v163, 0xffff0000, v4
	v_lshlrev_b32_e32 v164, 16, v5
	v_and_b32_e32 v165, 0xffff0000, v5
	v_lshlrev_b32_e32 v166, 16, v36
	v_and_b32_e32 v167, 0xffff0000, v36
	v_lshlrev_b32_e32 v168, 16, v37
	v_and_b32_e32 v169, 0xffff0000, v37
	v_pk_mul_f32 v[162:163], v[162:163], v[252:253] op_sel_hi:[1,0]
	v_pk_mul_f32 v[164:165], v[164:165], v[252:253] op_sel_hi:[1,0]
	v_pk_mul_f32 v[162:163], v[162:163], v[138:139]
	v_pk_mul_f32 v[164:165], v[164:165], v[140:141]
	v_pk_fma_f32 v[162:163], v[142:143], v[162:163], v[166:167]
	v_pk_fma_f32 v[164:165], v[144:145], v[164:165], v[168:169]
	s_nop 0
	global_store_dwordx4 v238, v[162:165], s[30:31] offset:1024 nt
	s_nop 1
	ds_read_b128 v[130:133], v238 offset:4096
	ds_read_b128 v[134:137], v238 offset:20480
	ds_read_b128 v[138:141], v238 offset:5120
	ds_read_b128 v[142:145], v238 offset:21504
	s_waitcnt lgkmcnt(4)
	v_lshlrev_b32_e32 v162, 16, v6
	v_and_b32_e32 v163, 0xffff0000, v6
	v_lshlrev_b32_e32 v164, 16, v7
	v_and_b32_e32 v165, 0xffff0000, v7
	v_lshlrev_b32_e32 v166, 16, v38
	v_and_b32_e32 v167, 0xffff0000, v38
	v_lshlrev_b32_e32 v168, 16, v39
	v_and_b32_e32 v169, 0xffff0000, v39
	v_pk_mul_f32 v[162:163], v[162:163], v[252:253] op_sel_hi:[1,0]
	v_pk_mul_f32 v[164:165], v[164:165], v[252:253] op_sel_hi:[1,0]
	v_pk_mul_f32 v[162:163], v[162:163], v[146:147]
	v_pk_mul_f32 v[164:165], v[164:165], v[148:149]
	v_pk_fma_f32 v[162:163], v[150:151], v[162:163], v[166:167]
	v_pk_fma_f32 v[164:165], v[152:153], v[164:165], v[168:169]
	s_nop 0
	global_store_dwordx4 v238, v[162:165], s[30:31] offset:2048 nt
	s_nop 1
	v_lshlrev_b32_e32 v162, 16, v8
	v_and_b32_e32 v163, 0xffff0000, v8
	v_lshlrev_b32_e32 v164, 16, v9
	v_and_b32_e32 v165, 0xffff0000, v9
	v_lshlrev_b32_e32 v166, 16, v40
	v_and_b32_e32 v167, 0xffff0000, v40
	v_lshlrev_b32_e32 v168, 16, v41
	v_and_b32_e32 v169, 0xffff0000, v41
	v_pk_mul_f32 v[162:163], v[162:163], v[252:253] op_sel_hi:[1,0]
	v_pk_mul_f32 v[164:165], v[164:165], v[252:253] op_sel_hi:[1,0]
	v_pk_mul_f32 v[162:163], v[162:163], v[154:155]
	v_pk_mul_f32 v[164:165], v[164:165], v[156:157]
	v_pk_fma_f32 v[162:163], v[158:159], v[162:163], v[166:167]
	v_pk_fma_f32 v[164:165], v[160:161], v[164:165], v[168:169]
	s_nop 0
	global_store_dwordx4 v238, v[162:165], s[30:31] offset:3072 nt
	s_nop 1
	ds_read_b128 v[146:149], v238 offset:6144
	ds_read_b128 v[150:153], v238 offset:22528
	ds_read_b128 v[154:157], v238 offset:7168
	ds_read_b128 v[158:161], v238 offset:23552
	s_waitcnt lgkmcnt(4)
	v_lshlrev_b32_e32 v162, 16, v10
	v_and_b32_e32 v163, 0xffff0000, v10
	v_lshlrev_b32_e32 v164, 16, v11
	v_and_b32_e32 v165, 0xffff0000, v11
	v_lshlrev_b32_e32 v166, 16, v42
	v_and_b32_e32 v167, 0xffff0000, v42
	v_lshlrev_b32_e32 v168, 16, v43
	v_and_b32_e32 v169, 0xffff0000, v43
	v_pk_mul_f32 v[162:163], v[162:163], v[252:253] op_sel_hi:[1,0]
	v_pk_mul_f32 v[164:165], v[164:165], v[252:253] op_sel_hi:[1,0]
	v_pk_mul_f32 v[162:163], v[162:163], v[130:131]
	v_pk_mul_f32 v[164:165], v[164:165], v[132:133]
	v_pk_fma_f32 v[162:163], v[134:135], v[162:163], v[166:167]
	v_pk_fma_f32 v[164:165], v[136:137], v[164:165], v[168:169]
	s_nop 0
	global_store_dwordx4 v241, v[162:165], s[30:31] offset:0 nt
	s_nop 1
	v_lshlrev_b32_e32 v162, 16, v12
	v_and_b32_e32 v163, 0xffff0000, v12
	v_lshlrev_b32_e32 v164, 16, v13
	v_and_b32_e32 v165, 0xffff0000, v13
	v_lshlrev_b32_e32 v166, 16, v44
	v_and_b32_e32 v167, 0xffff0000, v44
	v_lshlrev_b32_e32 v168, 16, v45
	v_and_b32_e32 v169, 0xffff0000, v45
	v_pk_mul_f32 v[162:163], v[162:163], v[252:253] op_sel_hi:[1,0]
	v_pk_mul_f32 v[164:165], v[164:165], v[252:253] op_sel_hi:[1,0]
	v_pk_mul_f32 v[162:163], v[162:163], v[138:139]
	v_pk_mul_f32 v[164:165], v[164:165], v[140:141]
	v_pk_fma_f32 v[162:163], v[142:143], v[162:163], v[166:167]
	v_pk_fma_f32 v[164:165], v[144:145], v[164:165], v[168:169]
	s_nop 0
	global_store_dwordx4 v241, v[162:165], s[30:31] offset:1024 nt
	s_nop 1
	ds_read_b128 v[130:133], v238 offset:8192
	ds_read_b128 v[134:137], v238 offset:24576
	ds_read_b128 v[138:141], v238 offset:9216
	ds_read_b128 v[142:145], v238 offset:25600
	s_waitcnt lgkmcnt(4)
	v_lshlrev_b32_e32 v162, 16, v14
	v_and_b32_e32 v163, 0xffff0000, v14
	v_lshlrev_b32_e32 v164, 16, v15
	v_and_b32_e32 v165, 0xffff0000, v15
	v_lshlrev_b32_e32 v166, 16, v46
	v_and_b32_e32 v167, 0xffff0000, v46
	v_lshlrev_b32_e32 v168, 16, v47
	v_and_b32_e32 v169, 0xffff0000, v47
	v_pk_mul_f32 v[162:163], v[162:163], v[252:253] op_sel_hi:[1,0]
	v_pk_mul_f32 v[164:165], v[164:165], v[252:253] op_sel_hi:[1,0]
	v_pk_mul_f32 v[162:163], v[162:163], v[146:147]
	v_pk_mul_f32 v[164:165], v[164:165], v[148:149]
	v_pk_fma_f32 v[162:163], v[150:151], v[162:163], v[166:167]
	v_pk_fma_f32 v[164:165], v[152:153], v[164:165], v[168:169]
	s_nop 0
	global_store_dwordx4 v241, v[162:165], s[30:31] offset:2048 nt
	s_nop 1
	v_lshlrev_b32_e32 v162, 16, v16
	v_and_b32_e32 v163, 0xffff0000, v16
	v_lshlrev_b32_e32 v164, 16, v17
	v_and_b32_e32 v165, 0xffff0000, v17
	v_lshlrev_b32_e32 v166, 16, v48
	v_and_b32_e32 v167, 0xffff0000, v48
	v_lshlrev_b32_e32 v168, 16, v49
	v_and_b32_e32 v169, 0xffff0000, v49
	v_pk_mul_f32 v[162:163], v[162:163], v[252:253] op_sel_hi:[1,0]
	v_pk_mul_f32 v[164:165], v[164:165], v[252:253] op_sel_hi:[1,0]
	v_pk_mul_f32 v[162:163], v[162:163], v[154:155]
	v_pk_mul_f32 v[164:165], v[164:165], v[156:157]
	v_pk_fma_f32 v[162:163], v[158:159], v[162:163], v[166:167]
	v_pk_fma_f32 v[164:165], v[160:161], v[164:165], v[168:169]
	s_nop 0
	global_store_dwordx4 v241, v[162:165], s[30:31] offset:3072 nt
	s_nop 1
	ds_read_b128 v[146:149], v238 offset:10240
	ds_read_b128 v[150:153], v238 offset:26624
	ds_read_b128 v[154:157], v238 offset:11264
	ds_read_b128 v[158:161], v238 offset:27648
	s_waitcnt lgkmcnt(4)
	v_lshlrev_b32_e32 v162, 16, v18
	v_and_b32_e32 v163, 0xffff0000, v18
	v_lshlrev_b32_e32 v164, 16, v19
	v_and_b32_e32 v165, 0xffff0000, v19
	v_lshlrev_b32_e32 v166, 16, v50
	v_and_b32_e32 v167, 0xffff0000, v50
	v_lshlrev_b32_e32 v168, 16, v51
	v_and_b32_e32 v169, 0xffff0000, v51
	v_pk_mul_f32 v[162:163], v[162:163], v[252:253] op_sel_hi:[1,0]
	v_pk_mul_f32 v[164:165], v[164:165], v[252:253] op_sel_hi:[1,0]
	v_pk_mul_f32 v[162:163], v[162:163], v[130:131]
	v_pk_mul_f32 v[164:165], v[164:165], v[132:133]
	v_pk_fma_f32 v[162:163], v[134:135], v[162:163], v[166:167]
	v_pk_fma_f32 v[164:165], v[136:137], v[164:165], v[168:169]
	s_nop 0
	global_store_dwordx4 v242, v[162:165], s[30:31] offset:0 nt
	s_nop 1
	v_lshlrev_b32_e32 v162, 16, v20
	v_and_b32_e32 v163, 0xffff0000, v20
	v_lshlrev_b32_e32 v164, 16, v21
	v_and_b32_e32 v165, 0xffff0000, v21
	v_lshlrev_b32_e32 v166, 16, v52
	v_and_b32_e32 v167, 0xffff0000, v52
	v_lshlrev_b32_e32 v168, 16, v53
	v_and_b32_e32 v169, 0xffff0000, v53
	v_pk_mul_f32 v[162:163], v[162:163], v[252:253] op_sel_hi:[1,0]
	v_pk_mul_f32 v[164:165], v[164:165], v[252:253] op_sel_hi:[1,0]
	v_pk_mul_f32 v[162:163], v[162:163], v[138:139]
	v_pk_mul_f32 v[164:165], v[164:165], v[140:141]
	v_pk_fma_f32 v[162:163], v[142:143], v[162:163], v[166:167]
	v_pk_fma_f32 v[164:165], v[144:145], v[164:165], v[168:169]
	s_nop 0
	global_store_dwordx4 v242, v[162:165], s[30:31] offset:1024 nt
	s_nop 1
	ds_read_b128 v[130:133], v238 offset:12288
	ds_read_b128 v[134:137], v238 offset:28672
	ds_read_b128 v[138:141], v238 offset:13312
	ds_read_b128 v[142:145], v238 offset:29696
	s_waitcnt lgkmcnt(4)
	v_lshlrev_b32_e32 v162, 16, v22
	v_and_b32_e32 v163, 0xffff0000, v22
	v_lshlrev_b32_e32 v164, 16, v23
	v_and_b32_e32 v165, 0xffff0000, v23
	v_lshlrev_b32_e32 v166, 16, v54
	v_and_b32_e32 v167, 0xffff0000, v54
	v_lshlrev_b32_e32 v168, 16, v55
	v_and_b32_e32 v169, 0xffff0000, v55
	v_pk_mul_f32 v[162:163], v[162:163], v[252:253] op_sel_hi:[1,0]
	v_pk_mul_f32 v[164:165], v[164:165], v[252:253] op_sel_hi:[1,0]
	v_pk_mul_f32 v[162:163], v[162:163], v[146:147]
	v_pk_mul_f32 v[164:165], v[164:165], v[148:149]
	v_pk_fma_f32 v[162:163], v[150:151], v[162:163], v[166:167]
	v_pk_fma_f32 v[164:165], v[152:153], v[164:165], v[168:169]
	s_nop 0
	global_store_dwordx4 v242, v[162:165], s[30:31] offset:2048 nt
	s_nop 1
	v_lshlrev_b32_e32 v162, 16, v24
	v_and_b32_e32 v163, 0xffff0000, v24
	v_lshlrev_b32_e32 v164, 16, v25
	v_and_b32_e32 v165, 0xffff0000, v25
	v_lshlrev_b32_e32 v166, 16, v56
	v_and_b32_e32 v167, 0xffff0000, v56
	v_lshlrev_b32_e32 v168, 16, v57
	v_and_b32_e32 v169, 0xffff0000, v57
	v_pk_mul_f32 v[162:163], v[162:163], v[252:253] op_sel_hi:[1,0]
	v_pk_mul_f32 v[164:165], v[164:165], v[252:253] op_sel_hi:[1,0]
	v_pk_mul_f32 v[162:163], v[162:163], v[154:155]
	v_pk_mul_f32 v[164:165], v[164:165], v[156:157]
	v_pk_fma_f32 v[162:163], v[158:159], v[162:163], v[166:167]
	v_pk_fma_f32 v[164:165], v[160:161], v[164:165], v[168:169]
	s_nop 0
	global_store_dwordx4 v242, v[162:165], s[30:31] offset:3072 nt
	s_nop 1
	ds_read_b128 v[146:149], v238 offset:14336
	ds_read_b128 v[150:153], v238 offset:30720
	ds_read_b128 v[154:157], v238 offset:15360
	ds_read_b128 v[158:161], v238 offset:31744
	s_waitcnt lgkmcnt(4)
	v_lshlrev_b32_e32 v162, 16, v26
	v_and_b32_e32 v163, 0xffff0000, v26
	v_lshlrev_b32_e32 v164, 16, v27
	v_and_b32_e32 v165, 0xffff0000, v27
	v_lshlrev_b32_e32 v166, 16, v58
	v_and_b32_e32 v167, 0xffff0000, v58
	v_lshlrev_b32_e32 v168, 16, v59
	v_and_b32_e32 v169, 0xffff0000, v59
	v_pk_mul_f32 v[162:163], v[162:163], v[252:253] op_sel_hi:[1,0]
	v_pk_mul_f32 v[164:165], v[164:165], v[252:253] op_sel_hi:[1,0]
	v_pk_mul_f32 v[162:163], v[162:163], v[130:131]
	v_pk_mul_f32 v[164:165], v[164:165], v[132:133]
	v_pk_fma_f32 v[162:163], v[134:135], v[162:163], v[166:167]
	v_pk_fma_f32 v[164:165], v[136:137], v[164:165], v[168:169]
	s_nop 0
	global_store_dwordx4 v243, v[162:165], s[30:31] offset:0 nt
	s_nop 1
	v_lshlrev_b32_e32 v162, 16, v28
	v_and_b32_e32 v163, 0xffff0000, v28
	v_lshlrev_b32_e32 v164, 16, v29
	v_and_b32_e32 v165, 0xffff0000, v29
	v_lshlrev_b32_e32 v166, 16, v60
	v_and_b32_e32 v167, 0xffff0000, v60
	v_lshlrev_b32_e32 v168, 16, v61
	v_and_b32_e32 v169, 0xffff0000, v61
	v_pk_mul_f32 v[162:163], v[162:163], v[252:253] op_sel_hi:[1,0]
	v_pk_mul_f32 v[164:165], v[164:165], v[252:253] op_sel_hi:[1,0]
	v_pk_mul_f32 v[162:163], v[162:163], v[138:139]
	v_pk_mul_f32 v[164:165], v[164:165], v[140:141]
	v_pk_fma_f32 v[162:163], v[142:143], v[162:163], v[166:167]
	v_pk_fma_f32 v[164:165], v[144:145], v[164:165], v[168:169]
	s_nop 0
	global_store_dwordx4 v243, v[162:165], s[30:31] offset:1024 nt
	s_nop 1
	s_waitcnt lgkmcnt(0)
	v_lshlrev_b32_e32 v162, 16, v30
	v_and_b32_e32 v163, 0xffff0000, v30
	v_lshlrev_b32_e32 v164, 16, v31
	v_and_b32_e32 v165, 0xffff0000, v31
	v_lshlrev_b32_e32 v166, 16, v62
	v_and_b32_e32 v167, 0xffff0000, v62
	v_lshlrev_b32_e32 v168, 16, v63
	v_and_b32_e32 v169, 0xffff0000, v63
	v_pk_mul_f32 v[162:163], v[162:163], v[252:253] op_sel_hi:[1,0]
	v_pk_mul_f32 v[164:165], v[164:165], v[252:253] op_sel_hi:[1,0]
	v_pk_mul_f32 v[162:163], v[162:163], v[146:147]
	v_pk_mul_f32 v[164:165], v[164:165], v[148:149]
	v_pk_fma_f32 v[162:163], v[150:151], v[162:163], v[166:167]
	v_pk_fma_f32 v[164:165], v[152:153], v[164:165], v[168:169]
	s_nop 0
	global_store_dwordx4 v243, v[162:165], s[30:31] offset:2048 nt
	s_nop 1
	v_lshlrev_b32_e32 v162, 16, v32
	v_and_b32_e32 v163, 0xffff0000, v32
	v_lshlrev_b32_e32 v164, 16, v33
	v_and_b32_e32 v165, 0xffff0000, v33
	v_lshlrev_b32_e32 v166, 16, v64
	v_and_b32_e32 v167, 0xffff0000, v64
	v_lshlrev_b32_e32 v168, 16, v65
	v_and_b32_e32 v169, 0xffff0000, v65
	v_pk_mul_f32 v[162:163], v[162:163], v[252:253] op_sel_hi:[1,0]
	v_pk_mul_f32 v[164:165], v[164:165], v[252:253] op_sel_hi:[1,0]
	v_pk_mul_f32 v[162:163], v[162:163], v[154:155]
	v_pk_mul_f32 v[164:165], v[164:165], v[156:157]
	v_pk_fma_f32 v[162:163], v[158:159], v[162:163], v[166:167]
	v_pk_fma_f32 v[164:165], v[160:161], v[164:165], v[168:169]
	s_nop 0
	global_store_dwordx4 v243, v[162:165], s[30:31] offset:3072 nt
	s_nop 1
	s_add_u32 s30, s30, 0x2000000
	s_addc_u32 s31, s31, 0
	s_waitcnt vmcnt(16)
	s_add_u32 s22, s22, 0x1000000
	s_addc_u32 s23, s23, 0
	s_add_u32 s24, s24, 0x1000000
	s_addc_u32 s25, s25, 0
	global_load_dwordx2 v[2:3], v244, s[22:23] offset:0
	global_load_dwordx2 v[4:5], v244, s[22:23] offset:512
	global_load_dwordx2 v[6:7], v244, s[22:23] offset:1024
	global_load_dwordx2 v[8:9], v244, s[22:23] offset:1536
	global_load_dwordx2 v[10:11], v244, s[22:23] offset:2048
	global_load_dwordx2 v[12:13], v244, s[22:23] offset:2560
	global_load_dwordx2 v[14:15], v244, s[22:23] offset:3072
	global_load_dwordx2 v[16:17], v244, s[22:23] offset:3584
	global_load_dwordx2 v[18:19], v245, s[22:23] offset:0
	global_load_dwordx2 v[20:21], v245, s[22:23] offset:512
	global_load_dwordx2 v[22:23], v245, s[22:23] offset:1024
	global_load_dwordx2 v[24:25], v245, s[22:23] offset:1536
	global_load_dwordx2 v[26:27], v245, s[22:23] offset:2048
	global_load_dwordx2 v[28:29], v245, s[22:23] offset:2560
	global_load_dwordx2 v[30:31], v245, s[22:23] offset:3072
	global_load_dwordx2 v[32:33], v245, s[22:23] offset:3584
	global_load_dwordx2 v[34:35], v244, s[24:25] offset:0
	global_load_dwordx2 v[36:37], v244, s[24:25] offset:512
	global_load_dwordx2 v[38:39], v244, s[24:25] offset:1024
	global_load_dwordx2 v[40:41], v244, s[24:25] offset:1536
	global_load_dwordx2 v[42:43], v244, s[24:25] offset:2048
	global_load_dwordx2 v[44:45], v244, s[24:25] offset:2560
	global_load_dwordx2 v[46:47], v244, s[24:25] offset:3072
	global_load_dwordx2 v[48:49], v244, s[24:25] offset:3584
	global_load_dwordx2 v[50:51], v245, s[24:25] offset:0
	global_load_dwordx2 v[52:53], v245, s[24:25] offset:512
	global_load_dwordx2 v[54:55], v245, s[24:25] offset:1024
	global_load_dwordx2 v[56:57], v245, s[24:25] offset:1536
	global_load_dwordx2 v[58:59], v245, s[24:25] offset:2048
	global_load_dwordx2 v[60:61], v245, s[24:25] offset:2560
	global_load_dwordx2 v[62:63], v245, s[24:25] offset:3072
	global_load_dwordx2 v[64:65], v245, s[24:25] offset:3584
	ds_read_b128 v[130:133], v238 offset:0
	ds_read_b128 v[134:137], v238 offset:16384
	ds_read_b128 v[138:141], v238 offset:1024
	ds_read_b128 v[142:145], v238 offset:17408
	v_lshlrev_b32_e32 v162, 16, v66
	v_and_b32_e32 v163, 0xffff0000, v66
	v_lshlrev_b32_e32 v164, 16, v67
	v_and_b32_e32 v165, 0xffff0000, v67
	v_pk_mul_f32 v[176:177], v[162:163], v[162:163]
	v_pk_mul_f32 v[178:179], v[164:165], v[164:165]
	v_lshlrev_b32_e32 v166, 16, v68
	v_and_b32_e32 v167, 0xffff0000, v68
	v_lshlrev_b32_e32 v168, 16, v69
	v_and_b32_e32 v169, 0xffff0000, v69
	v_pk_fma_f32 v[176:177], v[166:167], v[166:167], v[176:177]
	v_pk_fma_f32 v[178:179], v[168:169], v[168:169], v[178:179]
	v_lshlrev_b32_e32 v162, 16, v70
	v_and_b32_e32 v163, 0xffff0000, v70
	v_lshlrev_b32_e32 v164, 16, v71
	v_and_b32_e32 v165, 0xffff0000, v71
	v_pk_fma_f32 v[176:177], v[162:163], v[162:163], v[176:177]
	v_pk_fma_f32 v[178:179], v[164:165], v[164:165], v[178:179]
	v_lshlrev_b32_e32 v166, 16, v72
	v_and_b32_e32 v167, 0xffff0000, v72
	v_lshlrev_b32_e32 v168, 16, v73
	v_and_b32_e32 v169, 0xffff0000, v73
	v_pk_fma_f32 v[176:177], v[166:167], v[166:167], v[176:177]
	v_pk_fma_f32 v[178:179], v[168:169], v[168:169], v[178:179]
	v_lshlrev_b32_e32 v162, 16, v74
	v_and_b32_e32 v163, 0xffff0000, v74
	v_lshlrev_b32_e32 v164, 16, v75
	v_and_b32_e32 v165, 0xffff0000, v75
	v_pk_fma_f32 v[176:177], v[162:163], v[162:163], v[176:177]
	v_pk_fma_f32 v[178:179], v[164:165], v[164:165], v[178:179]
	v_lshlrev_b32_e32 v166, 16, v76
	v_and_b32_e32 v167, 0xffff0000, v76
	v_lshlrev_b32_e32 v168, 16, v77
	v_and_b32_e32 v169, 0xffff0000, v77
	v_pk_fma_f32 v[176:177], v[166:167], v[166:167], v[176:177]
	v_pk_fma_f32 v[178:179], v[168:169], v[168:169], v[178:179]
	v_lshlrev_b32_e32 v162, 16, v78
	v_and_b32_e32 v163, 0xffff0000, v78
	v_lshlrev_b32_e32 v164, 16, v79
	v_and_b32_e32 v165, 0xffff0000, v79
	v_pk_fma_f32 v[176:177], v[162:163], v[162:163], v[176:177]
	v_pk_fma_f32 v[178:179], v[164:165], v[164:165], v[178:179]
	v_lshlrev_b32_e32 v166, 16, v80
	v_and_b32_e32 v167, 0xffff0000, v80
	v_lshlrev_b32_e32 v168, 16, v81
	v_and_b32_e32 v169, 0xffff0000, v81
	v_pk_fma_f32 v[176:177], v[166:167], v[166:167], v[176:177]
	v_pk_fma_f32 v[178:179], v[168:169], v[168:169], v[178:179]
	v_lshlrev_b32_e32 v162, 16, v82
	v_and_b32_e32 v163, 0xffff0000, v82
	v_lshlrev_b32_e32 v164, 16, v83
	v_and_b32_e32 v165, 0xffff0000, v83
	v_pk_fma_f32 v[176:177], v[162:163], v[162:163], v[176:177]
	v_pk_fma_f32 v[178:179], v[164:165], v[164:165], v[178:179]
	v_lshlrev_b32_e32 v166, 16, v84
	v_and_b32_e32 v167, 0xffff0000, v84
	v_lshlrev_b32_e32 v168, 16, v85
	v_and_b32_e32 v169, 0xffff0000, v85
	v_pk_fma_f32 v[176:177], v[166:167], v[166:167], v[176:177]
	v_pk_fma_f32 v[178:179], v[168:169], v[168:169], v[178:179]
	v_lshlrev_b32_e32 v162, 16, v86
	v_and_b32_e32 v163, 0xffff0000, v86
	v_lshlrev_b32_e32 v164, 16, v87
	v_and_b32_e32 v165, 0xffff0000, v87
	v_pk_fma_f32 v[176:177], v[162:163], v[162:163], v[176:177]
	v_pk_fma_f32 v[178:179], v[164:165], v[164:165], v[178:179]
	v_lshlrev_b32_e32 v166, 16, v88
	v_and_b32_e32 v167, 0xffff0000, v88
	v_lshlrev_b32_e32 v168, 16, v89
	v_and_b32_e32 v169, 0xffff0000, v89
	v_pk_fma_f32 v[176:177], v[166:167], v[166:167], v[176:177]
	v_pk_fma_f32 v[178:179], v[168:169], v[168:169], v[178:179]
	v_lshlrev_b32_e32 v162, 16, v90
	v_and_b32_e32 v163, 0xffff0000, v90
	v_lshlrev_b32_e32 v164, 16, v91
	v_and_b32_e32 v165, 0xffff0000, v91
	v_pk_fma_f32 v[176:177], v[162:163], v[162:163], v[176:177]
	v_pk_fma_f32 v[178:179], v[164:165], v[164:165], v[178:179]
	v_lshlrev_b32_e32 v166, 16, v92
	v_and_b32_e32 v167, 0xffff0000, v92
	v_lshlrev_b32_e32 v168, 16, v93
	v_and_b32_e32 v169, 0xffff0000, v93
	v_pk_fma_f32 v[176:177], v[166:167], v[166:167], v[176:177]
	v_pk_fma_f32 v[178:179], v[168:169], v[168:169], v[178:179]
	v_lshlrev_b32_e32 v162, 16, v94
	v_and_b32_e32 v163, 0xffff0000, v94
	v_lshlrev_b32_e32 v164, 16, v95
	v_and_b32_e32 v165, 0xffff0000, v95
	v_pk_fma_f32 v[176:177], v[162:163], v[162:163], v[176:177]
	v_pk_fma_f32 v[178:179], v[164:165], v[164:165], v[178:179]
	v_lshlrev_b32_e32 v166, 16, v96
	v_and_b32_e32 v167, 0xffff0000, v96
	v_lshlrev_b32_e32 v168, 16, v97
	v_and_b32_e32 v169, 0xffff0000, v97
	v_pk_fma_f32 v[176:177], v[166:167], v[166:167], v[176:177]
	v_pk_fma_f32 v[178:179], v[168:169], v[168:169], v[178:179]
	v_pk_add_f32 v[176:177], v[176:177], v[178:179]
	s_nop 0
	v_add_f32_e32 v252, v176, v177
	s_waitcnt lgkmcnt(0)
	ds_bpermute_b32 v254, v246, v252
	s_waitcnt lgkmcnt(0)
	v_add_f32_e32 v252, v252, v254
	ds_bpermute_b32 v254, v247, v252
	s_waitcnt lgkmcnt(0)
	v_add_f32_e32 v252, v252, v254
	ds_bpermute_b32 v254, v248, v252
	s_waitcnt lgkmcnt(0)
	v_add_f32_e32 v252, v252, v254
	ds_bpermute_b32 v254, v249, v252
	s_waitcnt lgkmcnt(0)
	v_add_f32_e32 v252, v252, v254
	ds_bpermute_b32 v254, v250, v252
	s_waitcnt lgkmcnt(0)
	v_add_f32_e32 v252, v252, v254
	ds_bpermute_b32 v254, v251, v252
	s_waitcnt lgkmcnt(0)
	v_add_f32_e32 v252, v252, v254
	v_mov_b32_e32 v254, 0x358637bd
	v_fmac_f32_e32 v254, 0x39800000, v252
	v_mul_f32_e32 v252, 0x4b800000, v254
	v_cmp_gt_f32_e32 vcc, s20, v254
	s_nop 1
	v_cndmask_b32_e32 v254, v254, v252, vcc
	v_rsq_f32_e32 v254, v254
	s_nop 0
	v_mul_f32_e32 v252, 0x45800000, v254
	v_cndmask_b32_e32 v252, v254, v252, vcc
	ds_read_b128 v[146:149], v238 offset:2048
	ds_read_b128 v[150:153], v238 offset:18432
	ds_read_b128 v[154:157], v238 offset:3072
	ds_read_b128 v[158:161], v238 offset:19456
	s_waitcnt lgkmcnt(4)
	v_lshlrev_b32_e32 v162, 16, v66
	v_and_b32_e32 v163, 0xffff0000, v66
	v_lshlrev_b32_e32 v164, 16, v67
	v_and_b32_e32 v165, 0xffff0000, v67
	v_lshlrev_b32_e32 v166, 16, v98
	v_and_b32_e32 v167, 0xffff0000, v98
	v_lshlrev_b32_e32 v168, 16, v99
	v_and_b32_e32 v169, 0xffff0000, v99
	v_pk_mul_f32 v[162:163], v[162:163], v[252:253] op_sel_hi:[1,0]
	v_pk_mul_f32 v[164:165], v[164:165], v[252:253] op_sel_hi:[1,0]
	v_pk_mul_f32 v[162:163], v[162:163], v[130:131]
	v_pk_mul_f32 v[164:165], v[164:165], v[132:133]
	v_pk_fma_f32 v[162:163], v[134:135], v[162:163], v[166:167]
	v_pk_fma_f32 v[164:165], v[136:137], v[164:165], v[168:169]
	s_nop 0
	global_store_dwordx4 v238, v[162:165], s[30:31] offset:0 nt
	s_nop 1
	v_lshlrev_b32_e32 v162, 16, v68
	v_and_b32_e32 v163, 0xffff0000, v68
	v_lshlrev_b32_e32 v164, 16, v69
	v_and_b32_e32 v165, 0xffff0000, v69
	v_lshlrev_b32_e32 v166, 16, v100
	v_and_b32_e32 v167, 0xffff0000, v100
	v_lshlrev_b32_e32 v168, 16, v101
	v_and_b32_e32 v169, 0xffff0000, v101
	v_pk_mul_f32 v[162:163], v[162:163], v[252:253] op_sel_hi:[1,0]
	v_pk_mul_f32 v[164:165], v[164:165], v[252:253] op_sel_hi:[1,0]
	v_pk_mul_f32 v[162:163], v[162:163], v[138:139]
	v_pk_mul_f32 v[164:165], v[164:165], v[140:141]
	v_pk_fma_f32 v[162:163], v[142:143], v[162:163], v[166:167]
	v_pk_fma_f32 v[164:165], v[144:145], v[164:165], v[168:169]
	s_nop 0
	global_store_dwordx4 v238, v[162:165], s[30:31] offset:1024 nt
	s_nop 1
	ds_read_b128 v[130:133], v238 offset:4096
	ds_read_b128 v[134:137], v238 offset:20480
	ds_read_b128 v[138:141], v238 offset:5120
	ds_read_b128 v[142:145], v238 offset:21504
	s_waitcnt lgkmcnt(4)
	v_lshlrev_b32_e32 v162, 16, v70
	v_and_b32_e32 v163, 0xffff0000, v70
	v_lshlrev_b32_e32 v164, 16, v71
	v_and_b32_e32 v165, 0xffff0000, v71
	v_lshlrev_b32_e32 v166, 16, v102
	v_and_b32_e32 v167, 0xffff0000, v102
	v_lshlrev_b32_e32 v168, 16, v103
	v_and_b32_e32 v169, 0xffff0000, v103
	v_pk_mul_f32 v[162:163], v[162:163], v[252:253] op_sel_hi:[1,0]
	v_pk_mul_f32 v[164:165], v[164:165], v[252:253] op_sel_hi:[1,0]
	v_pk_mul_f32 v[162:163], v[162:163], v[146:147]
	v_pk_mul_f32 v[164:165], v[164:165], v[148:149]
	v_pk_fma_f32 v[162:163], v[150:151], v[162:163], v[166:167]
	v_pk_fma_f32 v[164:165], v[152:153], v[164:165], v[168:169]
	s_nop 0
	global_store_dwordx4 v238, v[162:165], s[30:31] offset:2048 nt
	s_nop 1
	v_lshlrev_b32_e32 v162, 16, v72
	v_and_b32_e32 v163, 0xffff0000, v72
	v_lshlrev_b32_e32 v164, 16, v73
	v_and_b32_e32 v165, 0xffff0000, v73
	v_lshlrev_b32_e32 v166, 16, v104
	v_and_b32_e32 v167, 0xffff0000, v104
	v_lshlrev_b32_e32 v168, 16, v105
	v_and_b32_e32 v169, 0xffff0000, v105
	v_pk_mul_f32 v[162:163], v[162:163], v[252:253] op_sel_hi:[1,0]
	v_pk_mul_f32 v[164:165], v[164:165], v[252:253] op_sel_hi:[1,0]
	v_pk_mul_f32 v[162:163], v[162:163], v[154:155]
	v_pk_mul_f32 v[164:165], v[164:165], v[156:157]
	v_pk_fma_f32 v[162:163], v[158:159], v[162:163], v[166:167]
	v_pk_fma_f32 v[164:165], v[160:161], v[164:165], v[168:169]
	s_nop 0
	global_store_dwordx4 v238, v[162:165], s[30:31] offset:3072 nt
	s_nop 1
	ds_read_b128 v[146:149], v238 offset:6144
	ds_read_b128 v[150:153], v238 offset:22528
	ds_read_b128 v[154:157], v238 offset:7168
	ds_read_b128 v[158:161], v238 offset:23552
	s_waitcnt lgkmcnt(4)
	v_lshlrev_b32_e32 v162, 16, v74
	v_and_b32_e32 v163, 0xffff0000, v74
	v_lshlrev_b32_e32 v164, 16, v75
	v_and_b32_e32 v165, 0xffff0000, v75
	v_lshlrev_b32_e32 v166, 16, v106
	v_and_b32_e32 v167, 0xffff0000, v106
	v_lshlrev_b32_e32 v168, 16, v107
	v_and_b32_e32 v169, 0xffff0000, v107
	v_pk_mul_f32 v[162:163], v[162:163], v[252:253] op_sel_hi:[1,0]
	v_pk_mul_f32 v[164:165], v[164:165], v[252:253] op_sel_hi:[1,0]
	v_pk_mul_f32 v[162:163], v[162:163], v[130:131]
	v_pk_mul_f32 v[164:165], v[164:165], v[132:133]
	v_pk_fma_f32 v[162:163], v[134:135], v[162:163], v[166:167]
	v_pk_fma_f32 v[164:165], v[136:137], v[164:165], v[168:169]
	s_nop 0
	global_store_dwordx4 v241, v[162:165], s[30:31] offset:0 nt
	s_nop 1
	v_lshlrev_b32_e32 v162, 16, v76
	v_and_b32_e32 v163, 0xffff0000, v76
	v_lshlrev_b32_e32 v164, 16, v77
	v_and_b32_e32 v165, 0xffff0000, v77
	v_lshlrev_b32_e32 v166, 16, v108
	v_and_b32_e32 v167, 0xffff0000, v108
	v_lshlrev_b32_e32 v168, 16, v109
	v_and_b32_e32 v169, 0xffff0000, v109
	v_pk_mul_f32 v[162:163], v[162:163], v[252:253] op_sel_hi:[1,0]
	v_pk_mul_f32 v[164:165], v[164:165], v[252:253] op_sel_hi:[1,0]
	v_pk_mul_f32 v[162:163], v[162:163], v[138:139]
	v_pk_mul_f32 v[164:165], v[164:165], v[140:141]
	v_pk_fma_f32 v[162:163], v[142:143], v[162:163], v[166:167]
	v_pk_fma_f32 v[164:165], v[144:145], v[164:165], v[168:169]
	s_nop 0
	global_store_dwordx4 v241, v[162:165], s[30:31] offset:1024 nt
	s_nop 1
	ds_read_b128 v[130:133], v238 offset:8192
	ds_read_b128 v[134:137], v238 offset:24576
	ds_read_b128 v[138:141], v238 offset:9216
	ds_read_b128 v[142:145], v238 offset:25600
	s_waitcnt lgkmcnt(4)
	v_lshlrev_b32_e32 v162, 16, v78
	v_and_b32_e32 v163, 0xffff0000, v78
	v_lshlrev_b32_e32 v164, 16, v79
	v_and_b32_e32 v165, 0xffff0000, v79
	v_lshlrev_b32_e32 v166, 16, v110
	v_and_b32_e32 v167, 0xffff0000, v110
	v_lshlrev_b32_e32 v168, 16, v111
	v_and_b32_e32 v169, 0xffff0000, v111
	v_pk_mul_f32 v[162:163], v[162:163], v[252:253] op_sel_hi:[1,0]
	v_pk_mul_f32 v[164:165], v[164:165], v[252:253] op_sel_hi:[1,0]
	v_pk_mul_f32 v[162:163], v[162:163], v[146:147]
	v_pk_mul_f32 v[164:165], v[164:165], v[148:149]
	v_pk_fma_f32 v[162:163], v[150:151], v[162:163], v[166:167]
	v_pk_fma_f32 v[164:165], v[152:153], v[164:165], v[168:169]
	s_nop 0
	global_store_dwordx4 v241, v[162:165], s[30:31] offset:2048 nt
	s_nop 1
	v_lshlrev_b32_e32 v162, 16, v80
	v_and_b32_e32 v163, 0xffff0000, v80
	v_lshlrev_b32_e32 v164, 16, v81
	v_and_b32_e32 v165, 0xffff0000, v81
	v_lshlrev_b32_e32 v166, 16, v112
	v_and_b32_e32 v167, 0xffff0000, v112
	v_lshlrev_b32_e32 v168, 16, v113
	v_and_b32_e32 v169, 0xffff0000, v113
	v_pk_mul_f32 v[162:163], v[162:163], v[252:253] op_sel_hi:[1,0]
	v_pk_mul_f32 v[164:165], v[164:165], v[252:253] op_sel_hi:[1,0]
	v_pk_mul_f32 v[162:163], v[162:163], v[154:155]
	v_pk_mul_f32 v[164:165], v[164:165], v[156:157]
	v_pk_fma_f32 v[162:163], v[158:159], v[162:163], v[166:167]
	v_pk_fma_f32 v[164:165], v[160:161], v[164:165], v[168:169]
	s_nop 0
	global_store_dwordx4 v241, v[162:165], s[30:31] offset:3072 nt
	s_nop 1
	ds_read_b128 v[146:149], v238 offset:10240
	ds_read_b128 v[150:153], v238 offset:26624
	ds_read_b128 v[154:157], v238 offset:11264
	ds_read_b128 v[158:161], v238 offset:27648
	s_waitcnt lgkmcnt(4)
	v_lshlrev_b32_e32 v162, 16, v82
	v_and_b32_e32 v163, 0xffff0000, v82
	v_lshlrev_b32_e32 v164, 16, v83
	v_and_b32_e32 v165, 0xffff0000, v83
	v_lshlrev_b32_e32 v166, 16, v114
	v_and_b32_e32 v167, 0xffff0000, v114
	v_lshlrev_b32_e32 v168, 16, v115
	v_and_b32_e32 v169, 0xffff0000, v115
	v_pk_mul_f32 v[162:163], v[162:163], v[252:253] op_sel_hi:[1,0]
	v_pk_mul_f32 v[164:165], v[164:165], v[252:253] op_sel_hi:[1,0]
	v_pk_mul_f32 v[162:163], v[162:163], v[130:131]
	v_pk_mul_f32 v[164:165], v[164:165], v[132:133]
	v_pk_fma_f32 v[162:163], v[134:135], v[162:163], v[166:167]
	v_pk_fma_f32 v[164:165], v[136:137], v[164:165], v[168:169]
	s_nop 0
	global_store_dwordx4 v242, v[162:165], s[30:31] offset:0 nt
	s_nop 1
	v_lshlrev_b32_e32 v162, 16, v84
	v_and_b32_e32 v163, 0xffff0000, v84
	v_lshlrev_b32_e32 v164, 16, v85
	v_and_b32_e32 v165, 0xffff0000, v85
	v_lshlrev_b32_e32 v166, 16, v116
	v_and_b32_e32 v167, 0xffff0000, v116
	v_lshlrev_b32_e32 v168, 16, v117
	v_and_b32_e32 v169, 0xffff0000, v117
	v_pk_mul_f32 v[162:163], v[162:163], v[252:253] op_sel_hi:[1,0]
	v_pk_mul_f32 v[164:165], v[164:165], v[252:253] op_sel_hi:[1,0]
	v_pk_mul_f32 v[162:163], v[162:163], v[138:139]
	v_pk_mul_f32 v[164:165], v[164:165], v[140:141]
	v_pk_fma_f32 v[162:163], v[142:143], v[162:163], v[166:167]
	v_pk_fma_f32 v[164:165], v[144:145], v[164:165], v[168:169]
	s_nop 0
	global_store_dwordx4 v242, v[162:165], s[30:31] offset:1024 nt
	s_nop 1
	ds_read_b128 v[130:133], v238 offset:12288
	ds_read_b128 v[134:137], v238 offset:28672
	ds_read_b128 v[138:141], v238 offset:13312
	ds_read_b128 v[142:145], v238 offset:29696
	s_waitcnt lgkmcnt(4)
	v_lshlrev_b32_e32 v162, 16, v86
	v_and_b32_e32 v163, 0xffff0000, v86
	v_lshlrev_b32_e32 v164, 16, v87
	v_and_b32_e32 v165, 0xffff0000, v87
	v_lshlrev_b32_e32 v166, 16, v118
	v_and_b32_e32 v167, 0xffff0000, v118
	v_lshlrev_b32_e32 v168, 16, v119
	v_and_b32_e32 v169, 0xffff0000, v119
	v_pk_mul_f32 v[162:163], v[162:163], v[252:253] op_sel_hi:[1,0]
	v_pk_mul_f32 v[164:165], v[164:165], v[252:253] op_sel_hi:[1,0]
	v_pk_mul_f32 v[162:163], v[162:163], v[146:147]
	v_pk_mul_f32 v[164:165], v[164:165], v[148:149]
	v_pk_fma_f32 v[162:163], v[150:151], v[162:163], v[166:167]
	v_pk_fma_f32 v[164:165], v[152:153], v[164:165], v[168:169]
	s_nop 0
	global_store_dwordx4 v242, v[162:165], s[30:31] offset:2048 nt
	s_nop 1
	v_lshlrev_b32_e32 v162, 16, v88
	v_and_b32_e32 v163, 0xffff0000, v88
	v_lshlrev_b32_e32 v164, 16, v89
	v_and_b32_e32 v165, 0xffff0000, v89
	v_lshlrev_b32_e32 v166, 16, v120
	v_and_b32_e32 v167, 0xffff0000, v120
	v_lshlrev_b32_e32 v168, 16, v121
	v_and_b32_e32 v169, 0xffff0000, v121
	v_pk_mul_f32 v[162:163], v[162:163], v[252:253] op_sel_hi:[1,0]
	v_pk_mul_f32 v[164:165], v[164:165], v[252:253] op_sel_hi:[1,0]
	v_pk_mul_f32 v[162:163], v[162:163], v[154:155]
	v_pk_mul_f32 v[164:165], v[164:165], v[156:157]
	v_pk_fma_f32 v[162:163], v[158:159], v[162:163], v[166:167]
	v_pk_fma_f32 v[164:165], v[160:161], v[164:165], v[168:169]
	s_nop 0
	global_store_dwordx4 v242, v[162:165], s[30:31] offset:3072 nt
	s_nop 1
	ds_read_b128 v[146:149], v238 offset:14336
	ds_read_b128 v[150:153], v238 offset:30720
	ds_read_b128 v[154:157], v238 offset:15360
	ds_read_b128 v[158:161], v238 offset:31744
	s_waitcnt lgkmcnt(4)
	v_lshlrev_b32_e32 v162, 16, v90
	v_and_b32_e32 v163, 0xffff0000, v90
	v_lshlrev_b32_e32 v164, 16, v91
	v_and_b32_e32 v165, 0xffff0000, v91
	v_lshlrev_b32_e32 v166, 16, v122
	v_and_b32_e32 v167, 0xffff0000, v122
	v_lshlrev_b32_e32 v168, 16, v123
	v_and_b32_e32 v169, 0xffff0000, v123
	v_pk_mul_f32 v[162:163], v[162:163], v[252:253] op_sel_hi:[1,0]
	v_pk_mul_f32 v[164:165], v[164:165], v[252:253] op_sel_hi:[1,0]
	v_pk_mul_f32 v[162:163], v[162:163], v[130:131]
	v_pk_mul_f32 v[164:165], v[164:165], v[132:133]
	v_pk_fma_f32 v[162:163], v[134:135], v[162:163], v[166:167]
	v_pk_fma_f32 v[164:165], v[136:137], v[164:165], v[168:169]
	s_nop 0
	global_store_dwordx4 v243, v[162:165], s[30:31] offset:0 nt
	s_nop 1
	v_lshlrev_b32_e32 v162, 16, v92
	v_and_b32_e32 v163, 0xffff0000, v92
	v_lshlrev_b32_e32 v164, 16, v93
	v_and_b32_e32 v165, 0xffff0000, v93
	v_lshlrev_b32_e32 v166, 16, v124
	v_and_b32_e32 v167, 0xffff0000, v124
	v_lshlrev_b32_e32 v168, 16, v125
	v_and_b32_e32 v169, 0xffff0000, v125
	v_pk_mul_f32 v[162:163], v[162:163], v[252:253] op_sel_hi:[1,0]
	v_pk_mul_f32 v[164:165], v[164:165], v[252:253] op_sel_hi:[1,0]
	v_pk_mul_f32 v[162:163], v[162:163], v[138:139]
	v_pk_mul_f32 v[164:165], v[164:165], v[140:141]
	v_pk_fma_f32 v[162:163], v[142:143], v[162:163], v[166:167]
	v_pk_fma_f32 v[164:165], v[144:145], v[164:165], v[168:169]
	s_nop 0
	global_store_dwordx4 v243, v[162:165], s[30:31] offset:1024 nt
	s_nop 1
	s_waitcnt lgkmcnt(0)
	v_lshlrev_b32_e32 v162, 16, v94
	v_and_b32_e32 v163, 0xffff0000, v94
	v_lshlrev_b32_e32 v164, 16, v95
	v_and_b32_e32 v165, 0xffff0000, v95
	v_lshlrev_b32_e32 v166, 16, v126
	v_and_b32_e32 v167, 0xffff0000, v126
	v_lshlrev_b32_e32 v168, 16, v127
	v_and_b32_e32 v169, 0xffff0000, v127
	v_pk_mul_f32 v[162:163], v[162:163], v[252:253] op_sel_hi:[1,0]
	v_pk_mul_f32 v[164:165], v[164:165], v[252:253] op_sel_hi:[1,0]
	v_pk_mul_f32 v[162:163], v[162:163], v[146:147]
	v_pk_mul_f32 v[164:165], v[164:165], v[148:149]
	v_pk_fma_f32 v[162:163], v[150:151], v[162:163], v[166:167]
	v_pk_fma_f32 v[164:165], v[152:153], v[164:165], v[168:169]
	s_nop 0
	global_store_dwordx4 v243, v[162:165], s[30:31] offset:2048 nt
	s_nop 1
	v_lshlrev_b32_e32 v162, 16, v96
	v_and_b32_e32 v163, 0xffff0000, v96
	v_lshlrev_b32_e32 v164, 16, v97
	v_and_b32_e32 v165, 0xffff0000, v97
	v_lshlrev_b32_e32 v166, 16, v128
	v_and_b32_e32 v167, 0xffff0000, v128
	v_lshlrev_b32_e32 v168, 16, v129
	v_and_b32_e32 v169, 0xffff0000, v129
	v_pk_mul_f32 v[162:163], v[162:163], v[252:253] op_sel_hi:[1,0]
	v_pk_mul_f32 v[164:165], v[164:165], v[252:253] op_sel_hi:[1,0]
	v_pk_mul_f32 v[162:163], v[162:163], v[154:155]
	v_pk_mul_f32 v[164:165], v[164:165], v[156:157]
	v_pk_fma_f32 v[162:163], v[158:159], v[162:163], v[166:167]
	v_pk_fma_f32 v[164:165], v[160:161], v[164:165], v[168:169]
	s_nop 0
	global_store_dwordx4 v243, v[162:165], s[30:31] offset:3072 nt
	s_nop 1
	s_add_u32 s30, s30, 0x2000000
	s_addc_u32 s31, s31, 0
	s_waitcnt vmcnt(16)
	s_add_u32 s22, s22, 0x1000000
	s_addc_u32 s23, s23, 0
	s_add_u32 s24, s24, 0x1000000
	s_addc_u32 s25, s25, 0
	global_load_dwordx2 v[66:67], v244, s[22:23] offset:0
	global_load_dwordx2 v[68:69], v244, s[22:23] offset:512
	global_load_dwordx2 v[70:71], v244, s[22:23] offset:1024
	global_load_dwordx2 v[72:73], v244, s[22:23] offset:1536
	global_load_dwordx2 v[74:75], v244, s[22:23] offset:2048
	global_load_dwordx2 v[76:77], v244, s[22:23] offset:2560
	global_load_dwordx2 v[78:79], v244, s[22:23] offset:3072
	global_load_dwordx2 v[80:81], v244, s[22:23] offset:3584
	global_load_dwordx2 v[82:83], v245, s[22:23] offset:0
	global_load_dwordx2 v[84:85], v245, s[22:23] offset:512
	global_load_dwordx2 v[86:87], v245, s[22:23] offset:1024
	global_load_dwordx2 v[88:89], v245, s[22:23] offset:1536
	global_load_dwordx2 v[90:91], v245, s[22:23] offset:2048
	global_load_dwordx2 v[92:93], v245, s[22:23] offset:2560
	global_load_dwordx2 v[94:95], v245, s[22:23] offset:3072
	global_load_dwordx2 v[96:97], v245, s[22:23] offset:3584
	global_load_dwordx2 v[98:99], v244, s[24:25] offset:0
	global_load_dwordx2 v[100:101], v244, s[24:25] offset:512
	global_load_dwordx2 v[102:103], v244, s[24:25] offset:1024
	global_load_dwordx2 v[104:105], v244, s[24:25] offset:1536
	global_load_dwordx2 v[106:107], v244, s[24:25] offset:2048
	global_load_dwordx2 v[108:109], v244, s[24:25] offset:2560
	global_load_dwordx2 v[110:111], v244, s[24:25] offset:3072
	global_load_dwordx2 v[112:113], v244, s[24:25] offset:3584
	global_load_dwordx2 v[114:115], v245, s[24:25] offset:0
	global_load_dwordx2 v[116:117], v245, s[24:25] offset:512
	global_load_dwordx2 v[118:119], v245, s[24:25] offset:1024
	global_load_dwordx2 v[120:121], v245, s[24:25] offset:1536
	global_load_dwordx2 v[122:123], v245, s[24:25] offset:2048
	global_load_dwordx2 v[124:125], v245, s[24:25] offset:2560
	global_load_dwordx2 v[126:127], v245, s[24:25] offset:3072
	global_load_dwordx2 v[128:129], v245, s[24:25] offset:3584
	ds_read_b128 v[130:133], v238 offset:0
	ds_read_b128 v[134:137], v238 offset:32768
	ds_read_b128 v[138:141], v238 offset:1024
	ds_read_b128 v[142:145], v238 offset:33792
	v_lshlrev_b32_e32 v162, 16, v2
	v_and_b32_e32 v163, 0xffff0000, v2
	v_lshlrev_b32_e32 v164, 16, v3
	v_and_b32_e32 v165, 0xffff0000, v3
	v_pk_mul_f32 v[176:177], v[162:163], v[162:163]
	v_pk_mul_f32 v[178:179], v[164:165], v[164:165]
	v_lshlrev_b32_e32 v166, 16, v4
	v_and_b32_e32 v167, 0xffff0000, v4
	v_lshlrev_b32_e32 v168, 16, v5
	v_and_b32_e32 v169, 0xffff0000, v5
	v_pk_fma_f32 v[176:177], v[166:167], v[166:167], v[176:177]
	v_pk_fma_f32 v[178:179], v[168:169], v[168:169], v[178:179]
	v_lshlrev_b32_e32 v162, 16, v6
	v_and_b32_e32 v163, 0xffff0000, v6
	v_lshlrev_b32_e32 v164, 16, v7
	v_and_b32_e32 v165, 0xffff0000, v7
	v_pk_fma_f32 v[176:177], v[162:163], v[162:163], v[176:177]
	v_pk_fma_f32 v[178:179], v[164:165], v[164:165], v[178:179]
	v_lshlrev_b32_e32 v166, 16, v8
	v_and_b32_e32 v167, 0xffff0000, v8
	v_lshlrev_b32_e32 v168, 16, v9
	v_and_b32_e32 v169, 0xffff0000, v9
	v_pk_fma_f32 v[176:177], v[166:167], v[166:167], v[176:177]
	v_pk_fma_f32 v[178:179], v[168:169], v[168:169], v[178:179]
	v_lshlrev_b32_e32 v162, 16, v10
	v_and_b32_e32 v163, 0xffff0000, v10
	v_lshlrev_b32_e32 v164, 16, v11
	v_and_b32_e32 v165, 0xffff0000, v11
	v_pk_fma_f32 v[176:177], v[162:163], v[162:163], v[176:177]
	v_pk_fma_f32 v[178:179], v[164:165], v[164:165], v[178:179]
	v_lshlrev_b32_e32 v166, 16, v12
	v_and_b32_e32 v167, 0xffff0000, v12
	v_lshlrev_b32_e32 v168, 16, v13
	v_and_b32_e32 v169, 0xffff0000, v13
	v_pk_fma_f32 v[176:177], v[166:167], v[166:167], v[176:177]
	v_pk_fma_f32 v[178:179], v[168:169], v[168:169], v[178:179]
	v_lshlrev_b32_e32 v162, 16, v14
	v_and_b32_e32 v163, 0xffff0000, v14
	v_lshlrev_b32_e32 v164, 16, v15
	v_and_b32_e32 v165, 0xffff0000, v15
	v_pk_fma_f32 v[176:177], v[162:163], v[162:163], v[176:177]
	v_pk_fma_f32 v[178:179], v[164:165], v[164:165], v[178:179]
	v_lshlrev_b32_e32 v166, 16, v16
	v_and_b32_e32 v167, 0xffff0000, v16
	v_lshlrev_b32_e32 v168, 16, v17
	v_and_b32_e32 v169, 0xffff0000, v17
	v_pk_fma_f32 v[176:177], v[166:167], v[166:167], v[176:177]
	v_pk_fma_f32 v[178:179], v[168:169], v[168:169], v[178:179]
	v_lshlrev_b32_e32 v162, 16, v18
	v_and_b32_e32 v163, 0xffff0000, v18
	v_lshlrev_b32_e32 v164, 16, v19
	v_and_b32_e32 v165, 0xffff0000, v19
	v_pk_fma_f32 v[176:177], v[162:163], v[162:163], v[176:177]
	v_pk_fma_f32 v[178:179], v[164:165], v[164:165], v[178:179]
	v_lshlrev_b32_e32 v166, 16, v20
	v_and_b32_e32 v167, 0xffff0000, v20
	v_lshlrev_b32_e32 v168, 16, v21
	v_and_b32_e32 v169, 0xffff0000, v21
	v_pk_fma_f32 v[176:177], v[166:167], v[166:167], v[176:177]
	v_pk_fma_f32 v[178:179], v[168:169], v[168:169], v[178:179]
	v_lshlrev_b32_e32 v162, 16, v22
	v_and_b32_e32 v163, 0xffff0000, v22
	v_lshlrev_b32_e32 v164, 16, v23
	v_and_b32_e32 v165, 0xffff0000, v23
	v_pk_fma_f32 v[176:177], v[162:163], v[162:163], v[176:177]
	v_pk_fma_f32 v[178:179], v[164:165], v[164:165], v[178:179]
	v_lshlrev_b32_e32 v166, 16, v24
	v_and_b32_e32 v167, 0xffff0000, v24
	v_lshlrev_b32_e32 v168, 16, v25
	v_and_b32_e32 v169, 0xffff0000, v25
	v_pk_fma_f32 v[176:177], v[166:167], v[166:167], v[176:177]
	v_pk_fma_f32 v[178:179], v[168:169], v[168:169], v[178:179]
	v_lshlrev_b32_e32 v162, 16, v26
	v_and_b32_e32 v163, 0xffff0000, v26
	v_lshlrev_b32_e32 v164, 16, v27
	v_and_b32_e32 v165, 0xffff0000, v27
	v_pk_fma_f32 v[176:177], v[162:163], v[162:163], v[176:177]
	v_pk_fma_f32 v[178:179], v[164:165], v[164:165], v[178:179]
	v_lshlrev_b32_e32 v166, 16, v28
	v_and_b32_e32 v167, 0xffff0000, v28
	v_lshlrev_b32_e32 v168, 16, v29
	v_and_b32_e32 v169, 0xffff0000, v29
	v_pk_fma_f32 v[176:177], v[166:167], v[166:167], v[176:177]
	v_pk_fma_f32 v[178:179], v[168:169], v[168:169], v[178:179]
	v_lshlrev_b32_e32 v162, 16, v30
	v_and_b32_e32 v163, 0xffff0000, v30
	v_lshlrev_b32_e32 v164, 16, v31
	v_and_b32_e32 v165, 0xffff0000, v31
	v_pk_fma_f32 v[176:177], v[162:163], v[162:163], v[176:177]
	v_pk_fma_f32 v[178:179], v[164:165], v[164:165], v[178:179]
	v_lshlrev_b32_e32 v166, 16, v32
	v_and_b32_e32 v167, 0xffff0000, v32
	v_lshlrev_b32_e32 v168, 16, v33
	v_and_b32_e32 v169, 0xffff0000, v33
	v_pk_fma_f32 v[176:177], v[166:167], v[166:167], v[176:177]
	v_pk_fma_f32 v[178:179], v[168:169], v[168:169], v[178:179]
	v_pk_add_f32 v[176:177], v[176:177], v[178:179]
	s_nop 0
	v_add_f32_e32 v252, v176, v177
	s_waitcnt lgkmcnt(0)
	ds_bpermute_b32 v254, v246, v252
	s_waitcnt lgkmcnt(0)
	v_add_f32_e32 v252, v252, v254
	ds_bpermute_b32 v254, v247, v252
	s_waitcnt lgkmcnt(0)
	v_add_f32_e32 v252, v252, v254
	ds_bpermute_b32 v254, v248, v252
	s_waitcnt lgkmcnt(0)
	v_add_f32_e32 v252, v252, v254
	ds_bpermute_b32 v254, v249, v252
	s_waitcnt lgkmcnt(0)
	v_add_f32_e32 v252, v252, v254
	ds_bpermute_b32 v254, v250, v252
	s_waitcnt lgkmcnt(0)
	v_add_f32_e32 v252, v252, v254
	ds_bpermute_b32 v254, v251, v252
	s_waitcnt lgkmcnt(0)
	v_add_f32_e32 v252, v252, v254
	v_mov_b32_e32 v254, 0x358637bd
	v_fmac_f32_e32 v254, 0x39800000, v252
	v_mul_f32_e32 v252, 0x4b800000, v254
	v_cmp_gt_f32_e32 vcc, s20, v254
	s_nop 1
	v_cndmask_b32_e32 v254, v254, v252, vcc
	v_rsq_f32_e32 v254, v254
	s_nop 0
	v_mul_f32_e32 v252, 0x45800000, v254
	v_cndmask_b32_e32 v252, v254, v252, vcc
	ds_read_b128 v[146:149], v238 offset:2048
	ds_read_b128 v[150:153], v238 offset:34816
	ds_read_b128 v[154:157], v238 offset:3072
	ds_read_b128 v[158:161], v238 offset:35840
	s_waitcnt lgkmcnt(4)
	v_lshlrev_b32_e32 v162, 16, v2
	v_and_b32_e32 v163, 0xffff0000, v2
	v_lshlrev_b32_e32 v164, 16, v3
	v_and_b32_e32 v165, 0xffff0000, v3
	v_lshlrev_b32_e32 v166, 16, v34
	v_and_b32_e32 v167, 0xffff0000, v34
	v_lshlrev_b32_e32 v168, 16, v35
	v_and_b32_e32 v169, 0xffff0000, v35
	v_pk_mul_f32 v[162:163], v[162:163], v[252:253] op_sel_hi:[1,0]
	v_pk_mul_f32 v[164:165], v[164:165], v[252:253] op_sel_hi:[1,0]
	v_pk_mul_f32 v[162:163], v[162:163], v[130:131]
	v_pk_mul_f32 v[164:165], v[164:165], v[132:133]
	v_pk_fma_f32 v[162:163], v[134:135], v[162:163], v[166:167]
	v_pk_fma_f32 v[164:165], v[136:137], v[164:165], v[168:169]
	s_nop 0
	global_store_dwordx4 v238, v[162:165], s[30:31] offset:0 nt
	s_nop 1
	v_lshlrev_b32_e32 v162, 16, v4
	v_and_b32_e32 v163, 0xffff0000, v4
	v_lshlrev_b32_e32 v164, 16, v5
	v_and_b32_e32 v165, 0xffff0000, v5
	v_lshlrev_b32_e32 v166, 16, v36
	v_and_b32_e32 v167, 0xffff0000, v36
	v_lshlrev_b32_e32 v168, 16, v37
	v_and_b32_e32 v169, 0xffff0000, v37
	v_pk_mul_f32 v[162:163], v[162:163], v[252:253] op_sel_hi:[1,0]
	v_pk_mul_f32 v[164:165], v[164:165], v[252:253] op_sel_hi:[1,0]
	v_pk_mul_f32 v[162:163], v[162:163], v[138:139]
	v_pk_mul_f32 v[164:165], v[164:165], v[140:141]
	v_pk_fma_f32 v[162:163], v[142:143], v[162:163], v[166:167]
	v_pk_fma_f32 v[164:165], v[144:145], v[164:165], v[168:169]
	s_nop 0
	global_store_dwordx4 v238, v[162:165], s[30:31] offset:1024 nt
	s_nop 1
	ds_read_b128 v[130:133], v238 offset:4096
	ds_read_b128 v[134:137], v238 offset:36864
	ds_read_b128 v[138:141], v238 offset:5120
	ds_read_b128 v[142:145], v238 offset:37888
	s_waitcnt lgkmcnt(4)
	v_lshlrev_b32_e32 v162, 16, v6
	v_and_b32_e32 v163, 0xffff0000, v6
	v_lshlrev_b32_e32 v164, 16, v7
	v_and_b32_e32 v165, 0xffff0000, v7
	v_lshlrev_b32_e32 v166, 16, v38
	v_and_b32_e32 v167, 0xffff0000, v38
	v_lshlrev_b32_e32 v168, 16, v39
	v_and_b32_e32 v169, 0xffff0000, v39
	v_pk_mul_f32 v[162:163], v[162:163], v[252:253] op_sel_hi:[1,0]
	v_pk_mul_f32 v[164:165], v[164:165], v[252:253] op_sel_hi:[1,0]
	v_pk_mul_f32 v[162:163], v[162:163], v[146:147]
	v_pk_mul_f32 v[164:165], v[164:165], v[148:149]
	v_pk_fma_f32 v[162:163], v[150:151], v[162:163], v[166:167]
	v_pk_fma_f32 v[164:165], v[152:153], v[164:165], v[168:169]
	s_nop 0
	global_store_dwordx4 v238, v[162:165], s[30:31] offset:2048 nt
	s_nop 1
	v_lshlrev_b32_e32 v162, 16, v8
	v_and_b32_e32 v163, 0xffff0000, v8
	v_lshlrev_b32_e32 v164, 16, v9
	v_and_b32_e32 v165, 0xffff0000, v9
	v_lshlrev_b32_e32 v166, 16, v40
	v_and_b32_e32 v167, 0xffff0000, v40
	v_lshlrev_b32_e32 v168, 16, v41
	v_and_b32_e32 v169, 0xffff0000, v41
	v_pk_mul_f32 v[162:163], v[162:163], v[252:253] op_sel_hi:[1,0]
	v_pk_mul_f32 v[164:165], v[164:165], v[252:253] op_sel_hi:[1,0]
	v_pk_mul_f32 v[162:163], v[162:163], v[154:155]
	v_pk_mul_f32 v[164:165], v[164:165], v[156:157]
	v_pk_fma_f32 v[162:163], v[158:159], v[162:163], v[166:167]
	v_pk_fma_f32 v[164:165], v[160:161], v[164:165], v[168:169]
	s_nop 0
	global_store_dwordx4 v238, v[162:165], s[30:31] offset:3072 nt
	s_nop 1
	ds_read_b128 v[146:149], v238 offset:6144
	ds_read_b128 v[150:153], v238 offset:38912
	ds_read_b128 v[154:157], v238 offset:7168
	ds_read_b128 v[158:161], v238 offset:39936
	s_waitcnt lgkmcnt(4)
	v_lshlrev_b32_e32 v162, 16, v10
	v_and_b32_e32 v163, 0xffff0000, v10
	v_lshlrev_b32_e32 v164, 16, v11
	v_and_b32_e32 v165, 0xffff0000, v11
	v_lshlrev_b32_e32 v166, 16, v42
	v_and_b32_e32 v167, 0xffff0000, v42
	v_lshlrev_b32_e32 v168, 16, v43
	v_and_b32_e32 v169, 0xffff0000, v43
	v_pk_mul_f32 v[162:163], v[162:163], v[252:253] op_sel_hi:[1,0]
	v_pk_mul_f32 v[164:165], v[164:165], v[252:253] op_sel_hi:[1,0]
	v_pk_mul_f32 v[162:163], v[162:163], v[130:131]
	v_pk_mul_f32 v[164:165], v[164:165], v[132:133]
	v_pk_fma_f32 v[162:163], v[134:135], v[162:163], v[166:167]
	v_pk_fma_f32 v[164:165], v[136:137], v[164:165], v[168:169]
	s_nop 0
	global_store_dwordx4 v241, v[162:165], s[30:31] offset:0 nt
	s_nop 1
	v_lshlrev_b32_e32 v162, 16, v12
	v_and_b32_e32 v163, 0xffff0000, v12
	v_lshlrev_b32_e32 v164, 16, v13
	v_and_b32_e32 v165, 0xffff0000, v13
	v_lshlrev_b32_e32 v166, 16, v44
	v_and_b32_e32 v167, 0xffff0000, v44
	v_lshlrev_b32_e32 v168, 16, v45
	v_and_b32_e32 v169, 0xffff0000, v45
	v_pk_mul_f32 v[162:163], v[162:163], v[252:253] op_sel_hi:[1,0]
	v_pk_mul_f32 v[164:165], v[164:165], v[252:253] op_sel_hi:[1,0]
	v_pk_mul_f32 v[162:163], v[162:163], v[138:139]
	v_pk_mul_f32 v[164:165], v[164:165], v[140:141]
	v_pk_fma_f32 v[162:163], v[142:143], v[162:163], v[166:167]
	v_pk_fma_f32 v[164:165], v[144:145], v[164:165], v[168:169]
	s_nop 0
	global_store_dwordx4 v241, v[162:165], s[30:31] offset:1024 nt
	s_nop 1
	ds_read_b128 v[130:133], v238 offset:8192
	ds_read_b128 v[134:137], v238 offset:40960
	ds_read_b128 v[138:141], v238 offset:9216
	ds_read_b128 v[142:145], v238 offset:41984
	s_waitcnt lgkmcnt(4)
	v_lshlrev_b32_e32 v162, 16, v14
	v_and_b32_e32 v163, 0xffff0000, v14
	v_lshlrev_b32_e32 v164, 16, v15
	v_and_b32_e32 v165, 0xffff0000, v15
	v_lshlrev_b32_e32 v166, 16, v46
	v_and_b32_e32 v167, 0xffff0000, v46
	v_lshlrev_b32_e32 v168, 16, v47
	v_and_b32_e32 v169, 0xffff0000, v47
	v_pk_mul_f32 v[162:163], v[162:163], v[252:253] op_sel_hi:[1,0]
	v_pk_mul_f32 v[164:165], v[164:165], v[252:253] op_sel_hi:[1,0]
	v_pk_mul_f32 v[162:163], v[162:163], v[146:147]
	v_pk_mul_f32 v[164:165], v[164:165], v[148:149]
	v_pk_fma_f32 v[162:163], v[150:151], v[162:163], v[166:167]
	v_pk_fma_f32 v[164:165], v[152:153], v[164:165], v[168:169]
	s_nop 0
	global_store_dwordx4 v241, v[162:165], s[30:31] offset:2048 nt
	s_nop 1
	v_lshlrev_b32_e32 v162, 16, v16
	v_and_b32_e32 v163, 0xffff0000, v16
	v_lshlrev_b32_e32 v164, 16, v17
	v_and_b32_e32 v165, 0xffff0000, v17
	v_lshlrev_b32_e32 v166, 16, v48
	v_and_b32_e32 v167, 0xffff0000, v48
	v_lshlrev_b32_e32 v168, 16, v49
	v_and_b32_e32 v169, 0xffff0000, v49
	v_pk_mul_f32 v[162:163], v[162:163], v[252:253] op_sel_hi:[1,0]
	v_pk_mul_f32 v[164:165], v[164:165], v[252:253] op_sel_hi:[1,0]
	v_pk_mul_f32 v[162:163], v[162:163], v[154:155]
	v_pk_mul_f32 v[164:165], v[164:165], v[156:157]
	v_pk_fma_f32 v[162:163], v[158:159], v[162:163], v[166:167]
	v_pk_fma_f32 v[164:165], v[160:161], v[164:165], v[168:169]
	s_nop 0
	global_store_dwordx4 v241, v[162:165], s[30:31] offset:3072 nt
	s_nop 1
	ds_read_b128 v[146:149], v238 offset:10240
	ds_read_b128 v[150:153], v238 offset:43008
	ds_read_b128 v[154:157], v238 offset:11264
	ds_read_b128 v[158:161], v238 offset:44032
	s_waitcnt lgkmcnt(4)
	v_lshlrev_b32_e32 v162, 16, v18
	v_and_b32_e32 v163, 0xffff0000, v18
	v_lshlrev_b32_e32 v164, 16, v19
	v_and_b32_e32 v165, 0xffff0000, v19
	v_lshlrev_b32_e32 v166, 16, v50
	v_and_b32_e32 v167, 0xffff0000, v50
	v_lshlrev_b32_e32 v168, 16, v51
	v_and_b32_e32 v169, 0xffff0000, v51
	v_pk_mul_f32 v[162:163], v[162:163], v[252:253] op_sel_hi:[1,0]
	v_pk_mul_f32 v[164:165], v[164:165], v[252:253] op_sel_hi:[1,0]
	v_pk_mul_f32 v[162:163], v[162:163], v[130:131]
	v_pk_mul_f32 v[164:165], v[164:165], v[132:133]
	v_pk_fma_f32 v[162:163], v[134:135], v[162:163], v[166:167]
	v_pk_fma_f32 v[164:165], v[136:137], v[164:165], v[168:169]
	s_nop 0
	global_store_dwordx4 v242, v[162:165], s[30:31] offset:0 nt
	s_nop 1
	v_lshlrev_b32_e32 v162, 16, v20
	v_and_b32_e32 v163, 0xffff0000, v20
	v_lshlrev_b32_e32 v164, 16, v21
	v_and_b32_e32 v165, 0xffff0000, v21
	v_lshlrev_b32_e32 v166, 16, v52
	v_and_b32_e32 v167, 0xffff0000, v52
	v_lshlrev_b32_e32 v168, 16, v53
	v_and_b32_e32 v169, 0xffff0000, v53
	v_pk_mul_f32 v[162:163], v[162:163], v[252:253] op_sel_hi:[1,0]
	v_pk_mul_f32 v[164:165], v[164:165], v[252:253] op_sel_hi:[1,0]
	v_pk_mul_f32 v[162:163], v[162:163], v[138:139]
	v_pk_mul_f32 v[164:165], v[164:165], v[140:141]
	v_pk_fma_f32 v[162:163], v[142:143], v[162:163], v[166:167]
	v_pk_fma_f32 v[164:165], v[144:145], v[164:165], v[168:169]
	s_nop 0
	global_store_dwordx4 v242, v[162:165], s[30:31] offset:1024 nt
	s_nop 1
	ds_read_b128 v[130:133], v238 offset:12288
	ds_read_b128 v[134:137], v238 offset:45056
	ds_read_b128 v[138:141], v238 offset:13312
	ds_read_b128 v[142:145], v238 offset:46080
	s_waitcnt lgkmcnt(4)
	v_lshlrev_b32_e32 v162, 16, v22
	v_and_b32_e32 v163, 0xffff0000, v22
	v_lshlrev_b32_e32 v164, 16, v23
	v_and_b32_e32 v165, 0xffff0000, v23
	v_lshlrev_b32_e32 v166, 16, v54
	v_and_b32_e32 v167, 0xffff0000, v54
	v_lshlrev_b32_e32 v168, 16, v55
	v_and_b32_e32 v169, 0xffff0000, v55
	v_pk_mul_f32 v[162:163], v[162:163], v[252:253] op_sel_hi:[1,0]
	v_pk_mul_f32 v[164:165], v[164:165], v[252:253] op_sel_hi:[1,0]
	v_pk_mul_f32 v[162:163], v[162:163], v[146:147]
	v_pk_mul_f32 v[164:165], v[164:165], v[148:149]
	v_pk_fma_f32 v[162:163], v[150:151], v[162:163], v[166:167]
	v_pk_fma_f32 v[164:165], v[152:153], v[164:165], v[168:169]
	s_nop 0
	global_store_dwordx4 v242, v[162:165], s[30:31] offset:2048 nt
	s_nop 1
	v_lshlrev_b32_e32 v162, 16, v24
	v_and_b32_e32 v163, 0xffff0000, v24
	v_lshlrev_b32_e32 v164, 16, v25
	v_and_b32_e32 v165, 0xffff0000, v25
	v_lshlrev_b32_e32 v166, 16, v56
	v_and_b32_e32 v167, 0xffff0000, v56
	v_lshlrev_b32_e32 v168, 16, v57
	v_and_b32_e32 v169, 0xffff0000, v57
	v_pk_mul_f32 v[162:163], v[162:163], v[252:253] op_sel_hi:[1,0]
	v_pk_mul_f32 v[164:165], v[164:165], v[252:253] op_sel_hi:[1,0]
	v_pk_mul_f32 v[162:163], v[162:163], v[154:155]
	v_pk_mul_f32 v[164:165], v[164:165], v[156:157]
	v_pk_fma_f32 v[162:163], v[158:159], v[162:163], v[166:167]
	v_pk_fma_f32 v[164:165], v[160:161], v[164:165], v[168:169]
	s_nop 0
	global_store_dwordx4 v242, v[162:165], s[30:31] offset:3072 nt
	s_nop 1
	ds_read_b128 v[146:149], v238 offset:14336
	ds_read_b128 v[150:153], v238 offset:47104
	ds_read_b128 v[154:157], v238 offset:15360
	ds_read_b128 v[158:161], v238 offset:48128
	s_waitcnt lgkmcnt(4)
	v_lshlrev_b32_e32 v162, 16, v26
	v_and_b32_e32 v163, 0xffff0000, v26
	v_lshlrev_b32_e32 v164, 16, v27
	v_and_b32_e32 v165, 0xffff0000, v27
	v_lshlrev_b32_e32 v166, 16, v58
	v_and_b32_e32 v167, 0xffff0000, v58
	v_lshlrev_b32_e32 v168, 16, v59
	v_and_b32_e32 v169, 0xffff0000, v59
	v_pk_mul_f32 v[162:163], v[162:163], v[252:253] op_sel_hi:[1,0]
	v_pk_mul_f32 v[164:165], v[164:165], v[252:253] op_sel_hi:[1,0]
	v_pk_mul_f32 v[162:163], v[162:163], v[130:131]
	v_pk_mul_f32 v[164:165], v[164:165], v[132:133]
	v_pk_fma_f32 v[162:163], v[134:135], v[162:163], v[166:167]
	v_pk_fma_f32 v[164:165], v[136:137], v[164:165], v[168:169]
	s_nop 0
	global_store_dwordx4 v243, v[162:165], s[30:31] offset:0 nt
	s_nop 1
	v_lshlrev_b32_e32 v162, 16, v28
	v_and_b32_e32 v163, 0xffff0000, v28
	v_lshlrev_b32_e32 v164, 16, v29
	v_and_b32_e32 v165, 0xffff0000, v29
	v_lshlrev_b32_e32 v166, 16, v60
	v_and_b32_e32 v167, 0xffff0000, v60
	v_lshlrev_b32_e32 v168, 16, v61
	v_and_b32_e32 v169, 0xffff0000, v61
	v_pk_mul_f32 v[162:163], v[162:163], v[252:253] op_sel_hi:[1,0]
	v_pk_mul_f32 v[164:165], v[164:165], v[252:253] op_sel_hi:[1,0]
	v_pk_mul_f32 v[162:163], v[162:163], v[138:139]
	v_pk_mul_f32 v[164:165], v[164:165], v[140:141]
	v_pk_fma_f32 v[162:163], v[142:143], v[162:163], v[166:167]
	v_pk_fma_f32 v[164:165], v[144:145], v[164:165], v[168:169]
	s_nop 0
	global_store_dwordx4 v243, v[162:165], s[30:31] offset:1024 nt
	s_nop 1
	s_waitcnt lgkmcnt(0)
	v_lshlrev_b32_e32 v162, 16, v30
	v_and_b32_e32 v163, 0xffff0000, v30
	v_lshlrev_b32_e32 v164, 16, v31
	v_and_b32_e32 v165, 0xffff0000, v31
	v_lshlrev_b32_e32 v166, 16, v62
	v_and_b32_e32 v167, 0xffff0000, v62
	v_lshlrev_b32_e32 v168, 16, v63
	v_and_b32_e32 v169, 0xffff0000, v63
	v_pk_mul_f32 v[162:163], v[162:163], v[252:253] op_sel_hi:[1,0]
	v_pk_mul_f32 v[164:165], v[164:165], v[252:253] op_sel_hi:[1,0]
	v_pk_mul_f32 v[162:163], v[162:163], v[146:147]
	v_pk_mul_f32 v[164:165], v[164:165], v[148:149]
	v_pk_fma_f32 v[162:163], v[150:151], v[162:163], v[166:167]
	v_pk_fma_f32 v[164:165], v[152:153], v[164:165], v[168:169]
	s_nop 0
	global_store_dwordx4 v243, v[162:165], s[30:31] offset:2048 nt
	s_nop 1
	v_lshlrev_b32_e32 v162, 16, v32
	v_and_b32_e32 v163, 0xffff0000, v32
	v_lshlrev_b32_e32 v164, 16, v33
	v_and_b32_e32 v165, 0xffff0000, v33
	v_lshlrev_b32_e32 v166, 16, v64
	v_and_b32_e32 v167, 0xffff0000, v64
	v_lshlrev_b32_e32 v168, 16, v65
	v_and_b32_e32 v169, 0xffff0000, v65
	v_pk_mul_f32 v[162:163], v[162:163], v[252:253] op_sel_hi:[1,0]
	v_pk_mul_f32 v[164:165], v[164:165], v[252:253] op_sel_hi:[1,0]
	v_pk_mul_f32 v[162:163], v[162:163], v[154:155]
	v_pk_mul_f32 v[164:165], v[164:165], v[156:157]
	v_pk_fma_f32 v[162:163], v[158:159], v[162:163], v[166:167]
	v_pk_fma_f32 v[164:165], v[160:161], v[164:165], v[168:169]
	s_nop 0
	global_store_dwordx4 v243, v[162:165], s[30:31] offset:3072 nt
	s_nop 1
	s_add_u32 s30, s30, 0x2000000
	s_addc_u32 s31, s31, 0
	s_waitcnt vmcnt(16)
	ds_read_b128 v[130:133], v238 offset:0
	ds_read_b128 v[134:137], v238 offset:49152
	ds_read_b128 v[138:141], v238 offset:1024
	ds_read_b128 v[142:145], v238 offset:50176
	v_lshlrev_b32_e32 v162, 16, v66
	v_and_b32_e32 v163, 0xffff0000, v66
	v_lshlrev_b32_e32 v164, 16, v67
	v_and_b32_e32 v165, 0xffff0000, v67
	v_pk_mul_f32 v[176:177], v[162:163], v[162:163]
	v_pk_mul_f32 v[178:179], v[164:165], v[164:165]
	v_lshlrev_b32_e32 v166, 16, v68
	v_and_b32_e32 v167, 0xffff0000, v68
	v_lshlrev_b32_e32 v168, 16, v69
	v_and_b32_e32 v169, 0xffff0000, v69
	v_pk_fma_f32 v[176:177], v[166:167], v[166:167], v[176:177]
	v_pk_fma_f32 v[178:179], v[168:169], v[168:169], v[178:179]
	v_lshlrev_b32_e32 v162, 16, v70
	v_and_b32_e32 v163, 0xffff0000, v70
	v_lshlrev_b32_e32 v164, 16, v71
	v_and_b32_e32 v165, 0xffff0000, v71
	v_pk_fma_f32 v[176:177], v[162:163], v[162:163], v[176:177]
	v_pk_fma_f32 v[178:179], v[164:165], v[164:165], v[178:179]
	v_lshlrev_b32_e32 v166, 16, v72
	v_and_b32_e32 v167, 0xffff0000, v72
	v_lshlrev_b32_e32 v168, 16, v73
	v_and_b32_e32 v169, 0xffff0000, v73
	v_pk_fma_f32 v[176:177], v[166:167], v[166:167], v[176:177]
	v_pk_fma_f32 v[178:179], v[168:169], v[168:169], v[178:179]
	v_lshlrev_b32_e32 v162, 16, v74
	v_and_b32_e32 v163, 0xffff0000, v74
	v_lshlrev_b32_e32 v164, 16, v75
	v_and_b32_e32 v165, 0xffff0000, v75
	v_pk_fma_f32 v[176:177], v[162:163], v[162:163], v[176:177]
	v_pk_fma_f32 v[178:179], v[164:165], v[164:165], v[178:179]
	v_lshlrev_b32_e32 v166, 16, v76
	v_and_b32_e32 v167, 0xffff0000, v76
	v_lshlrev_b32_e32 v168, 16, v77
	v_and_b32_e32 v169, 0xffff0000, v77
	v_pk_fma_f32 v[176:177], v[166:167], v[166:167], v[176:177]
	v_pk_fma_f32 v[178:179], v[168:169], v[168:169], v[178:179]
	v_lshlrev_b32_e32 v162, 16, v78
	v_and_b32_e32 v163, 0xffff0000, v78
	v_lshlrev_b32_e32 v164, 16, v79
	v_and_b32_e32 v165, 0xffff0000, v79
	v_pk_fma_f32 v[176:177], v[162:163], v[162:163], v[176:177]
	v_pk_fma_f32 v[178:179], v[164:165], v[164:165], v[178:179]
	v_lshlrev_b32_e32 v166, 16, v80
	v_and_b32_e32 v167, 0xffff0000, v80
	v_lshlrev_b32_e32 v168, 16, v81
	v_and_b32_e32 v169, 0xffff0000, v81
	v_pk_fma_f32 v[176:177], v[166:167], v[166:167], v[176:177]
	v_pk_fma_f32 v[178:179], v[168:169], v[168:169], v[178:179]
	v_lshlrev_b32_e32 v162, 16, v82
	v_and_b32_e32 v163, 0xffff0000, v82
	v_lshlrev_b32_e32 v164, 16, v83
	v_and_b32_e32 v165, 0xffff0000, v83
	v_pk_fma_f32 v[176:177], v[162:163], v[162:163], v[176:177]
	v_pk_fma_f32 v[178:179], v[164:165], v[164:165], v[178:179]
	v_lshlrev_b32_e32 v166, 16, v84
	v_and_b32_e32 v167, 0xffff0000, v84
	v_lshlrev_b32_e32 v168, 16, v85
	v_and_b32_e32 v169, 0xffff0000, v85
	v_pk_fma_f32 v[176:177], v[166:167], v[166:167], v[176:177]
	v_pk_fma_f32 v[178:179], v[168:169], v[168:169], v[178:179]
	v_lshlrev_b32_e32 v162, 16, v86
	v_and_b32_e32 v163, 0xffff0000, v86
	v_lshlrev_b32_e32 v164, 16, v87
	v_and_b32_e32 v165, 0xffff0000, v87
	v_pk_fma_f32 v[176:177], v[162:163], v[162:163], v[176:177]
	v_pk_fma_f32 v[178:179], v[164:165], v[164:165], v[178:179]
	v_lshlrev_b32_e32 v166, 16, v88
	v_and_b32_e32 v167, 0xffff0000, v88
	v_lshlrev_b32_e32 v168, 16, v89
	v_and_b32_e32 v169, 0xffff0000, v89
	v_pk_fma_f32 v[176:177], v[166:167], v[166:167], v[176:177]
	v_pk_fma_f32 v[178:179], v[168:169], v[168:169], v[178:179]
	v_lshlrev_b32_e32 v162, 16, v90
	v_and_b32_e32 v163, 0xffff0000, v90
	v_lshlrev_b32_e32 v164, 16, v91
	v_and_b32_e32 v165, 0xffff0000, v91
	v_pk_fma_f32 v[176:177], v[162:163], v[162:163], v[176:177]
	v_pk_fma_f32 v[178:179], v[164:165], v[164:165], v[178:179]
	v_lshlrev_b32_e32 v166, 16, v92
	v_and_b32_e32 v167, 0xffff0000, v92
	v_lshlrev_b32_e32 v168, 16, v93
	v_and_b32_e32 v169, 0xffff0000, v93
	v_pk_fma_f32 v[176:177], v[166:167], v[166:167], v[176:177]
	v_pk_fma_f32 v[178:179], v[168:169], v[168:169], v[178:179]
	v_lshlrev_b32_e32 v162, 16, v94
	v_and_b32_e32 v163, 0xffff0000, v94
	v_lshlrev_b32_e32 v164, 16, v95
	v_and_b32_e32 v165, 0xffff0000, v95
	v_pk_fma_f32 v[176:177], v[162:163], v[162:163], v[176:177]
	v_pk_fma_f32 v[178:179], v[164:165], v[164:165], v[178:179]
	v_lshlrev_b32_e32 v166, 16, v96
	v_and_b32_e32 v167, 0xffff0000, v96
	v_lshlrev_b32_e32 v168, 16, v97
	v_and_b32_e32 v169, 0xffff0000, v97
	v_pk_fma_f32 v[176:177], v[166:167], v[166:167], v[176:177]
	v_pk_fma_f32 v[178:179], v[168:169], v[168:169], v[178:179]
	v_pk_add_f32 v[176:177], v[176:177], v[178:179]
	s_nop 0
	v_add_f32_e32 v252, v176, v177
	s_waitcnt lgkmcnt(0)
	ds_bpermute_b32 v254, v246, v252
	s_waitcnt lgkmcnt(0)
	v_add_f32_e32 v252, v252, v254
	ds_bpermute_b32 v254, v247, v252
	s_waitcnt lgkmcnt(0)
	v_add_f32_e32 v252, v252, v254
	ds_bpermute_b32 v254, v248, v252
	s_waitcnt lgkmcnt(0)
	v_add_f32_e32 v252, v252, v254
	ds_bpermute_b32 v254, v249, v252
	s_waitcnt lgkmcnt(0)
	v_add_f32_e32 v252, v252, v254
	ds_bpermute_b32 v254, v250, v252
	s_waitcnt lgkmcnt(0)
	v_add_f32_e32 v252, v252, v254
	ds_bpermute_b32 v254, v251, v252
	s_waitcnt lgkmcnt(0)
	v_add_f32_e32 v252, v252, v254
	v_mov_b32_e32 v254, 0x358637bd
	v_fmac_f32_e32 v254, 0x39800000, v252
	v_mul_f32_e32 v252, 0x4b800000, v254
	v_cmp_gt_f32_e32 vcc, s20, v254
	s_nop 1
	v_cndmask_b32_e32 v254, v254, v252, vcc
	v_rsq_f32_e32 v254, v254
	s_nop 0
	v_mul_f32_e32 v252, 0x45800000, v254
	v_cndmask_b32_e32 v252, v254, v252, vcc
	ds_read_b128 v[146:149], v238 offset:2048
	ds_read_b128 v[150:153], v238 offset:51200
	ds_read_b128 v[154:157], v238 offset:3072
	ds_read_b128 v[158:161], v238 offset:52224
	s_waitcnt lgkmcnt(4)
	v_lshlrev_b32_e32 v162, 16, v66
	v_and_b32_e32 v163, 0xffff0000, v66
	v_lshlrev_b32_e32 v164, 16, v67
	v_and_b32_e32 v165, 0xffff0000, v67
	v_lshlrev_b32_e32 v166, 16, v98
	v_and_b32_e32 v167, 0xffff0000, v98
	v_lshlrev_b32_e32 v168, 16, v99
	v_and_b32_e32 v169, 0xffff0000, v99
	v_pk_mul_f32 v[162:163], v[162:163], v[252:253] op_sel_hi:[1,0]
	v_pk_mul_f32 v[164:165], v[164:165], v[252:253] op_sel_hi:[1,0]
	v_pk_mul_f32 v[162:163], v[162:163], v[130:131]
	v_pk_mul_f32 v[164:165], v[164:165], v[132:133]
	v_pk_fma_f32 v[162:163], v[134:135], v[162:163], v[166:167]
	v_pk_fma_f32 v[164:165], v[136:137], v[164:165], v[168:169]
	s_nop 0
	global_store_dwordx4 v238, v[162:165], s[30:31] offset:0 nt
	s_nop 1
	v_lshlrev_b32_e32 v162, 16, v68
	v_and_b32_e32 v163, 0xffff0000, v68
	v_lshlrev_b32_e32 v164, 16, v69
	v_and_b32_e32 v165, 0xffff0000, v69
	v_lshlrev_b32_e32 v166, 16, v100
	v_and_b32_e32 v167, 0xffff0000, v100
	v_lshlrev_b32_e32 v168, 16, v101
	v_and_b32_e32 v169, 0xffff0000, v101
	v_pk_mul_f32 v[162:163], v[162:163], v[252:253] op_sel_hi:[1,0]
	v_pk_mul_f32 v[164:165], v[164:165], v[252:253] op_sel_hi:[1,0]
	v_pk_mul_f32 v[162:163], v[162:163], v[138:139]
	v_pk_mul_f32 v[164:165], v[164:165], v[140:141]
	v_pk_fma_f32 v[162:163], v[142:143], v[162:163], v[166:167]
	v_pk_fma_f32 v[164:165], v[144:145], v[164:165], v[168:169]
	s_nop 0
	global_store_dwordx4 v238, v[162:165], s[30:31] offset:1024 nt
	s_nop 1
	ds_read_b128 v[130:133], v238 offset:4096
	ds_read_b128 v[134:137], v238 offset:53248
	ds_read_b128 v[138:141], v238 offset:5120
	ds_read_b128 v[142:145], v238 offset:54272
	s_waitcnt lgkmcnt(4)
	v_lshlrev_b32_e32 v162, 16, v70
	v_and_b32_e32 v163, 0xffff0000, v70
	v_lshlrev_b32_e32 v164, 16, v71
	v_and_b32_e32 v165, 0xffff0000, v71
	v_lshlrev_b32_e32 v166, 16, v102
	v_and_b32_e32 v167, 0xffff0000, v102
	v_lshlrev_b32_e32 v168, 16, v103
	v_and_b32_e32 v169, 0xffff0000, v103
	v_pk_mul_f32 v[162:163], v[162:163], v[252:253] op_sel_hi:[1,0]
	v_pk_mul_f32 v[164:165], v[164:165], v[252:253] op_sel_hi:[1,0]
	v_pk_mul_f32 v[162:163], v[162:163], v[146:147]
	v_pk_mul_f32 v[164:165], v[164:165], v[148:149]
	v_pk_fma_f32 v[162:163], v[150:151], v[162:163], v[166:167]
	v_pk_fma_f32 v[164:165], v[152:153], v[164:165], v[168:169]
	s_nop 0
	global_store_dwordx4 v238, v[162:165], s[30:31] offset:2048 nt
	s_nop 1
	v_lshlrev_b32_e32 v162, 16, v72
	v_and_b32_e32 v163, 0xffff0000, v72
	v_lshlrev_b32_e32 v164, 16, v73
	v_and_b32_e32 v165, 0xffff0000, v73
	v_lshlrev_b32_e32 v166, 16, v104
	v_and_b32_e32 v167, 0xffff0000, v104
	v_lshlrev_b32_e32 v168, 16, v105
	v_and_b32_e32 v169, 0xffff0000, v105
	v_pk_mul_f32 v[162:163], v[162:163], v[252:253] op_sel_hi:[1,0]
	v_pk_mul_f32 v[164:165], v[164:165], v[252:253] op_sel_hi:[1,0]
	v_pk_mul_f32 v[162:163], v[162:163], v[154:155]
	v_pk_mul_f32 v[164:165], v[164:165], v[156:157]
	v_pk_fma_f32 v[162:163], v[158:159], v[162:163], v[166:167]
	v_pk_fma_f32 v[164:165], v[160:161], v[164:165], v[168:169]
	s_nop 0
	global_store_dwordx4 v238, v[162:165], s[30:31] offset:3072 nt
	s_nop 1
	ds_read_b128 v[146:149], v238 offset:6144
	ds_read_b128 v[150:153], v238 offset:55296
	ds_read_b128 v[154:157], v238 offset:7168
	ds_read_b128 v[158:161], v238 offset:56320
	s_waitcnt lgkmcnt(4)
	v_lshlrev_b32_e32 v162, 16, v74
	v_and_b32_e32 v163, 0xffff0000, v74
	v_lshlrev_b32_e32 v164, 16, v75
	v_and_b32_e32 v165, 0xffff0000, v75
	v_lshlrev_b32_e32 v166, 16, v106
	v_and_b32_e32 v167, 0xffff0000, v106
	v_lshlrev_b32_e32 v168, 16, v107
	v_and_b32_e32 v169, 0xffff0000, v107
	v_pk_mul_f32 v[162:163], v[162:163], v[252:253] op_sel_hi:[1,0]
	v_pk_mul_f32 v[164:165], v[164:165], v[252:253] op_sel_hi:[1,0]
	v_pk_mul_f32 v[162:163], v[162:163], v[130:131]
	v_pk_mul_f32 v[164:165], v[164:165], v[132:133]
	v_pk_fma_f32 v[162:163], v[134:135], v[162:163], v[166:167]
	v_pk_fma_f32 v[164:165], v[136:137], v[164:165], v[168:169]
	s_nop 0
	global_store_dwordx4 v241, v[162:165], s[30:31] offset:0 nt
	s_nop 1
	v_lshlrev_b32_e32 v162, 16, v76
	v_and_b32_e32 v163, 0xffff0000, v76
	v_lshlrev_b32_e32 v164, 16, v77
	v_and_b32_e32 v165, 0xffff0000, v77
	v_lshlrev_b32_e32 v166, 16, v108
	v_and_b32_e32 v167, 0xffff0000, v108
	v_lshlrev_b32_e32 v168, 16, v109
	v_and_b32_e32 v169, 0xffff0000, v109
	v_pk_mul_f32 v[162:163], v[162:163], v[252:253] op_sel_hi:[1,0]
	v_pk_mul_f32 v[164:165], v[164:165], v[252:253] op_sel_hi:[1,0]
	v_pk_mul_f32 v[162:163], v[162:163], v[138:139]
	v_pk_mul_f32 v[164:165], v[164:165], v[140:141]
	v_pk_fma_f32 v[162:163], v[142:143], v[162:163], v[166:167]
	v_pk_fma_f32 v[164:165], v[144:145], v[164:165], v[168:169]
	s_nop 0
	global_store_dwordx4 v241, v[162:165], s[30:31] offset:1024 nt
	s_nop 1
	ds_read_b128 v[130:133], v238 offset:8192
	ds_read_b128 v[134:137], v238 offset:57344
	ds_read_b128 v[138:141], v238 offset:9216
	ds_read_b128 v[142:145], v238 offset:58368
	s_waitcnt lgkmcnt(4)
	v_lshlrev_b32_e32 v162, 16, v78
	v_and_b32_e32 v163, 0xffff0000, v78
	v_lshlrev_b32_e32 v164, 16, v79
	v_and_b32_e32 v165, 0xffff0000, v79
	v_lshlrev_b32_e32 v166, 16, v110
	v_and_b32_e32 v167, 0xffff0000, v110
	v_lshlrev_b32_e32 v168, 16, v111
	v_and_b32_e32 v169, 0xffff0000, v111
	v_pk_mul_f32 v[162:163], v[162:163], v[252:253] op_sel_hi:[1,0]
	v_pk_mul_f32 v[164:165], v[164:165], v[252:253] op_sel_hi:[1,0]
	v_pk_mul_f32 v[162:163], v[162:163], v[146:147]
	v_pk_mul_f32 v[164:165], v[164:165], v[148:149]
	v_pk_fma_f32 v[162:163], v[150:151], v[162:163], v[166:167]
	v_pk_fma_f32 v[164:165], v[152:153], v[164:165], v[168:169]
	s_nop 0
	global_store_dwordx4 v241, v[162:165], s[30:31] offset:2048 nt
	s_nop 1
	v_lshlrev_b32_e32 v162, 16, v80
	v_and_b32_e32 v163, 0xffff0000, v80
	v_lshlrev_b32_e32 v164, 16, v81
	v_and_b32_e32 v165, 0xffff0000, v81
	v_lshlrev_b32_e32 v166, 16, v112
	v_and_b32_e32 v167, 0xffff0000, v112
	v_lshlrev_b32_e32 v168, 16, v113
	v_and_b32_e32 v169, 0xffff0000, v113
	v_pk_mul_f32 v[162:163], v[162:163], v[252:253] op_sel_hi:[1,0]
	v_pk_mul_f32 v[164:165], v[164:165], v[252:253] op_sel_hi:[1,0]
	v_pk_mul_f32 v[162:163], v[162:163], v[154:155]
	v_pk_mul_f32 v[164:165], v[164:165], v[156:157]
	v_pk_fma_f32 v[162:163], v[158:159], v[162:163], v[166:167]
	v_pk_fma_f32 v[164:165], v[160:161], v[164:165], v[168:169]
	s_nop 0
	global_store_dwordx4 v241, v[162:165], s[30:31] offset:3072 nt
	s_nop 1
	ds_read_b128 v[146:149], v238 offset:10240
	ds_read_b128 v[150:153], v238 offset:59392
	ds_read_b128 v[154:157], v238 offset:11264
	ds_read_b128 v[158:161], v238 offset:60416
	s_waitcnt lgkmcnt(4)
	v_lshlrev_b32_e32 v162, 16, v82
	v_and_b32_e32 v163, 0xffff0000, v82
	v_lshlrev_b32_e32 v164, 16, v83
	v_and_b32_e32 v165, 0xffff0000, v83
	v_lshlrev_b32_e32 v166, 16, v114
	v_and_b32_e32 v167, 0xffff0000, v114
	v_lshlrev_b32_e32 v168, 16, v115
	v_and_b32_e32 v169, 0xffff0000, v115
	v_pk_mul_f32 v[162:163], v[162:163], v[252:253] op_sel_hi:[1,0]
	v_pk_mul_f32 v[164:165], v[164:165], v[252:253] op_sel_hi:[1,0]
	v_pk_mul_f32 v[162:163], v[162:163], v[130:131]
	v_pk_mul_f32 v[164:165], v[164:165], v[132:133]
	v_pk_fma_f32 v[162:163], v[134:135], v[162:163], v[166:167]
	v_pk_fma_f32 v[164:165], v[136:137], v[164:165], v[168:169]
	s_nop 0
	global_store_dwordx4 v242, v[162:165], s[30:31] offset:0 nt
	s_nop 1
	v_lshlrev_b32_e32 v162, 16, v84
	v_and_b32_e32 v163, 0xffff0000, v84
	v_lshlrev_b32_e32 v164, 16, v85
	v_and_b32_e32 v165, 0xffff0000, v85
	v_lshlrev_b32_e32 v166, 16, v116
	v_and_b32_e32 v167, 0xffff0000, v116
	v_lshlrev_b32_e32 v168, 16, v117
	v_and_b32_e32 v169, 0xffff0000, v117
	v_pk_mul_f32 v[162:163], v[162:163], v[252:253] op_sel_hi:[1,0]
	v_pk_mul_f32 v[164:165], v[164:165], v[252:253] op_sel_hi:[1,0]
	v_pk_mul_f32 v[162:163], v[162:163], v[138:139]
	v_pk_mul_f32 v[164:165], v[164:165], v[140:141]
	v_pk_fma_f32 v[162:163], v[142:143], v[162:163], v[166:167]
	v_pk_fma_f32 v[164:165], v[144:145], v[164:165], v[168:169]
	s_nop 0
	global_store_dwordx4 v242, v[162:165], s[30:31] offset:1024 nt
	s_nop 1
	ds_read_b128 v[130:133], v238 offset:12288
	ds_read_b128 v[134:137], v238 offset:61440
	ds_read_b128 v[138:141], v238 offset:13312
	ds_read_b128 v[142:145], v238 offset:62464
	s_waitcnt lgkmcnt(4)
	v_lshlrev_b32_e32 v162, 16, v86
	v_and_b32_e32 v163, 0xffff0000, v86
	v_lshlrev_b32_e32 v164, 16, v87
	v_and_b32_e32 v165, 0xffff0000, v87
	v_lshlrev_b32_e32 v166, 16, v118
	v_and_b32_e32 v167, 0xffff0000, v118
	v_lshlrev_b32_e32 v168, 16, v119
	v_and_b32_e32 v169, 0xffff0000, v119
	v_pk_mul_f32 v[162:163], v[162:163], v[252:253] op_sel_hi:[1,0]
	v_pk_mul_f32 v[164:165], v[164:165], v[252:253] op_sel_hi:[1,0]
	v_pk_mul_f32 v[162:163], v[162:163], v[146:147]
	v_pk_mul_f32 v[164:165], v[164:165], v[148:149]
	v_pk_fma_f32 v[162:163], v[150:151], v[162:163], v[166:167]
	v_pk_fma_f32 v[164:165], v[152:153], v[164:165], v[168:169]
	s_nop 0
	global_store_dwordx4 v242, v[162:165], s[30:31] offset:2048 nt
	s_nop 1
	v_lshlrev_b32_e32 v162, 16, v88
	v_and_b32_e32 v163, 0xffff0000, v88
	v_lshlrev_b32_e32 v164, 16, v89
	v_and_b32_e32 v165, 0xffff0000, v89
	v_lshlrev_b32_e32 v166, 16, v120
	v_and_b32_e32 v167, 0xffff0000, v120
	v_lshlrev_b32_e32 v168, 16, v121
	v_and_b32_e32 v169, 0xffff0000, v121
	v_pk_mul_f32 v[162:163], v[162:163], v[252:253] op_sel_hi:[1,0]
	v_pk_mul_f32 v[164:165], v[164:165], v[252:253] op_sel_hi:[1,0]
	v_pk_mul_f32 v[162:163], v[162:163], v[154:155]
	v_pk_mul_f32 v[164:165], v[164:165], v[156:157]
	v_pk_fma_f32 v[162:163], v[158:159], v[162:163], v[166:167]
	v_pk_fma_f32 v[164:165], v[160:161], v[164:165], v[168:169]
	s_nop 0
	global_store_dwordx4 v242, v[162:165], s[30:31] offset:3072 nt
	s_nop 1
	ds_read_b128 v[146:149], v238 offset:14336
	ds_read_b128 v[150:153], v238 offset:63488
	ds_read_b128 v[154:157], v238 offset:15360
	ds_read_b128 v[158:161], v238 offset:64512
	s_waitcnt lgkmcnt(4)
	v_lshlrev_b32_e32 v162, 16, v90
	v_and_b32_e32 v163, 0xffff0000, v90
	v_lshlrev_b32_e32 v164, 16, v91
	v_and_b32_e32 v165, 0xffff0000, v91
	v_lshlrev_b32_e32 v166, 16, v122
	v_and_b32_e32 v167, 0xffff0000, v122
	v_lshlrev_b32_e32 v168, 16, v123
	v_and_b32_e32 v169, 0xffff0000, v123
	v_pk_mul_f32 v[162:163], v[162:163], v[252:253] op_sel_hi:[1,0]
	v_pk_mul_f32 v[164:165], v[164:165], v[252:253] op_sel_hi:[1,0]
	v_pk_mul_f32 v[162:163], v[162:163], v[130:131]
	v_pk_mul_f32 v[164:165], v[164:165], v[132:133]
	v_pk_fma_f32 v[162:163], v[134:135], v[162:163], v[166:167]
	v_pk_fma_f32 v[164:165], v[136:137], v[164:165], v[168:169]
	s_nop 0
	global_store_dwordx4 v243, v[162:165], s[30:31] offset:0 nt
	s_nop 1
	v_lshlrev_b32_e32 v162, 16, v92
	v_and_b32_e32 v163, 0xffff0000, v92
	v_lshlrev_b32_e32 v164, 16, v93
	v_and_b32_e32 v165, 0xffff0000, v93
	v_lshlrev_b32_e32 v166, 16, v124
	v_and_b32_e32 v167, 0xffff0000, v124
	v_lshlrev_b32_e32 v168, 16, v125
	v_and_b32_e32 v169, 0xffff0000, v125
	v_pk_mul_f32 v[162:163], v[162:163], v[252:253] op_sel_hi:[1,0]
	v_pk_mul_f32 v[164:165], v[164:165], v[252:253] op_sel_hi:[1,0]
	v_pk_mul_f32 v[162:163], v[162:163], v[138:139]
	v_pk_mul_f32 v[164:165], v[164:165], v[140:141]
	v_pk_fma_f32 v[162:163], v[142:143], v[162:163], v[166:167]
	v_pk_fma_f32 v[164:165], v[144:145], v[164:165], v[168:169]
	s_nop 0
	global_store_dwordx4 v243, v[162:165], s[30:31] offset:1024 nt
	s_nop 1
	s_waitcnt lgkmcnt(0)
	v_lshlrev_b32_e32 v162, 16, v94
	v_and_b32_e32 v163, 0xffff0000, v94
	v_lshlrev_b32_e32 v164, 16, v95
	v_and_b32_e32 v165, 0xffff0000, v95
	v_lshlrev_b32_e32 v166, 16, v126
	v_and_b32_e32 v167, 0xffff0000, v126
	v_lshlrev_b32_e32 v168, 16, v127
	v_and_b32_e32 v169, 0xffff0000, v127
	v_pk_mul_f32 v[162:163], v[162:163], v[252:253] op_sel_hi:[1,0]
	v_pk_mul_f32 v[164:165], v[164:165], v[252:253] op_sel_hi:[1,0]
	v_pk_mul_f32 v[162:163], v[162:163], v[146:147]
	v_pk_mul_f32 v[164:165], v[164:165], v[148:149]
	v_pk_fma_f32 v[162:163], v[150:151], v[162:163], v[166:167]
	v_pk_fma_f32 v[164:165], v[152:153], v[164:165], v[168:169]
	s_nop 0
	global_store_dwordx4 v243, v[162:165], s[30:31] offset:2048 nt
	s_nop 1
	v_lshlrev_b32_e32 v162, 16, v96
	v_and_b32_e32 v163, 0xffff0000, v96
	v_lshlrev_b32_e32 v164, 16, v97
	v_and_b32_e32 v165, 0xffff0000, v97
	v_lshlrev_b32_e32 v166, 16, v128
	v_and_b32_e32 v167, 0xffff0000, v128
	v_lshlrev_b32_e32 v168, 16, v129
	v_and_b32_e32 v169, 0xffff0000, v129
	v_pk_mul_f32 v[162:163], v[162:163], v[252:253] op_sel_hi:[1,0]
	v_pk_mul_f32 v[164:165], v[164:165], v[252:253] op_sel_hi:[1,0]
	v_pk_mul_f32 v[162:163], v[162:163], v[154:155]
	v_pk_mul_f32 v[164:165], v[164:165], v[156:157]
	v_pk_fma_f32 v[162:163], v[158:159], v[162:163], v[166:167]
	v_pk_fma_f32 v[164:165], v[160:161], v[164:165], v[168:169]
	s_nop 0
	global_store_dwordx4 v243, v[162:165], s[30:31] offset:3072 nt
	s_nop 1
	s_branch .LBB0_988
.LrB_old:
	v_mbcnt_lo_u32_b32 v0, -1, 0
	v_mbcnt_hi_u32_b32 v0, -1, v0
	v_and_b32_e32 v1, 64, v0
	v_add_u32_e32 v1, 64, v1
	v_xor_b32_e32 v2, 1, v0
	v_cmp_lt_i32_e32 vcc, v2, v1
	v_readlane_b32 s4, v255, 2
	v_readlane_b32 s5, v255, 3
	v_cndmask_b32_e32 v2, v0, v2, vcc
	v_lshlrev_b32_e32 v87, 2, v2
	v_xor_b32_e32 v2, 2, v0
	v_cmp_lt_i32_e32 vcc, v2, v1
	s_ashr_i32 s1, s0, 31
	s_lshl_b32 s2, s33, 3
	v_cndmask_b32_e32 v2, v0, v2, vcc
	s_waitcnt vmcnt(0)
	v_lshlrev_b32_e32 v128, 2, v2
	v_xor_b32_e32 v2, 4, v0
	v_cmp_lt_i32_e32 vcc, v2, v1
	s_lshl_b64 s[4:5], s[0:1], 13
	v_mov_b32_e32 v29, 0
	v_cndmask_b32_e32 v2, v0, v2, vcc
	v_lshlrev_b32_e32 v129, 2, v2
	v_xor_b32_e32 v2, 8, v0
	v_cmp_lt_i32_e32 vcc, v2, v1
	s_add_u32 s4, s70, s4
	v_lshlrev_b32_e32 v26, 3, v174
	v_cndmask_b32_e32 v2, v0, v2, vcc
	v_lshlrev_b32_e32 v130, 2, v2
	v_xor_b32_e32 v2, 16, v0
	v_cmp_lt_i32_e32 vcc, v2, v1
	v_mov_b32_e32 v27, v29
	s_addc_u32 s5, s71, s5
	v_cndmask_b32_e32 v2, v0, v2, vcc
	v_readlane_b32 s6, v255, 4
	v_readlane_b32 s7, v255, 5
	v_lshl_add_u64 v[26:27], s[4:5], 0, v[26:27]
	s_mov_b64 s[4:5], 0x51001e00
	s_ashr_i32 s3, s2, 31
	v_lshlrev_b32_e32 v30, 2, v174
	v_lshlrev_b32_e32 v131, 2, v2
	v_xor_b32_e32 v2, 32, v0
	v_lshl_add_u64 v[26:27], v[26:27], 0, s[4:5]
	s_lshl_b64 s[4:5], s[2:3], 13
	s_lshl_b64 s[6:7], s[0:1], 14
	v_cmp_lt_i32_e32 vcc, v2, v1
	v_or_b32_e32 v32, 0xc00, v30
	v_or_b32_e32 v40, 0x400, v30
	v_or_b32_e32 v42, 0x500, v30
	v_or_b32_e32 v44, 0x600, v30
	v_or_b32_e32 v46, 0x700, v30
	v_or_b32_e32 v48, 0x800, v30
	v_or_b32_e32 v50, 0x900, v30
	v_or_b32_e32 v52, 0xa00, v30
	v_or_b32_e32 v54, 0xb00, v30
	v_or_b32_e32 v56, 0xd00, v30
	v_or_b32_e32 v58, 0xe00, v30
	v_or_b32_e32 v60, 0xf00, v30
	v_readlane_b32 s10, v255, 8
	v_readlane_b32 s11, v255, 9
	v_readlane_b32 s14, v255, 12
	v_readlane_b32 s15, v255, 13
	s_add_u32 s6, s68, s6
	v_cndmask_b32_e32 v0, v0, v2, vcc
	v_or_b32_e32 v34, 0x100, v30
	v_or_b32_e32 v36, 0x200, v30
	v_or_b32_e32 v38, 0x300, v30
	v_lshlrev_b32_e32 v28, 4, v174
	v_readlane_b32 s12, v255, 10
	s_mov_b64 s[10:11], s[14:15]
	v_lshlrev_b32_e32 v2, 2, v40
	v_mov_b32_e32 v3, v29
	v_lshlrev_b32_e32 v4, 2, v42
	v_mov_b32_e32 v5, v29
	v_lshlrev_b32_e32 v6, 2, v44
	v_mov_b32_e32 v7, v29
	v_lshlrev_b32_e32 v8, 2, v46
	v_mov_b32_e32 v9, v29
	v_lshlrev_b32_e32 v10, 2, v48
	v_mov_b32_e32 v11, v29
	v_lshlrev_b32_e32 v12, 2, v50
	v_mov_b32_e32 v13, v29
	v_lshlrev_b32_e32 v14, 2, v52
	v_mov_b32_e32 v15, v29
	v_lshlrev_b32_e32 v16, 2, v54
	v_mov_b32_e32 v17, v29
	v_lshlrev_b32_e32 v18, 2, v32
	v_mov_b32_e32 v19, v29
	v_lshlrev_b32_e32 v20, 2, v56
	v_mov_b32_e32 v21, v29
	v_lshlrev_b32_e32 v22, 2, v58
	v_mov_b32_e32 v23, v29
	v_lshlrev_b32_e32 v24, 2, v60
	v_mov_b32_e32 v25, v29
	s_addc_u32 s7, s69, s7
	v_lshlrev_b32_e32 v132, 2, v0
	v_lshl_add_u64 v[0:1], s[10:11], 0, v[28:29]
	v_lshl_add_u64 v[2:3], s[10:11], 0, v[2:3]
	v_lshl_add_u64 v[4:5], s[10:11], 0, v[4:5]
	v_lshl_add_u64 v[6:7], s[10:11], 0, v[6:7]
	v_lshl_add_u64 v[8:9], s[10:11], 0, v[8:9]
	v_lshl_add_u64 v[10:11], s[10:11], 0, v[10:11]
	v_lshl_add_u64 v[12:13], s[10:11], 0, v[12:13]
	v_lshl_add_u64 v[14:15], s[10:11], 0, v[14:15]
	v_lshl_add_u64 v[16:17], s[10:11], 0, v[16:17]
	v_lshl_add_u64 v[18:19], s[10:11], 0, v[18:19]
	v_lshl_add_u64 v[20:21], s[10:11], 0, v[20:21]
	v_lshl_add_u64 v[22:23], s[10:11], 0, v[22:23]
	v_lshl_add_u64 v[24:25], s[10:11], 0, v[24:25]
	v_lshl_add_u64 v[28:29], s[6:7], 0, v[28:29]
	s_lshl_b64 s[6:7], s[2:3], 14
	s_mov_b32 s1, 0xee000000
	v_mov_b32_e32 v133, 0x358637bd
	s_mov_b32 s3, 0x800000
	v_lshlrev_b32_e32 v134, 2, v30
	v_lshlrev_b32_e32 v135, 2, v34
	v_lshlrev_b32_e32 v136, 2, v36
	v_lshlrev_b32_e32 v137, 2, v38
	v_lshlrev_b32_e32 v138, 2, v40
	v_lshlrev_b32_e32 v139, 2, v42
	v_lshlrev_b32_e32 v140, 2, v44
	v_lshlrev_b32_e32 v141, 2, v46
	s_movk_i32 s10, 0x1000
	v_lshlrev_b32_e32 v142, 2, v48
	v_lshlrev_b32_e32 v143, 2, v50
	v_lshlrev_b32_e32 v144, 2, v52
	v_lshlrev_b32_e32 v145, 2, v54
	s_movk_i32 s11, 0x2000
	v_lshlrev_b32_e32 v146, 2, v32
	v_lshlrev_b32_e32 v147, 2, v56
	v_lshlrev_b32_e32 v148, 2, v58
	v_lshlrev_b32_e32 v149, 2, v60
	s_movk_i32 s12, 0x3000
	v_readlane_b32 s8, v255, 6
	v_readlane_b32 s9, v255, 7
	v_readlane_b32 s13, v255, 11
	v_readlane_b32 s16, v255, 14
	v_readlane_b32 s17, v255, 15
	v_readlane_b32 s18, v255, 16
	v_readlane_b32 s19, v255, 17
